# P0 adaLN projection rewritten: silu table in LDS once per workgroup, one wave per 32 columns on all 256 workgroups (32 loads in flight), other waves start transposes at once
# speedup vs baseline: 1.0344x; 1.0043x over previous
; __device__ __forceinline__ float siluf_(float x) { return x * sigm(x); }
; __device__ __forceinline__ void ada_item(const Params& P, int item, float* sm) {
;     float* sv = sm; float* red = sm + 5 * 1024;
;     const int tid = threadIdx.x & 255;
;     for (int e = tid; e < 5 * 1024; e += 256) { const int r = e >> 10, k = e & 1023; const float c = r < 4 ? P.in[1][r * 1024 + k] : P.in[3][k]; sv[e] = siluf_(c); }
;     __syncthreads();
;     const int cgp = tid & 15, kg = tid >> 4, n0 = item * 64;
; __device__ __forceinline__ void phase0(const Params& P, unsigned char* smem) {
;     ...
;     const int n_ada = 144;
;     for (int base = blockIdx.x * 2; base < n_ada; base += gridDim.x * 2) ada_item(P, base + hb, scr);
.LBB0_10:
	s_load_dwordx16 s[36:51], s[0:1], 0x0
	s_load_dwordx16 s[4:19], s[0:1], 0x40
	s_cmp_lt_i32 s70, 1
	s_waitcnt lgkmcnt(0)
	s_barrier
	v_writelane_b32 v251, s4, 5
	s_nop 1
	v_writelane_b32 v251, s5, 6
	v_writelane_b32 v251, s6, 7
	v_writelane_b32 v251, s7, 8
	v_writelane_b32 v251, s8, 9
	v_writelane_b32 v251, s9, 10
	v_writelane_b32 v251, s10, 11
	v_writelane_b32 v251, s11, 12
	v_writelane_b32 v251, s12, 13
	v_writelane_b32 v251, s13, 14
	v_writelane_b32 v251, s14, 15
	v_writelane_b32 v251, s15, 16
	v_writelane_b32 v251, s16, 17
	v_writelane_b32 v251, s17, 18
	v_writelane_b32 v251, s18, 19
	v_writelane_b32 v251, s19, 20
	s_load_dwordx16 s[4:19], s[0:1], 0x80
	s_waitcnt lgkmcnt(0)
	v_writelane_b32 v251, s4, 21
	s_nop 1
	v_writelane_b32 v251, s5, 22
	v_writelane_b32 v251, s6, 23
	v_writelane_b32 v251, s7, 24
	v_writelane_b32 v251, s8, 25
	v_writelane_b32 v251, s9, 26
	v_writelane_b32 v251, s10, 27
	v_writelane_b32 v251, s11, 28
	v_writelane_b32 v251, s12, 29
	v_writelane_b32 v251, s13, 30
	v_writelane_b32 v251, s14, 31
	v_writelane_b32 v251, s15, 32
	v_writelane_b32 v251, s16, 33
	v_writelane_b32 v251, s17, 34
	v_writelane_b32 v251, s18, 35
	v_writelane_b32 v251, s19, 36
	s_load_dwordx16 s[4:19], s[0:1], 0xc0
	s_cselect_b64 s[0:1], -1, 0
	s_cmp_gt_i32 s71, 0
	s_cselect_b64 s[2:3], -1, 0
	s_and_b64 s[0:1], s[0:1], s[2:3]
	s_waitcnt lgkmcnt(0)
	v_writelane_b32 v251, s4, 37
	s_andn2_b64 vcc, exec, s[0:1]
	s_mov_b32 s0, 0
	v_writelane_b32 v251, s5, 38
	v_writelane_b32 v251, s6, 39
	v_writelane_b32 v251, s7, 40
	v_writelane_b32 v251, s8, 41
	v_writelane_b32 v251, s9, 42
	v_writelane_b32 v251, s10, 43
	v_writelane_b32 v251, s11, 44
	v_writelane_b32 v251, s12, 45
	v_writelane_b32 v251, s13, 46
	v_writelane_b32 v251, s14, 47
	v_writelane_b32 v251, s15, 48
	v_writelane_b32 v251, s16, 49
	v_writelane_b32 v251, s17, 50
	v_writelane_b32 v251, s18, 51
	v_writelane_b32 v251, s19, 52
	v_writelane_b32 v251, s0, 53
	s_cbranch_vccnz .LBB0_131
	v_lshlrev_b32_e32 v1, 2, v168
	v_add_u32_e32 v2, 0x1000, v1
	v_add_u32_e32 v3, 0x2000, v1
	v_add_u32_e32 v4, 0x3000, v1
	global_load_dword v10, v1, s[38:39]
	global_load_dword v11, v1, s[38:39] offset:2048
	global_load_dword v12, v2, s[38:39]
	global_load_dword v13, v2, s[38:39] offset:2048
	global_load_dword v14, v3, s[38:39]
	global_load_dword v15, v3, s[38:39] offset:2048
	global_load_dword v16, v4, s[38:39]
	global_load_dword v17, v4, s[38:39] offset:2048
	global_load_dword v18, v1, s[42:43]
	global_load_dword v19, v1, s[42:43] offset:2048
	v_and_b32_e32 v6, 7, v168
	v_lshrrev_b32_e32 v7, 3, v168
	v_mul_u32_u24_e32 v6, 0x210, v6
	v_lshl_add_u32 v5, v7, 2, v6
	v_add_u32_e32 v5, 0x13810, v5
	s_waitcnt vmcnt(0)
	v_mul_f32_e32 v20, 0xbfb8aa3b, v10
	v_mul_f32_e32 v21, 0xbfb8aa3b, v11
	v_mul_f32_e32 v22, 0xbfb8aa3b, v12
	v_mul_f32_e32 v23, 0xbfb8aa3b, v13
	v_mul_f32_e32 v24, 0xbfb8aa3b, v14
	v_mul_f32_e32 v25, 0xbfb8aa3b, v15
	v_mul_f32_e32 v26, 0xbfb8aa3b, v16
	v_mul_f32_e32 v27, 0xbfb8aa3b, v17
	v_mul_f32_e32 v28, 0xbfb8aa3b, v18
	v_mul_f32_e32 v29, 0xbfb8aa3b, v19
	v_exp_f32_e32 v20, v20
	v_exp_f32_e32 v21, v21
	v_exp_f32_e32 v22, v22
	v_exp_f32_e32 v23, v23
	v_exp_f32_e32 v24, v24
	v_exp_f32_e32 v25, v25
	v_exp_f32_e32 v26, v26
	v_exp_f32_e32 v27, v27
	v_exp_f32_e32 v28, v28
	v_exp_f32_e32 v29, v29
	v_add_f32_e32 v20, 1.0, v20
	v_add_f32_e32 v21, 1.0, v21
	v_add_f32_e32 v22, 1.0, v22
	v_add_f32_e32 v23, 1.0, v23
	v_add_f32_e32 v24, 1.0, v24
	v_add_f32_e32 v25, 1.0, v25
	v_add_f32_e32 v26, 1.0, v26
	v_add_f32_e32 v27, 1.0, v27
	v_add_f32_e32 v28, 1.0, v28
	v_add_f32_e32 v29, 1.0, v29
	v_rcp_f32_e32 v20, v20
	v_rcp_f32_e32 v21, v21
	v_rcp_f32_e32 v22, v22
	v_rcp_f32_e32 v23, v23
	v_rcp_f32_e32 v24, v24
	v_rcp_f32_e32 v25, v25
	v_rcp_f32_e32 v26, v26
	v_rcp_f32_e32 v27, v27
	v_rcp_f32_e32 v28, v28
	v_rcp_f32_e32 v29, v29
	v_mul_f32_e32 v10, v10, v20
	v_mul_f32_e32 v11, v11, v21
	v_mul_f32_e32 v12, v12, v22
	v_mul_f32_e32 v13, v13, v23
	v_mul_f32_e32 v14, v14, v24
	v_mul_f32_e32 v15, v15, v25
	v_mul_f32_e32 v16, v16, v26
	v_mul_f32_e32 v17, v17, v27
	v_mul_f32_e32 v18, v18, v28
	v_mul_f32_e32 v19, v19, v29
	ds_write_b32 v5, v10
	ds_write_b32 v5, v11 offset:256
	ds_write_b32 v5, v12 offset:4224
	ds_write_b32 v5, v13 offset:4480
	ds_write_b32 v5, v14 offset:8448
	ds_write_b32 v5, v15 offset:8704
	ds_write_b32 v5, v16 offset:12672
	ds_write_b32 v5, v17 offset:12928
	ds_write_b32 v5, v18 offset:16896
	ds_write_b32 v5, v19 offset:17152
	s_waitcnt lgkmcnt(0)
	s_barrier
	v_lshrrev_b32_e32 v6, 6, v168
	s_nop 1
	v_readfirstlane_b32 s0, v6
	s_nop 3
	s_mov_b32 s1, s33
	s_cmp_eq_u32 s0, 0
	s_cbranch_scc1 .Lada_go
	s_cmp_eq_u32 s0, 1
	s_cbranch_scc0 .LBB0_20
	s_cmp_lt_u32 s33, 32
	s_cbranch_scc0 .LBB0_20
	s_add_u32 s1, s33, 0x100
; __device__ __forceinline__ void ada_item(const Params& P, int item, float* sm) {
;     ...
;     f32x4 a[5];
; #pragma unroll
;     for (int r = 0; r < 5; ++r) a[r] = (f32x4){0.f, 0.f, 0.f, 0.f};
;     const float* wp = P.in[4] + (size_t)(kg * 64) * 9216 + n0 + cgp * 4;
; #pragma unroll 16
;     for (int kk = 0; kk < 64; ++kk) {
;         const f32x4 w4 = *(const f32x4*)(wp + (size_t)kk * 9216);
; #pragma unroll
;         for (int r = 0; r < 5; ++r) { const float s = sv[r * 1024 + kg * 64 + kk]; a[r] += w4 * s; }
;     }
.Lada_go:
	v_and_b32_e32 v1, 63, v168
	v_lshrrev_b32_e32 v2, 3, v1
	v_and_b32_e32 v3, 7, v1
	v_mul_u32_u24_e32 v4, 0x9000, v2
	v_lshl_add_u32 v4, v3, 4, v4
	v_mul_u32_u24_e32 v5, 0x210, v2
	v_add_u32_e32 v5, 0x13810, v5
	v_xor_b32_e32 v6, 16, v1
	v_xor_b32_e32 v7, 32, v1
	v_lshlrev_b32_e32 v6, 2, v6
	v_lshlrev_b32_e32 v7, 2, v7
	v_lshlrev_b32_e32 v8, 4, v1
	s_lshl_b32 s2, s1, 7
	s_add_u32 s6, s44, s2
	s_addc_u32 s7, s45, 0
	v_mov_b32_e32 v212, 0
	v_mov_b32_e32 v213, 0
	v_mov_b32_e32 v214, 0
	v_mov_b32_e32 v215, 0
	v_mov_b32_e32 v216, 0
	v_mov_b32_e32 v217, 0
	v_mov_b32_e32 v218, 0
	v_mov_b32_e32 v219, 0
	v_mov_b32_e32 v220, 0
	v_mov_b32_e32 v221, 0
	v_mov_b32_e32 v222, 0
	v_mov_b32_e32 v223, 0
	v_mov_b32_e32 v224, 0
	v_mov_b32_e32 v225, 0
	v_mov_b32_e32 v226, 0
	v_mov_b32_e32 v227, 0
	v_mov_b32_e32 v228, 0
	v_mov_b32_e32 v229, 0
	v_mov_b32_e32 v230, 0
	v_mov_b32_e32 v231, 0
	global_load_dwordx4 v[16:19], v4, s[6:7]
	s_add_u32 s6, s6, 0x48000
	s_addc_u32 s7, s7, 0
	global_load_dwordx4 v[20:23], v4, s[6:7]
	s_add_u32 s6, s6, 0x48000
	s_addc_u32 s7, s7, 0
	global_load_dwordx4 v[24:27], v4, s[6:7]
	s_add_u32 s6, s6, 0x48000
	s_addc_u32 s7, s7, 0
	global_load_dwordx4 v[28:31], v4, s[6:7]
	s_add_u32 s6, s6, 0x48000
	s_addc_u32 s7, s7, 0
	global_load_dwordx4 v[32:35], v4, s[6:7]
	s_add_u32 s6, s6, 0x48000
	s_addc_u32 s7, s7, 0
	global_load_dwordx4 v[36:39], v4, s[6:7]
	s_add_u32 s6, s6, 0x48000
	s_addc_u32 s7, s7, 0
	global_load_dwordx4 v[40:43], v4, s[6:7]
	s_add_u32 s6, s6, 0x48000
	s_addc_u32 s7, s7, 0
	global_load_dwordx4 v[44:47], v4, s[6:7]
	s_add_u32 s6, s6, 0x48000
	s_addc_u32 s7, s7, 0
	global_load_dwordx4 v[48:51], v4, s[6:7]
	s_add_u32 s6, s6, 0x48000
	s_addc_u32 s7, s7, 0
	global_load_dwordx4 v[52:55], v4, s[6:7]
	s_add_u32 s6, s6, 0x48000
	s_addc_u32 s7, s7, 0
	global_load_dwordx4 v[56:59], v4, s[6:7]
	s_add_u32 s6, s6, 0x48000
	s_addc_u32 s7, s7, 0
	global_load_dwordx4 v[60:63], v4, s[6:7]
	s_add_u32 s6, s6, 0x48000
	s_addc_u32 s7, s7, 0
	global_load_dwordx4 v[64:67], v4, s[6:7]
	s_add_u32 s6, s6, 0x48000
	s_addc_u32 s7, s7, 0
	global_load_dwordx4 v[68:71], v4, s[6:7]
	s_add_u32 s6, s6, 0x48000
	s_addc_u32 s7, s7, 0
	global_load_dwordx4 v[72:75], v4, s[6:7]
	s_add_u32 s6, s6, 0x48000
	s_addc_u32 s7, s7, 0
	global_load_dwordx4 v[76:79], v4, s[6:7]
	s_add_u32 s6, s6, 0x48000
	s_addc_u32 s7, s7, 0
	global_load_dwordx4 v[80:83], v4, s[6:7]
	s_add_u32 s6, s6, 0x48000
	s_addc_u32 s7, s7, 0
	global_load_dwordx4 v[84:87], v4, s[6:7]
	s_add_u32 s6, s6, 0x48000
	s_addc_u32 s7, s7, 0
	global_load_dwordx4 v[88:91], v4, s[6:7]
	s_add_u32 s6, s6, 0x48000
	s_addc_u32 s7, s7, 0
	global_load_dwordx4 v[92:95], v4, s[6:7]
	s_add_u32 s6, s6, 0x48000
	s_addc_u32 s7, s7, 0
	global_load_dwordx4 v[96:99], v4, s[6:7]
	s_add_u32 s6, s6, 0x48000
	s_addc_u32 s7, s7, 0
	global_load_dwordx4 v[100:103], v4, s[6:7]
	s_add_u32 s6, s6, 0x48000
	s_addc_u32 s7, s7, 0
	global_load_dwordx4 v[104:107], v4, s[6:7]
	s_add_u32 s6, s6, 0x48000
	s_addc_u32 s7, s7, 0
	global_load_dwordx4 v[108:111], v4, s[6:7]
	s_add_u32 s6, s6, 0x48000
	s_addc_u32 s7, s7, 0
	global_load_dwordx4 v[112:115], v4, s[6:7]
	s_add_u32 s6, s6, 0x48000
	s_addc_u32 s7, s7, 0
	global_load_dwordx4 v[116:119], v4, s[6:7]
	s_add_u32 s6, s6, 0x48000
	s_addc_u32 s7, s7, 0
	global_load_dwordx4 v[120:123], v4, s[6:7]
	s_add_u32 s6, s6, 0x48000
	s_addc_u32 s7, s7, 0
	global_load_dwordx4 v[124:127], v4, s[6:7]
	s_add_u32 s6, s6, 0x48000
	s_addc_u32 s7, s7, 0
	global_load_dwordx4 v[128:131], v4, s[6:7]
	s_add_u32 s6, s6, 0x48000
	s_addc_u32 s7, s7, 0
	global_load_dwordx4 v[132:135], v4, s[6:7]
	s_add_u32 s6, s6, 0x48000
	s_addc_u32 s7, s7, 0
	global_load_dwordx4 v[136:139], v4, s[6:7]
	s_add_u32 s6, s6, 0x48000
	s_addc_u32 s7, s7, 0
	global_load_dwordx4 v[140:143], v4, s[6:7]
	s_add_u32 s6, s6, 0x48000
	s_addc_u32 s7, s7, 0
	ds_read_b128 v[172:175], v5
	ds_read_b128 v[176:179], v5 offset:16
	ds_read_b128 v[180:183], v5 offset:4224
	ds_read_b128 v[184:187], v5 offset:4240
	ds_read_b128 v[188:191], v5 offset:8448
	ds_read_b128 v[192:195], v5 offset:8464
	ds_read_b128 v[196:199], v5 offset:12672
	ds_read_b128 v[200:203], v5 offset:12688
	ds_read_b128 v[204:207], v5 offset:16896
	ds_read_b128 v[208:211], v5 offset:16912
	s_waitcnt vmcnt(24)
	s_waitcnt lgkmcnt(0)
; __device__ __forceinline__ void ada_item(const Params& P, int item, float* sm) {
;     ...
;     for (int kk = 0; kk < 64; ++kk) {
;         const f32x4 w4 = *(const f32x4*)(wp + (size_t)kk * 9216);
; #pragma unroll
;         for (int r = 0; r < 5; ++r) { const float s = sv[r * 1024 + kg * 64 + kk]; a[r] += w4 * s; }
;     }
	v_pk_fma_f32 v[212:213], v[16:17], v[172:173], v[212:213] op_sel_hi:[1,0,1]
	v_pk_fma_f32 v[214:215], v[18:19], v[172:173], v[214:215] op_sel_hi:[1,0,1]
	v_pk_fma_f32 v[216:217], v[16:17], v[180:181], v[216:217] op_sel_hi:[1,0,1]
	v_pk_fma_f32 v[218:219], v[18:19], v[180:181], v[218:219] op_sel_hi:[1,0,1]
	v_pk_fma_f32 v[220:221], v[16:17], v[188:189], v[220:221] op_sel_hi:[1,0,1]
	v_pk_fma_f32 v[222:223], v[18:19], v[188:189], v[222:223] op_sel_hi:[1,0,1]
	v_pk_fma_f32 v[224:225], v[16:17], v[196:197], v[224:225] op_sel_hi:[1,0,1]
	v_pk_fma_f32 v[226:227], v[18:19], v[196:197], v[226:227] op_sel_hi:[1,0,1]
	v_pk_fma_f32 v[228:229], v[16:17], v[204:205], v[228:229] op_sel_hi:[1,0,1]
	v_pk_fma_f32 v[230:231], v[18:19], v[204:205], v[230:231] op_sel_hi:[1,0,1]
	v_pk_fma_f32 v[212:213], v[20:21], v[172:173], v[212:213] op_sel:[0,1,0] op_sel_hi:[1,1,1]
	v_pk_fma_f32 v[214:215], v[22:23], v[172:173], v[214:215] op_sel:[0,1,0] op_sel_hi:[1,1,1]
	v_pk_fma_f32 v[216:217], v[20:21], v[180:181], v[216:217] op_sel:[0,1,0] op_sel_hi:[1,1,1]
	v_pk_fma_f32 v[218:219], v[22:23], v[180:181], v[218:219] op_sel:[0,1,0] op_sel_hi:[1,1,1]
	v_pk_fma_f32 v[220:221], v[20:21], v[188:189], v[220:221] op_sel:[0,1,0] op_sel_hi:[1,1,1]
	v_pk_fma_f32 v[222:223], v[22:23], v[188:189], v[222:223] op_sel:[0,1,0] op_sel_hi:[1,1,1]
	v_pk_fma_f32 v[224:225], v[20:21], v[196:197], v[224:225] op_sel:[0,1,0] op_sel_hi:[1,1,1]
	v_pk_fma_f32 v[226:227], v[22:23], v[196:197], v[226:227] op_sel:[0,1,0] op_sel_hi:[1,1,1]
	v_pk_fma_f32 v[228:229], v[20:21], v[204:205], v[228:229] op_sel:[0,1,0] op_sel_hi:[1,1,1]
	v_pk_fma_f32 v[230:231], v[22:23], v[204:205], v[230:231] op_sel:[0,1,0] op_sel_hi:[1,1,1]
	v_pk_fma_f32 v[212:213], v[24:25], v[174:175], v[212:213] op_sel_hi:[1,0,1]
	v_pk_fma_f32 v[214:215], v[26:27], v[174:175], v[214:215] op_sel_hi:[1,0,1]
	v_pk_fma_f32 v[216:217], v[24:25], v[182:183], v[216:217] op_sel_hi:[1,0,1]
	v_pk_fma_f32 v[218:219], v[26:27], v[182:183], v[218:219] op_sel_hi:[1,0,1]
	v_pk_fma_f32 v[220:221], v[24:25], v[190:191], v[220:221] op_sel_hi:[1,0,1]
	v_pk_fma_f32 v[222:223], v[26:27], v[190:191], v[222:223] op_sel_hi:[1,0,1]
	v_pk_fma_f32 v[224:225], v[24:25], v[198:199], v[224:225] op_sel_hi:[1,0,1]
	v_pk_fma_f32 v[226:227], v[26:27], v[198:199], v[226:227] op_sel_hi:[1,0,1]
	v_pk_fma_f32 v[228:229], v[24:25], v[206:207], v[228:229] op_sel_hi:[1,0,1]
	v_pk_fma_f32 v[230:231], v[26:27], v[206:207], v[230:231] op_sel_hi:[1,0,1]
	v_pk_fma_f32 v[212:213], v[28:29], v[174:175], v[212:213] op_sel:[0,1,0] op_sel_hi:[1,1,1]
	v_pk_fma_f32 v[214:215], v[30:31], v[174:175], v[214:215] op_sel:[0,1,0] op_sel_hi:[1,1,1]
	v_pk_fma_f32 v[216:217], v[28:29], v[182:183], v[216:217] op_sel:[0,1,0] op_sel_hi:[1,1,1]
	v_pk_fma_f32 v[218:219], v[30:31], v[182:183], v[218:219] op_sel:[0,1,0] op_sel_hi:[1,1,1]
	v_pk_fma_f32 v[220:221], v[28:29], v[190:191], v[220:221] op_sel:[0,1,0] op_sel_hi:[1,1,1]
	v_pk_fma_f32 v[222:223], v[30:31], v[190:191], v[222:223] op_sel:[0,1,0] op_sel_hi:[1,1,1]
	v_pk_fma_f32 v[224:225], v[28:29], v[198:199], v[224:225] op_sel:[0,1,0] op_sel_hi:[1,1,1]
	v_pk_fma_f32 v[226:227], v[30:31], v[198:199], v[226:227] op_sel:[0,1,0] op_sel_hi:[1,1,1]
	v_pk_fma_f32 v[228:229], v[28:29], v[206:207], v[228:229] op_sel:[0,1,0] op_sel_hi:[1,1,1]
	v_pk_fma_f32 v[230:231], v[30:31], v[206:207], v[230:231] op_sel:[0,1,0] op_sel_hi:[1,1,1]
	v_pk_fma_f32 v[212:213], v[32:33], v[176:177], v[212:213] op_sel_hi:[1,0,1]
	v_pk_fma_f32 v[214:215], v[34:35], v[176:177], v[214:215] op_sel_hi:[1,0,1]
	v_pk_fma_f32 v[216:217], v[32:33], v[184:185], v[216:217] op_sel_hi:[1,0,1]
	v_pk_fma_f32 v[218:219], v[34:35], v[184:185], v[218:219] op_sel_hi:[1,0,1]
	v_pk_fma_f32 v[220:221], v[32:33], v[192:193], v[220:221] op_sel_hi:[1,0,1]
	v_pk_fma_f32 v[222:223], v[34:35], v[192:193], v[222:223] op_sel_hi:[1,0,1]
	v_pk_fma_f32 v[224:225], v[32:33], v[200:201], v[224:225] op_sel_hi:[1,0,1]
	v_pk_fma_f32 v[226:227], v[34:35], v[200:201], v[226:227] op_sel_hi:[1,0,1]
	v_pk_fma_f32 v[228:229], v[32:33], v[208:209], v[228:229] op_sel_hi:[1,0,1]
	v_pk_fma_f32 v[230:231], v[34:35], v[208:209], v[230:231] op_sel_hi:[1,0,1]
	v_pk_fma_f32 v[212:213], v[36:37], v[176:177], v[212:213] op_sel:[0,1,0] op_sel_hi:[1,1,1]
	v_pk_fma_f32 v[214:215], v[38:39], v[176:177], v[214:215] op_sel:[0,1,0] op_sel_hi:[1,1,1]
	v_pk_fma_f32 v[216:217], v[36:37], v[184:185], v[216:217] op_sel:[0,1,0] op_sel_hi:[1,1,1]
	v_pk_fma_f32 v[218:219], v[38:39], v[184:185], v[218:219] op_sel:[0,1,0] op_sel_hi:[1,1,1]
	v_pk_fma_f32 v[220:221], v[36:37], v[192:193], v[220:221] op_sel:[0,1,0] op_sel_hi:[1,1,1]
	v_pk_fma_f32 v[222:223], v[38:39], v[192:193], v[222:223] op_sel:[0,1,0] op_sel_hi:[1,1,1]
	v_pk_fma_f32 v[224:225], v[36:37], v[200:201], v[224:225] op_sel:[0,1,0] op_sel_hi:[1,1,1]
	v_pk_fma_f32 v[226:227], v[38:39], v[200:201], v[226:227] op_sel:[0,1,0] op_sel_hi:[1,1,1]
	v_pk_fma_f32 v[228:229], v[36:37], v[208:209], v[228:229] op_sel:[0,1,0] op_sel_hi:[1,1,1]
	v_pk_fma_f32 v[230:231], v[38:39], v[208:209], v[230:231] op_sel:[0,1,0] op_sel_hi:[1,1,1]
	v_pk_fma_f32 v[212:213], v[40:41], v[178:179], v[212:213] op_sel_hi:[1,0,1]
	v_pk_fma_f32 v[214:215], v[42:43], v[178:179], v[214:215] op_sel_hi:[1,0,1]
	v_pk_fma_f32 v[216:217], v[40:41], v[186:187], v[216:217] op_sel_hi:[1,0,1]
	v_pk_fma_f32 v[218:219], v[42:43], v[186:187], v[218:219] op_sel_hi:[1,0,1]
	v_pk_fma_f32 v[220:221], v[40:41], v[194:195], v[220:221] op_sel_hi:[1,0,1]
	v_pk_fma_f32 v[222:223], v[42:43], v[194:195], v[222:223] op_sel_hi:[1,0,1]
	v_pk_fma_f32 v[224:225], v[40:41], v[202:203], v[224:225] op_sel_hi:[1,0,1]
; __device__ __forceinline__ void ada_item(const Params& P, int item, float* sm) {
;     ...
;     for (int kk = 0; kk < 64; ++kk) {
;         const f32x4 w4 = *(const f32x4*)(wp + (size_t)kk * 9216);
; #pragma unroll
;         for (int r = 0; r < 5; ++r) { const float s = sv[r * 1024 + kg * 64 + kk]; a[r] += w4 * s; }
;     }
	v_pk_fma_f32 v[226:227], v[42:43], v[202:203], v[226:227] op_sel_hi:[1,0,1]
	v_pk_fma_f32 v[228:229], v[40:41], v[210:211], v[228:229] op_sel_hi:[1,0,1]
	v_pk_fma_f32 v[230:231], v[42:43], v[210:211], v[230:231] op_sel_hi:[1,0,1]
	v_pk_fma_f32 v[212:213], v[44:45], v[178:179], v[212:213] op_sel:[0,1,0] op_sel_hi:[1,1,1]
	v_pk_fma_f32 v[214:215], v[46:47], v[178:179], v[214:215] op_sel:[0,1,0] op_sel_hi:[1,1,1]
	v_pk_fma_f32 v[216:217], v[44:45], v[186:187], v[216:217] op_sel:[0,1,0] op_sel_hi:[1,1,1]
	v_pk_fma_f32 v[218:219], v[46:47], v[186:187], v[218:219] op_sel:[0,1,0] op_sel_hi:[1,1,1]
	v_pk_fma_f32 v[220:221], v[44:45], v[194:195], v[220:221] op_sel:[0,1,0] op_sel_hi:[1,1,1]
	v_pk_fma_f32 v[222:223], v[46:47], v[194:195], v[222:223] op_sel:[0,1,0] op_sel_hi:[1,1,1]
	v_pk_fma_f32 v[224:225], v[44:45], v[202:203], v[224:225] op_sel:[0,1,0] op_sel_hi:[1,1,1]
	v_pk_fma_f32 v[226:227], v[46:47], v[202:203], v[226:227] op_sel:[0,1,0] op_sel_hi:[1,1,1]
	v_pk_fma_f32 v[228:229], v[44:45], v[210:211], v[228:229] op_sel:[0,1,0] op_sel_hi:[1,1,1]
	v_pk_fma_f32 v[230:231], v[46:47], v[210:211], v[230:231] op_sel:[0,1,0] op_sel_hi:[1,1,1]
	global_load_dwordx4 v[16:19], v4, s[6:7]
	s_add_u32 s6, s6, 0x48000
	s_addc_u32 s7, s7, 0
	global_load_dwordx4 v[20:23], v4, s[6:7]
	s_add_u32 s6, s6, 0x48000
	s_addc_u32 s7, s7, 0
	global_load_dwordx4 v[24:27], v4, s[6:7]
	s_add_u32 s6, s6, 0x48000
	s_addc_u32 s7, s7, 0
	global_load_dwordx4 v[28:31], v4, s[6:7]
	s_add_u32 s6, s6, 0x48000
	s_addc_u32 s7, s7, 0
	global_load_dwordx4 v[32:35], v4, s[6:7]
	s_add_u32 s6, s6, 0x48000
	s_addc_u32 s7, s7, 0
	global_load_dwordx4 v[36:39], v4, s[6:7]
	s_add_u32 s6, s6, 0x48000
	s_addc_u32 s7, s7, 0
	global_load_dwordx4 v[40:43], v4, s[6:7]
	s_add_u32 s6, s6, 0x48000
	s_addc_u32 s7, s7, 0
	global_load_dwordx4 v[44:47], v4, s[6:7]
	s_add_u32 s6, s6, 0x48000
	s_addc_u32 s7, s7, 0
	ds_read_b128 v[172:175], v5 offset:32
	ds_read_b128 v[176:179], v5 offset:48
	ds_read_b128 v[180:183], v5 offset:4256
	ds_read_b128 v[184:187], v5 offset:4272
	ds_read_b128 v[188:191], v5 offset:8480
	ds_read_b128 v[192:195], v5 offset:8496
	ds_read_b128 v[196:199], v5 offset:12704
	ds_read_b128 v[200:203], v5 offset:12720
	ds_read_b128 v[204:207], v5 offset:16928
	ds_read_b128 v[208:211], v5 offset:16944
	s_waitcnt vmcnt(24)
	s_waitcnt lgkmcnt(0)
	v_pk_fma_f32 v[212:213], v[48:49], v[172:173], v[212:213] op_sel_hi:[1,0,1]
	v_pk_fma_f32 v[214:215], v[50:51], v[172:173], v[214:215] op_sel_hi:[1,0,1]
	v_pk_fma_f32 v[216:217], v[48:49], v[180:181], v[216:217] op_sel_hi:[1,0,1]
	v_pk_fma_f32 v[218:219], v[50:51], v[180:181], v[218:219] op_sel_hi:[1,0,1]
	v_pk_fma_f32 v[220:221], v[48:49], v[188:189], v[220:221] op_sel_hi:[1,0,1]
	v_pk_fma_f32 v[222:223], v[50:51], v[188:189], v[222:223] op_sel_hi:[1,0,1]
	v_pk_fma_f32 v[224:225], v[48:49], v[196:197], v[224:225] op_sel_hi:[1,0,1]
	v_pk_fma_f32 v[226:227], v[50:51], v[196:197], v[226:227] op_sel_hi:[1,0,1]
	v_pk_fma_f32 v[228:229], v[48:49], v[204:205], v[228:229] op_sel_hi:[1,0,1]
	v_pk_fma_f32 v[230:231], v[50:51], v[204:205], v[230:231] op_sel_hi:[1,0,1]
	v_pk_fma_f32 v[212:213], v[52:53], v[172:173], v[212:213] op_sel:[0,1,0] op_sel_hi:[1,1,1]
	v_pk_fma_f32 v[214:215], v[54:55], v[172:173], v[214:215] op_sel:[0,1,0] op_sel_hi:[1,1,1]
	v_pk_fma_f32 v[216:217], v[52:53], v[180:181], v[216:217] op_sel:[0,1,0] op_sel_hi:[1,1,1]
	v_pk_fma_f32 v[218:219], v[54:55], v[180:181], v[218:219] op_sel:[0,1,0] op_sel_hi:[1,1,1]
	v_pk_fma_f32 v[220:221], v[52:53], v[188:189], v[220:221] op_sel:[0,1,0] op_sel_hi:[1,1,1]
	v_pk_fma_f32 v[222:223], v[54:55], v[188:189], v[222:223] op_sel:[0,1,0] op_sel_hi:[1,1,1]
	v_pk_fma_f32 v[224:225], v[52:53], v[196:197], v[224:225] op_sel:[0,1,0] op_sel_hi:[1,1,1]
	v_pk_fma_f32 v[226:227], v[54:55], v[196:197], v[226:227] op_sel:[0,1,0] op_sel_hi:[1,1,1]
	v_pk_fma_f32 v[228:229], v[52:53], v[204:205], v[228:229] op_sel:[0,1,0] op_sel_hi:[1,1,1]
	v_pk_fma_f32 v[230:231], v[54:55], v[204:205], v[230:231] op_sel:[0,1,0] op_sel_hi:[1,1,1]
	v_pk_fma_f32 v[212:213], v[56:57], v[174:175], v[212:213] op_sel_hi:[1,0,1]
	v_pk_fma_f32 v[214:215], v[58:59], v[174:175], v[214:215] op_sel_hi:[1,0,1]
	v_pk_fma_f32 v[216:217], v[56:57], v[182:183], v[216:217] op_sel_hi:[1,0,1]
	v_pk_fma_f32 v[218:219], v[58:59], v[182:183], v[218:219] op_sel_hi:[1,0,1]
	v_pk_fma_f32 v[220:221], v[56:57], v[190:191], v[220:221] op_sel_hi:[1,0,1]
	v_pk_fma_f32 v[222:223], v[58:59], v[190:191], v[222:223] op_sel_hi:[1,0,1]
	v_pk_fma_f32 v[224:225], v[56:57], v[198:199], v[224:225] op_sel_hi:[1,0,1]
	v_pk_fma_f32 v[226:227], v[58:59], v[198:199], v[226:227] op_sel_hi:[1,0,1]
	v_pk_fma_f32 v[228:229], v[56:57], v[206:207], v[228:229] op_sel_hi:[1,0,1]
	v_pk_fma_f32 v[230:231], v[58:59], v[206:207], v[230:231] op_sel_hi:[1,0,1]
	v_pk_fma_f32 v[212:213], v[60:61], v[174:175], v[212:213] op_sel:[0,1,0] op_sel_hi:[1,1,1]
	v_pk_fma_f32 v[214:215], v[62:63], v[174:175], v[214:215] op_sel:[0,1,0] op_sel_hi:[1,1,1]
	v_pk_fma_f32 v[216:217], v[60:61], v[182:183], v[216:217] op_sel:[0,1,0] op_sel_hi:[1,1,1]
	v_pk_fma_f32 v[218:219], v[62:63], v[182:183], v[218:219] op_sel:[0,1,0] op_sel_hi:[1,1,1]
	v_pk_fma_f32 v[220:221], v[60:61], v[190:191], v[220:221] op_sel:[0,1,0] op_sel_hi:[1,1,1]
	v_pk_fma_f32 v[222:223], v[62:63], v[190:191], v[222:223] op_sel:[0,1,0] op_sel_hi:[1,1,1]
	v_pk_fma_f32 v[224:225], v[60:61], v[198:199], v[224:225] op_sel:[0,1,0] op_sel_hi:[1,1,1]
	v_pk_fma_f32 v[226:227], v[62:63], v[198:199], v[226:227] op_sel:[0,1,0] op_sel_hi:[1,1,1]
	v_pk_fma_f32 v[228:229], v[60:61], v[206:207], v[228:229] op_sel:[0,1,0] op_sel_hi:[1,1,1]
; __device__ __forceinline__ void ada_item(const Params& P, int item, float* sm) {
;     ...
;     for (int kk = 0; kk < 64; ++kk) {
;         const f32x4 w4 = *(const f32x4*)(wp + (size_t)kk * 9216);
; #pragma unroll
;         for (int r = 0; r < 5; ++r) { const float s = sv[r * 1024 + kg * 64 + kk]; a[r] += w4 * s; }
;     }
	v_pk_fma_f32 v[230:231], v[62:63], v[206:207], v[230:231] op_sel:[0,1,0] op_sel_hi:[1,1,1]
	v_pk_fma_f32 v[212:213], v[64:65], v[176:177], v[212:213] op_sel_hi:[1,0,1]
	v_pk_fma_f32 v[214:215], v[66:67], v[176:177], v[214:215] op_sel_hi:[1,0,1]
	v_pk_fma_f32 v[216:217], v[64:65], v[184:185], v[216:217] op_sel_hi:[1,0,1]
	v_pk_fma_f32 v[218:219], v[66:67], v[184:185], v[218:219] op_sel_hi:[1,0,1]
	v_pk_fma_f32 v[220:221], v[64:65], v[192:193], v[220:221] op_sel_hi:[1,0,1]
	v_pk_fma_f32 v[222:223], v[66:67], v[192:193], v[222:223] op_sel_hi:[1,0,1]
	v_pk_fma_f32 v[224:225], v[64:65], v[200:201], v[224:225] op_sel_hi:[1,0,1]
	v_pk_fma_f32 v[226:227], v[66:67], v[200:201], v[226:227] op_sel_hi:[1,0,1]
	v_pk_fma_f32 v[228:229], v[64:65], v[208:209], v[228:229] op_sel_hi:[1,0,1]
	v_pk_fma_f32 v[230:231], v[66:67], v[208:209], v[230:231] op_sel_hi:[1,0,1]
	v_pk_fma_f32 v[212:213], v[68:69], v[176:177], v[212:213] op_sel:[0,1,0] op_sel_hi:[1,1,1]
	v_pk_fma_f32 v[214:215], v[70:71], v[176:177], v[214:215] op_sel:[0,1,0] op_sel_hi:[1,1,1]
	v_pk_fma_f32 v[216:217], v[68:69], v[184:185], v[216:217] op_sel:[0,1,0] op_sel_hi:[1,1,1]
	v_pk_fma_f32 v[218:219], v[70:71], v[184:185], v[218:219] op_sel:[0,1,0] op_sel_hi:[1,1,1]
	v_pk_fma_f32 v[220:221], v[68:69], v[192:193], v[220:221] op_sel:[0,1,0] op_sel_hi:[1,1,1]
	v_pk_fma_f32 v[222:223], v[70:71], v[192:193], v[222:223] op_sel:[0,1,0] op_sel_hi:[1,1,1]
	v_pk_fma_f32 v[224:225], v[68:69], v[200:201], v[224:225] op_sel:[0,1,0] op_sel_hi:[1,1,1]
	v_pk_fma_f32 v[226:227], v[70:71], v[200:201], v[226:227] op_sel:[0,1,0] op_sel_hi:[1,1,1]
	v_pk_fma_f32 v[228:229], v[68:69], v[208:209], v[228:229] op_sel:[0,1,0] op_sel_hi:[1,1,1]
	v_pk_fma_f32 v[230:231], v[70:71], v[208:209], v[230:231] op_sel:[0,1,0] op_sel_hi:[1,1,1]
	v_pk_fma_f32 v[212:213], v[72:73], v[178:179], v[212:213] op_sel_hi:[1,0,1]
	v_pk_fma_f32 v[214:215], v[74:75], v[178:179], v[214:215] op_sel_hi:[1,0,1]
	v_pk_fma_f32 v[216:217], v[72:73], v[186:187], v[216:217] op_sel_hi:[1,0,1]
	v_pk_fma_f32 v[218:219], v[74:75], v[186:187], v[218:219] op_sel_hi:[1,0,1]
	v_pk_fma_f32 v[220:221], v[72:73], v[194:195], v[220:221] op_sel_hi:[1,0,1]
	v_pk_fma_f32 v[222:223], v[74:75], v[194:195], v[222:223] op_sel_hi:[1,0,1]
	v_pk_fma_f32 v[224:225], v[72:73], v[202:203], v[224:225] op_sel_hi:[1,0,1]
	v_pk_fma_f32 v[226:227], v[74:75], v[202:203], v[226:227] op_sel_hi:[1,0,1]
	v_pk_fma_f32 v[228:229], v[72:73], v[210:211], v[228:229] op_sel_hi:[1,0,1]
	v_pk_fma_f32 v[230:231], v[74:75], v[210:211], v[230:231] op_sel_hi:[1,0,1]
	v_pk_fma_f32 v[212:213], v[76:77], v[178:179], v[212:213] op_sel:[0,1,0] op_sel_hi:[1,1,1]
	v_pk_fma_f32 v[214:215], v[78:79], v[178:179], v[214:215] op_sel:[0,1,0] op_sel_hi:[1,1,1]
	v_pk_fma_f32 v[216:217], v[76:77], v[186:187], v[216:217] op_sel:[0,1,0] op_sel_hi:[1,1,1]
	v_pk_fma_f32 v[218:219], v[78:79], v[186:187], v[218:219] op_sel:[0,1,0] op_sel_hi:[1,1,1]
	v_pk_fma_f32 v[220:221], v[76:77], v[194:195], v[220:221] op_sel:[0,1,0] op_sel_hi:[1,1,1]
	v_pk_fma_f32 v[222:223], v[78:79], v[194:195], v[222:223] op_sel:[0,1,0] op_sel_hi:[1,1,1]
	v_pk_fma_f32 v[224:225], v[76:77], v[202:203], v[224:225] op_sel:[0,1,0] op_sel_hi:[1,1,1]
	v_pk_fma_f32 v[226:227], v[78:79], v[202:203], v[226:227] op_sel:[0,1,0] op_sel_hi:[1,1,1]
	v_pk_fma_f32 v[228:229], v[76:77], v[210:211], v[228:229] op_sel:[0,1,0] op_sel_hi:[1,1,1]
	v_pk_fma_f32 v[230:231], v[78:79], v[210:211], v[230:231] op_sel:[0,1,0] op_sel_hi:[1,1,1]
	global_load_dwordx4 v[48:51], v4, s[6:7]
	s_add_u32 s6, s6, 0x48000
	s_addc_u32 s7, s7, 0
	global_load_dwordx4 v[52:55], v4, s[6:7]
	s_add_u32 s6, s6, 0x48000
	s_addc_u32 s7, s7, 0
	global_load_dwordx4 v[56:59], v4, s[6:7]
	s_add_u32 s6, s6, 0x48000
	s_addc_u32 s7, s7, 0
	global_load_dwordx4 v[60:63], v4, s[6:7]
	s_add_u32 s6, s6, 0x48000
	s_addc_u32 s7, s7, 0
	global_load_dwordx4 v[64:67], v4, s[6:7]
	s_add_u32 s6, s6, 0x48000
	s_addc_u32 s7, s7, 0
	global_load_dwordx4 v[68:71], v4, s[6:7]
	s_add_u32 s6, s6, 0x48000
	s_addc_u32 s7, s7, 0
	global_load_dwordx4 v[72:75], v4, s[6:7]
	s_add_u32 s6, s6, 0x48000
	s_addc_u32 s7, s7, 0
	global_load_dwordx4 v[76:79], v4, s[6:7]
	s_add_u32 s6, s6, 0x48000
	s_addc_u32 s7, s7, 0
	ds_read_b128 v[172:175], v5 offset:64
	ds_read_b128 v[176:179], v5 offset:80
	ds_read_b128 v[180:183], v5 offset:4288
	ds_read_b128 v[184:187], v5 offset:4304
	ds_read_b128 v[188:191], v5 offset:8512
	ds_read_b128 v[192:195], v5 offset:8528
	ds_read_b128 v[196:199], v5 offset:12736
	ds_read_b128 v[200:203], v5 offset:12752
	ds_read_b128 v[204:207], v5 offset:16960
	ds_read_b128 v[208:211], v5 offset:16976
	s_waitcnt vmcnt(24)
	s_waitcnt lgkmcnt(0)
; __device__ __forceinline__ void ada_item(const Params& P, int item, float* sm) {
;     ...
;     for (int kk = 0; kk < 64; ++kk) {
;         const f32x4 w4 = *(const f32x4*)(wp + (size_t)kk * 9216);
; #pragma unroll
;         for (int r = 0; r < 5; ++r) { const float s = sv[r * 1024 + kg * 64 + kk]; a[r] += w4 * s; }
	v_pk_fma_f32 v[212:213], v[80:81], v[172:173], v[212:213] op_sel_hi:[1,0,1]
	v_pk_fma_f32 v[214:215], v[82:83], v[172:173], v[214:215] op_sel_hi:[1,0,1]
	v_pk_fma_f32 v[216:217], v[80:81], v[180:181], v[216:217] op_sel_hi:[1,0,1]
	v_pk_fma_f32 v[218:219], v[82:83], v[180:181], v[218:219] op_sel_hi:[1,0,1]
	v_pk_fma_f32 v[220:221], v[80:81], v[188:189], v[220:221] op_sel_hi:[1,0,1]
	v_pk_fma_f32 v[222:223], v[82:83], v[188:189], v[222:223] op_sel_hi:[1,0,1]
	v_pk_fma_f32 v[224:225], v[80:81], v[196:197], v[224:225] op_sel_hi:[1,0,1]
	v_pk_fma_f32 v[226:227], v[82:83], v[196:197], v[226:227] op_sel_hi:[1,0,1]
	v_pk_fma_f32 v[228:229], v[80:81], v[204:205], v[228:229] op_sel_hi:[1,0,1]
	v_pk_fma_f32 v[230:231], v[82:83], v[204:205], v[230:231] op_sel_hi:[1,0,1]
	v_pk_fma_f32 v[212:213], v[84:85], v[172:173], v[212:213] op_sel:[0,1,0] op_sel_hi:[1,1,1]
	v_pk_fma_f32 v[214:215], v[86:87], v[172:173], v[214:215] op_sel:[0,1,0] op_sel_hi:[1,1,1]
	v_pk_fma_f32 v[216:217], v[84:85], v[180:181], v[216:217] op_sel:[0,1,0] op_sel_hi:[1,1,1]
	v_pk_fma_f32 v[218:219], v[86:87], v[180:181], v[218:219] op_sel:[0,1,0] op_sel_hi:[1,1,1]
	v_pk_fma_f32 v[220:221], v[84:85], v[188:189], v[220:221] op_sel:[0,1,0] op_sel_hi:[1,1,1]
	v_pk_fma_f32 v[222:223], v[86:87], v[188:189], v[222:223] op_sel:[0,1,0] op_sel_hi:[1,1,1]
	v_pk_fma_f32 v[224:225], v[84:85], v[196:197], v[224:225] op_sel:[0,1,0] op_sel_hi:[1,1,1]
	v_pk_fma_f32 v[226:227], v[86:87], v[196:197], v[226:227] op_sel:[0,1,0] op_sel_hi:[1,1,1]
	v_pk_fma_f32 v[228:229], v[84:85], v[204:205], v[228:229] op_sel:[0,1,0] op_sel_hi:[1,1,1]
	v_pk_fma_f32 v[230:231], v[86:87], v[204:205], v[230:231] op_sel:[0,1,0] op_sel_hi:[1,1,1]
	v_pk_fma_f32 v[212:213], v[88:89], v[174:175], v[212:213] op_sel_hi:[1,0,1]
	v_pk_fma_f32 v[214:215], v[90:91], v[174:175], v[214:215] op_sel_hi:[1,0,1]
	v_pk_fma_f32 v[216:217], v[88:89], v[182:183], v[216:217] op_sel_hi:[1,0,1]
	v_pk_fma_f32 v[218:219], v[90:91], v[182:183], v[218:219] op_sel_hi:[1,0,1]
	v_pk_fma_f32 v[220:221], v[88:89], v[190:191], v[220:221] op_sel_hi:[1,0,1]
	v_pk_fma_f32 v[222:223], v[90:91], v[190:191], v[222:223] op_sel_hi:[1,0,1]
	v_pk_fma_f32 v[224:225], v[88:89], v[198:199], v[224:225] op_sel_hi:[1,0,1]
	v_pk_fma_f32 v[226:227], v[90:91], v[198:199], v[226:227] op_sel_hi:[1,0,1]
	v_pk_fma_f32 v[228:229], v[88:89], v[206:207], v[228:229] op_sel_hi:[1,0,1]
	v_pk_fma_f32 v[230:231], v[90:91], v[206:207], v[230:231] op_sel_hi:[1,0,1]
	v_pk_fma_f32 v[212:213], v[92:93], v[174:175], v[212:213] op_sel:[0,1,0] op_sel_hi:[1,1,1]
	v_pk_fma_f32 v[214:215], v[94:95], v[174:175], v[214:215] op_sel:[0,1,0] op_sel_hi:[1,1,1]
	v_pk_fma_f32 v[216:217], v[92:93], v[182:183], v[216:217] op_sel:[0,1,0] op_sel_hi:[1,1,1]
	v_pk_fma_f32 v[218:219], v[94:95], v[182:183], v[218:219] op_sel:[0,1,0] op_sel_hi:[1,1,1]
	v_pk_fma_f32 v[220:221], v[92:93], v[190:191], v[220:221] op_sel:[0,1,0] op_sel_hi:[1,1,1]
	v_pk_fma_f32 v[222:223], v[94:95], v[190:191], v[222:223] op_sel:[0,1,0] op_sel_hi:[1,1,1]
	v_pk_fma_f32 v[224:225], v[92:93], v[198:199], v[224:225] op_sel:[0,1,0] op_sel_hi:[1,1,1]
	v_pk_fma_f32 v[226:227], v[94:95], v[198:199], v[226:227] op_sel:[0,1,0] op_sel_hi:[1,1,1]
	v_pk_fma_f32 v[228:229], v[92:93], v[206:207], v[228:229] op_sel:[0,1,0] op_sel_hi:[1,1,1]
	v_pk_fma_f32 v[230:231], v[94:95], v[206:207], v[230:231] op_sel:[0,1,0] op_sel_hi:[1,1,1]
	v_pk_fma_f32 v[212:213], v[96:97], v[176:177], v[212:213] op_sel_hi:[1,0,1]
	v_pk_fma_f32 v[214:215], v[98:99], v[176:177], v[214:215] op_sel_hi:[1,0,1]
	v_pk_fma_f32 v[216:217], v[96:97], v[184:185], v[216:217] op_sel_hi:[1,0,1]
	v_pk_fma_f32 v[218:219], v[98:99], v[184:185], v[218:219] op_sel_hi:[1,0,1]
	v_pk_fma_f32 v[220:221], v[96:97], v[192:193], v[220:221] op_sel_hi:[1,0,1]
	v_pk_fma_f32 v[222:223], v[98:99], v[192:193], v[222:223] op_sel_hi:[1,0,1]
	v_pk_fma_f32 v[224:225], v[96:97], v[200:201], v[224:225] op_sel_hi:[1,0,1]
	v_pk_fma_f32 v[226:227], v[98:99], v[200:201], v[226:227] op_sel_hi:[1,0,1]
	v_pk_fma_f32 v[228:229], v[96:97], v[208:209], v[228:229] op_sel_hi:[1,0,1]
	v_pk_fma_f32 v[230:231], v[98:99], v[208:209], v[230:231] op_sel_hi:[1,0,1]
	v_pk_fma_f32 v[212:213], v[100:101], v[176:177], v[212:213] op_sel:[0,1,0] op_sel_hi:[1,1,1]
	v_pk_fma_f32 v[214:215], v[102:103], v[176:177], v[214:215] op_sel:[0,1,0] op_sel_hi:[1,1,1]
	v_pk_fma_f32 v[216:217], v[100:101], v[184:185], v[216:217] op_sel:[0,1,0] op_sel_hi:[1,1,1]
	v_pk_fma_f32 v[218:219], v[102:103], v[184:185], v[218:219] op_sel:[0,1,0] op_sel_hi:[1,1,1]
	v_pk_fma_f32 v[220:221], v[100:101], v[192:193], v[220:221] op_sel:[0,1,0] op_sel_hi:[1,1,1]
	v_pk_fma_f32 v[222:223], v[102:103], v[192:193], v[222:223] op_sel:[0,1,0] op_sel_hi:[1,1,1]
	v_pk_fma_f32 v[224:225], v[100:101], v[200:201], v[224:225] op_sel:[0,1,0] op_sel_hi:[1,1,1]
	v_pk_fma_f32 v[226:227], v[102:103], v[200:201], v[226:227] op_sel:[0,1,0] op_sel_hi:[1,1,1]
	v_pk_fma_f32 v[228:229], v[100:101], v[208:209], v[228:229] op_sel:[0,1,0] op_sel_hi:[1,1,1]
	v_pk_fma_f32 v[230:231], v[102:103], v[208:209], v[230:231] op_sel:[0,1,0] op_sel_hi:[1,1,1]
	v_pk_fma_f32 v[212:213], v[104:105], v[178:179], v[212:213] op_sel_hi:[1,0,1]
	v_pk_fma_f32 v[214:215], v[106:107], v[178:179], v[214:215] op_sel_hi:[1,0,1]
	v_pk_fma_f32 v[216:217], v[104:105], v[186:187], v[216:217] op_sel_hi:[1,0,1]
	v_pk_fma_f32 v[218:219], v[106:107], v[186:187], v[218:219] op_sel_hi:[1,0,1]
	v_pk_fma_f32 v[220:221], v[104:105], v[194:195], v[220:221] op_sel_hi:[1,0,1]
	v_pk_fma_f32 v[222:223], v[106:107], v[194:195], v[222:223] op_sel_hi:[1,0,1]
	v_pk_fma_f32 v[224:225], v[104:105], v[202:203], v[224:225] op_sel_hi:[1,0,1]
; __device__ __forceinline__ void ada_item(const Params& P, int item, float* sm) {
;     ...
;     for (int kk = 0; kk < 64; ++kk) {
;         const f32x4 w4 = *(const f32x4*)(wp + (size_t)kk * 9216);
; #pragma unroll
;         for (int r = 0; r < 5; ++r) { const float s = sv[r * 1024 + kg * 64 + kk]; a[r] += w4 * s; }
	v_pk_fma_f32 v[226:227], v[106:107], v[202:203], v[226:227] op_sel_hi:[1,0,1]
	v_pk_fma_f32 v[228:229], v[104:105], v[210:211], v[228:229] op_sel_hi:[1,0,1]
	v_pk_fma_f32 v[230:231], v[106:107], v[210:211], v[230:231] op_sel_hi:[1,0,1]
	v_pk_fma_f32 v[212:213], v[108:109], v[178:179], v[212:213] op_sel:[0,1,0] op_sel_hi:[1,1,1]
	v_pk_fma_f32 v[214:215], v[110:111], v[178:179], v[214:215] op_sel:[0,1,0] op_sel_hi:[1,1,1]
	v_pk_fma_f32 v[216:217], v[108:109], v[186:187], v[216:217] op_sel:[0,1,0] op_sel_hi:[1,1,1]
	v_pk_fma_f32 v[218:219], v[110:111], v[186:187], v[218:219] op_sel:[0,1,0] op_sel_hi:[1,1,1]
	v_pk_fma_f32 v[220:221], v[108:109], v[194:195], v[220:221] op_sel:[0,1,0] op_sel_hi:[1,1,1]
	v_pk_fma_f32 v[222:223], v[110:111], v[194:195], v[222:223] op_sel:[0,1,0] op_sel_hi:[1,1,1]
	v_pk_fma_f32 v[224:225], v[108:109], v[202:203], v[224:225] op_sel:[0,1,0] op_sel_hi:[1,1,1]
	v_pk_fma_f32 v[226:227], v[110:111], v[202:203], v[226:227] op_sel:[0,1,0] op_sel_hi:[1,1,1]
	v_pk_fma_f32 v[228:229], v[108:109], v[210:211], v[228:229] op_sel:[0,1,0] op_sel_hi:[1,1,1]
	v_pk_fma_f32 v[230:231], v[110:111], v[210:211], v[230:231] op_sel:[0,1,0] op_sel_hi:[1,1,1]
	global_load_dwordx4 v[80:83], v4, s[6:7]
	s_add_u32 s6, s6, 0x48000
	s_addc_u32 s7, s7, 0
	global_load_dwordx4 v[84:87], v4, s[6:7]
	s_add_u32 s6, s6, 0x48000
	s_addc_u32 s7, s7, 0
	global_load_dwordx4 v[88:91], v4, s[6:7]
	s_add_u32 s6, s6, 0x48000
	s_addc_u32 s7, s7, 0
	global_load_dwordx4 v[92:95], v4, s[6:7]
	s_add_u32 s6, s6, 0x48000
	s_addc_u32 s7, s7, 0
	global_load_dwordx4 v[96:99], v4, s[6:7]
	s_add_u32 s6, s6, 0x48000
	s_addc_u32 s7, s7, 0
	global_load_dwordx4 v[100:103], v4, s[6:7]
	s_add_u32 s6, s6, 0x48000
	s_addc_u32 s7, s7, 0
	global_load_dwordx4 v[104:107], v4, s[6:7]
	s_add_u32 s6, s6, 0x48000
	s_addc_u32 s7, s7, 0
	global_load_dwordx4 v[108:111], v4, s[6:7]
	s_add_u32 s6, s6, 0x48000
	s_addc_u32 s7, s7, 0
	ds_read_b128 v[172:175], v5 offset:96
	ds_read_b128 v[176:179], v5 offset:112
	ds_read_b128 v[180:183], v5 offset:4320
	ds_read_b128 v[184:187], v5 offset:4336
	ds_read_b128 v[188:191], v5 offset:8544
	ds_read_b128 v[192:195], v5 offset:8560
	ds_read_b128 v[196:199], v5 offset:12768
	ds_read_b128 v[200:203], v5 offset:12784
	ds_read_b128 v[204:207], v5 offset:16992
	ds_read_b128 v[208:211], v5 offset:17008
	s_waitcnt vmcnt(24)
	s_waitcnt lgkmcnt(0)
	v_pk_fma_f32 v[212:213], v[112:113], v[172:173], v[212:213] op_sel_hi:[1,0,1]
	v_pk_fma_f32 v[214:215], v[114:115], v[172:173], v[214:215] op_sel_hi:[1,0,1]
	v_pk_fma_f32 v[216:217], v[112:113], v[180:181], v[216:217] op_sel_hi:[1,0,1]
	v_pk_fma_f32 v[218:219], v[114:115], v[180:181], v[218:219] op_sel_hi:[1,0,1]
	v_pk_fma_f32 v[220:221], v[112:113], v[188:189], v[220:221] op_sel_hi:[1,0,1]
	v_pk_fma_f32 v[222:223], v[114:115], v[188:189], v[222:223] op_sel_hi:[1,0,1]
	v_pk_fma_f32 v[224:225], v[112:113], v[196:197], v[224:225] op_sel_hi:[1,0,1]
	v_pk_fma_f32 v[226:227], v[114:115], v[196:197], v[226:227] op_sel_hi:[1,0,1]
	v_pk_fma_f32 v[228:229], v[112:113], v[204:205], v[228:229] op_sel_hi:[1,0,1]
	v_pk_fma_f32 v[230:231], v[114:115], v[204:205], v[230:231] op_sel_hi:[1,0,1]
	v_pk_fma_f32 v[212:213], v[116:117], v[172:173], v[212:213] op_sel:[0,1,0] op_sel_hi:[1,1,1]
	v_pk_fma_f32 v[214:215], v[118:119], v[172:173], v[214:215] op_sel:[0,1,0] op_sel_hi:[1,1,1]
	v_pk_fma_f32 v[216:217], v[116:117], v[180:181], v[216:217] op_sel:[0,1,0] op_sel_hi:[1,1,1]
	v_pk_fma_f32 v[218:219], v[118:119], v[180:181], v[218:219] op_sel:[0,1,0] op_sel_hi:[1,1,1]
	v_pk_fma_f32 v[220:221], v[116:117], v[188:189], v[220:221] op_sel:[0,1,0] op_sel_hi:[1,1,1]
	v_pk_fma_f32 v[222:223], v[118:119], v[188:189], v[222:223] op_sel:[0,1,0] op_sel_hi:[1,1,1]
	v_pk_fma_f32 v[224:225], v[116:117], v[196:197], v[224:225] op_sel:[0,1,0] op_sel_hi:[1,1,1]
	v_pk_fma_f32 v[226:227], v[118:119], v[196:197], v[226:227] op_sel:[0,1,0] op_sel_hi:[1,1,1]
	v_pk_fma_f32 v[228:229], v[116:117], v[204:205], v[228:229] op_sel:[0,1,0] op_sel_hi:[1,1,1]
	v_pk_fma_f32 v[230:231], v[118:119], v[204:205], v[230:231] op_sel:[0,1,0] op_sel_hi:[1,1,1]
	v_pk_fma_f32 v[212:213], v[120:121], v[174:175], v[212:213] op_sel_hi:[1,0,1]
	v_pk_fma_f32 v[214:215], v[122:123], v[174:175], v[214:215] op_sel_hi:[1,0,1]
	v_pk_fma_f32 v[216:217], v[120:121], v[182:183], v[216:217] op_sel_hi:[1,0,1]
	v_pk_fma_f32 v[218:219], v[122:123], v[182:183], v[218:219] op_sel_hi:[1,0,1]
	v_pk_fma_f32 v[220:221], v[120:121], v[190:191], v[220:221] op_sel_hi:[1,0,1]
	v_pk_fma_f32 v[222:223], v[122:123], v[190:191], v[222:223] op_sel_hi:[1,0,1]
	v_pk_fma_f32 v[224:225], v[120:121], v[198:199], v[224:225] op_sel_hi:[1,0,1]
	v_pk_fma_f32 v[226:227], v[122:123], v[198:199], v[226:227] op_sel_hi:[1,0,1]
	v_pk_fma_f32 v[228:229], v[120:121], v[206:207], v[228:229] op_sel_hi:[1,0,1]
	v_pk_fma_f32 v[230:231], v[122:123], v[206:207], v[230:231] op_sel_hi:[1,0,1]
	v_pk_fma_f32 v[212:213], v[124:125], v[174:175], v[212:213] op_sel:[0,1,0] op_sel_hi:[1,1,1]
	v_pk_fma_f32 v[214:215], v[126:127], v[174:175], v[214:215] op_sel:[0,1,0] op_sel_hi:[1,1,1]
	v_pk_fma_f32 v[216:217], v[124:125], v[182:183], v[216:217] op_sel:[0,1,0] op_sel_hi:[1,1,1]
	v_pk_fma_f32 v[218:219], v[126:127], v[182:183], v[218:219] op_sel:[0,1,0] op_sel_hi:[1,1,1]
	v_pk_fma_f32 v[220:221], v[124:125], v[190:191], v[220:221] op_sel:[0,1,0] op_sel_hi:[1,1,1]
	v_pk_fma_f32 v[222:223], v[126:127], v[190:191], v[222:223] op_sel:[0,1,0] op_sel_hi:[1,1,1]
	v_pk_fma_f32 v[224:225], v[124:125], v[198:199], v[224:225] op_sel:[0,1,0] op_sel_hi:[1,1,1]
	v_pk_fma_f32 v[226:227], v[126:127], v[198:199], v[226:227] op_sel:[0,1,0] op_sel_hi:[1,1,1]
; __device__ __forceinline__ void ada_item(const Params& P, int item, float* sm) {
;     ...
;     for (int kk = 0; kk < 64; ++kk) {
;         const f32x4 w4 = *(const f32x4*)(wp + (size_t)kk * 9216);
; #pragma unroll
;         for (int r = 0; r < 5; ++r) { const float s = sv[r * 1024 + kg * 64 + kk]; a[r] += w4 * s; }
	v_pk_fma_f32 v[228:229], v[124:125], v[206:207], v[228:229] op_sel:[0,1,0] op_sel_hi:[1,1,1]
	v_pk_fma_f32 v[230:231], v[126:127], v[206:207], v[230:231] op_sel:[0,1,0] op_sel_hi:[1,1,1]
	v_pk_fma_f32 v[212:213], v[128:129], v[176:177], v[212:213] op_sel_hi:[1,0,1]
	v_pk_fma_f32 v[214:215], v[130:131], v[176:177], v[214:215] op_sel_hi:[1,0,1]
	v_pk_fma_f32 v[216:217], v[128:129], v[184:185], v[216:217] op_sel_hi:[1,0,1]
	v_pk_fma_f32 v[218:219], v[130:131], v[184:185], v[218:219] op_sel_hi:[1,0,1]
	v_pk_fma_f32 v[220:221], v[128:129], v[192:193], v[220:221] op_sel_hi:[1,0,1]
	v_pk_fma_f32 v[222:223], v[130:131], v[192:193], v[222:223] op_sel_hi:[1,0,1]
	v_pk_fma_f32 v[224:225], v[128:129], v[200:201], v[224:225] op_sel_hi:[1,0,1]
	v_pk_fma_f32 v[226:227], v[130:131], v[200:201], v[226:227] op_sel_hi:[1,0,1]
	v_pk_fma_f32 v[228:229], v[128:129], v[208:209], v[228:229] op_sel_hi:[1,0,1]
	v_pk_fma_f32 v[230:231], v[130:131], v[208:209], v[230:231] op_sel_hi:[1,0,1]
	v_pk_fma_f32 v[212:213], v[132:133], v[176:177], v[212:213] op_sel:[0,1,0] op_sel_hi:[1,1,1]
	v_pk_fma_f32 v[214:215], v[134:135], v[176:177], v[214:215] op_sel:[0,1,0] op_sel_hi:[1,1,1]
	v_pk_fma_f32 v[216:217], v[132:133], v[184:185], v[216:217] op_sel:[0,1,0] op_sel_hi:[1,1,1]
	v_pk_fma_f32 v[218:219], v[134:135], v[184:185], v[218:219] op_sel:[0,1,0] op_sel_hi:[1,1,1]
	v_pk_fma_f32 v[220:221], v[132:133], v[192:193], v[220:221] op_sel:[0,1,0] op_sel_hi:[1,1,1]
	v_pk_fma_f32 v[222:223], v[134:135], v[192:193], v[222:223] op_sel:[0,1,0] op_sel_hi:[1,1,1]
	v_pk_fma_f32 v[224:225], v[132:133], v[200:201], v[224:225] op_sel:[0,1,0] op_sel_hi:[1,1,1]
	v_pk_fma_f32 v[226:227], v[134:135], v[200:201], v[226:227] op_sel:[0,1,0] op_sel_hi:[1,1,1]
	v_pk_fma_f32 v[228:229], v[132:133], v[208:209], v[228:229] op_sel:[0,1,0] op_sel_hi:[1,1,1]
	v_pk_fma_f32 v[230:231], v[134:135], v[208:209], v[230:231] op_sel:[0,1,0] op_sel_hi:[1,1,1]
	v_pk_fma_f32 v[212:213], v[136:137], v[178:179], v[212:213] op_sel_hi:[1,0,1]
	v_pk_fma_f32 v[214:215], v[138:139], v[178:179], v[214:215] op_sel_hi:[1,0,1]
	v_pk_fma_f32 v[216:217], v[136:137], v[186:187], v[216:217] op_sel_hi:[1,0,1]
	v_pk_fma_f32 v[218:219], v[138:139], v[186:187], v[218:219] op_sel_hi:[1,0,1]
	v_pk_fma_f32 v[220:221], v[136:137], v[194:195], v[220:221] op_sel_hi:[1,0,1]
	v_pk_fma_f32 v[222:223], v[138:139], v[194:195], v[222:223] op_sel_hi:[1,0,1]
	v_pk_fma_f32 v[224:225], v[136:137], v[202:203], v[224:225] op_sel_hi:[1,0,1]
	v_pk_fma_f32 v[226:227], v[138:139], v[202:203], v[226:227] op_sel_hi:[1,0,1]
	v_pk_fma_f32 v[228:229], v[136:137], v[210:211], v[228:229] op_sel_hi:[1,0,1]
	v_pk_fma_f32 v[230:231], v[138:139], v[210:211], v[230:231] op_sel_hi:[1,0,1]
	v_pk_fma_f32 v[212:213], v[140:141], v[178:179], v[212:213] op_sel:[0,1,0] op_sel_hi:[1,1,1]
	v_pk_fma_f32 v[214:215], v[142:143], v[178:179], v[214:215] op_sel:[0,1,0] op_sel_hi:[1,1,1]
	v_pk_fma_f32 v[216:217], v[140:141], v[186:187], v[216:217] op_sel:[0,1,0] op_sel_hi:[1,1,1]
	v_pk_fma_f32 v[218:219], v[142:143], v[186:187], v[218:219] op_sel:[0,1,0] op_sel_hi:[1,1,1]
	v_pk_fma_f32 v[220:221], v[140:141], v[194:195], v[220:221] op_sel:[0,1,0] op_sel_hi:[1,1,1]
	v_pk_fma_f32 v[222:223], v[142:143], v[194:195], v[222:223] op_sel:[0,1,0] op_sel_hi:[1,1,1]
	v_pk_fma_f32 v[224:225], v[140:141], v[202:203], v[224:225] op_sel:[0,1,0] op_sel_hi:[1,1,1]
	v_pk_fma_f32 v[226:227], v[142:143], v[202:203], v[226:227] op_sel:[0,1,0] op_sel_hi:[1,1,1]
	v_pk_fma_f32 v[228:229], v[140:141], v[210:211], v[228:229] op_sel:[0,1,0] op_sel_hi:[1,1,1]
	v_pk_fma_f32 v[230:231], v[142:143], v[210:211], v[230:231] op_sel:[0,1,0] op_sel_hi:[1,1,1]
	global_load_dwordx4 v[112:115], v4, s[6:7]
	s_add_u32 s6, s6, 0x48000
	s_addc_u32 s7, s7, 0
	global_load_dwordx4 v[116:119], v4, s[6:7]
	s_add_u32 s6, s6, 0x48000
	s_addc_u32 s7, s7, 0
	global_load_dwordx4 v[120:123], v4, s[6:7]
	s_add_u32 s6, s6, 0x48000
	s_addc_u32 s7, s7, 0
	global_load_dwordx4 v[124:127], v4, s[6:7]
	s_add_u32 s6, s6, 0x48000
	s_addc_u32 s7, s7, 0
	global_load_dwordx4 v[128:131], v4, s[6:7]
	s_add_u32 s6, s6, 0x48000
	s_addc_u32 s7, s7, 0
	global_load_dwordx4 v[132:135], v4, s[6:7]
	s_add_u32 s6, s6, 0x48000
	s_addc_u32 s7, s7, 0
	global_load_dwordx4 v[136:139], v4, s[6:7]
	s_add_u32 s6, s6, 0x48000
	s_addc_u32 s7, s7, 0
	global_load_dwordx4 v[140:143], v4, s[6:7]
	s_add_u32 s6, s6, 0x48000
	s_addc_u32 s7, s7, 0
	ds_read_b128 v[172:175], v5 offset:128
	ds_read_b128 v[176:179], v5 offset:144
	ds_read_b128 v[180:183], v5 offset:4352
	ds_read_b128 v[184:187], v5 offset:4368
	ds_read_b128 v[188:191], v5 offset:8576
	ds_read_b128 v[192:195], v5 offset:8592
	ds_read_b128 v[196:199], v5 offset:12800
	ds_read_b128 v[200:203], v5 offset:12816
	ds_read_b128 v[204:207], v5 offset:17024
	ds_read_b128 v[208:211], v5 offset:17040
	s_waitcnt vmcnt(24)
	s_waitcnt lgkmcnt(0)
; __device__ __forceinline__ void ada_item(const Params& P, int item, float* sm) {
;     ...
;     for (int kk = 0; kk < 64; ++kk) {
;         const f32x4 w4 = *(const f32x4*)(wp + (size_t)kk * 9216);
; #pragma unroll
;         for (int r = 0; r < 5; ++r) { const float s = sv[r * 1024 + kg * 64 + kk]; a[r] += w4 * s; }
	v_pk_fma_f32 v[212:213], v[16:17], v[172:173], v[212:213] op_sel_hi:[1,0,1]
	v_pk_fma_f32 v[214:215], v[18:19], v[172:173], v[214:215] op_sel_hi:[1,0,1]
	v_pk_fma_f32 v[216:217], v[16:17], v[180:181], v[216:217] op_sel_hi:[1,0,1]
	v_pk_fma_f32 v[218:219], v[18:19], v[180:181], v[218:219] op_sel_hi:[1,0,1]
	v_pk_fma_f32 v[220:221], v[16:17], v[188:189], v[220:221] op_sel_hi:[1,0,1]
	v_pk_fma_f32 v[222:223], v[18:19], v[188:189], v[222:223] op_sel_hi:[1,0,1]
	v_pk_fma_f32 v[224:225], v[16:17], v[196:197], v[224:225] op_sel_hi:[1,0,1]
	v_pk_fma_f32 v[226:227], v[18:19], v[196:197], v[226:227] op_sel_hi:[1,0,1]
	v_pk_fma_f32 v[228:229], v[16:17], v[204:205], v[228:229] op_sel_hi:[1,0,1]
	v_pk_fma_f32 v[230:231], v[18:19], v[204:205], v[230:231] op_sel_hi:[1,0,1]
	v_pk_fma_f32 v[212:213], v[20:21], v[172:173], v[212:213] op_sel:[0,1,0] op_sel_hi:[1,1,1]
	v_pk_fma_f32 v[214:215], v[22:23], v[172:173], v[214:215] op_sel:[0,1,0] op_sel_hi:[1,1,1]
	v_pk_fma_f32 v[216:217], v[20:21], v[180:181], v[216:217] op_sel:[0,1,0] op_sel_hi:[1,1,1]
	v_pk_fma_f32 v[218:219], v[22:23], v[180:181], v[218:219] op_sel:[0,1,0] op_sel_hi:[1,1,1]
	v_pk_fma_f32 v[220:221], v[20:21], v[188:189], v[220:221] op_sel:[0,1,0] op_sel_hi:[1,1,1]
	v_pk_fma_f32 v[222:223], v[22:23], v[188:189], v[222:223] op_sel:[0,1,0] op_sel_hi:[1,1,1]
	v_pk_fma_f32 v[224:225], v[20:21], v[196:197], v[224:225] op_sel:[0,1,0] op_sel_hi:[1,1,1]
	v_pk_fma_f32 v[226:227], v[22:23], v[196:197], v[226:227] op_sel:[0,1,0] op_sel_hi:[1,1,1]
	v_pk_fma_f32 v[228:229], v[20:21], v[204:205], v[228:229] op_sel:[0,1,0] op_sel_hi:[1,1,1]
	v_pk_fma_f32 v[230:231], v[22:23], v[204:205], v[230:231] op_sel:[0,1,0] op_sel_hi:[1,1,1]
	v_pk_fma_f32 v[212:213], v[24:25], v[174:175], v[212:213] op_sel_hi:[1,0,1]
	v_pk_fma_f32 v[214:215], v[26:27], v[174:175], v[214:215] op_sel_hi:[1,0,1]
	v_pk_fma_f32 v[216:217], v[24:25], v[182:183], v[216:217] op_sel_hi:[1,0,1]
	v_pk_fma_f32 v[218:219], v[26:27], v[182:183], v[218:219] op_sel_hi:[1,0,1]
	v_pk_fma_f32 v[220:221], v[24:25], v[190:191], v[220:221] op_sel_hi:[1,0,1]
	v_pk_fma_f32 v[222:223], v[26:27], v[190:191], v[222:223] op_sel_hi:[1,0,1]
	v_pk_fma_f32 v[224:225], v[24:25], v[198:199], v[224:225] op_sel_hi:[1,0,1]
	v_pk_fma_f32 v[226:227], v[26:27], v[198:199], v[226:227] op_sel_hi:[1,0,1]
	v_pk_fma_f32 v[228:229], v[24:25], v[206:207], v[228:229] op_sel_hi:[1,0,1]
	v_pk_fma_f32 v[230:231], v[26:27], v[206:207], v[230:231] op_sel_hi:[1,0,1]
	v_pk_fma_f32 v[212:213], v[28:29], v[174:175], v[212:213] op_sel:[0,1,0] op_sel_hi:[1,1,1]
	v_pk_fma_f32 v[214:215], v[30:31], v[174:175], v[214:215] op_sel:[0,1,0] op_sel_hi:[1,1,1]
	v_pk_fma_f32 v[216:217], v[28:29], v[182:183], v[216:217] op_sel:[0,1,0] op_sel_hi:[1,1,1]
	v_pk_fma_f32 v[218:219], v[30:31], v[182:183], v[218:219] op_sel:[0,1,0] op_sel_hi:[1,1,1]
	v_pk_fma_f32 v[220:221], v[28:29], v[190:191], v[220:221] op_sel:[0,1,0] op_sel_hi:[1,1,1]
	v_pk_fma_f32 v[222:223], v[30:31], v[190:191], v[222:223] op_sel:[0,1,0] op_sel_hi:[1,1,1]
	v_pk_fma_f32 v[224:225], v[28:29], v[198:199], v[224:225] op_sel:[0,1,0] op_sel_hi:[1,1,1]
	v_pk_fma_f32 v[226:227], v[30:31], v[198:199], v[226:227] op_sel:[0,1,0] op_sel_hi:[1,1,1]
	v_pk_fma_f32 v[228:229], v[28:29], v[206:207], v[228:229] op_sel:[0,1,0] op_sel_hi:[1,1,1]
	v_pk_fma_f32 v[230:231], v[30:31], v[206:207], v[230:231] op_sel:[0,1,0] op_sel_hi:[1,1,1]
	v_pk_fma_f32 v[212:213], v[32:33], v[176:177], v[212:213] op_sel_hi:[1,0,1]
	v_pk_fma_f32 v[214:215], v[34:35], v[176:177], v[214:215] op_sel_hi:[1,0,1]
	v_pk_fma_f32 v[216:217], v[32:33], v[184:185], v[216:217] op_sel_hi:[1,0,1]
	v_pk_fma_f32 v[218:219], v[34:35], v[184:185], v[218:219] op_sel_hi:[1,0,1]
	v_pk_fma_f32 v[220:221], v[32:33], v[192:193], v[220:221] op_sel_hi:[1,0,1]
	v_pk_fma_f32 v[222:223], v[34:35], v[192:193], v[222:223] op_sel_hi:[1,0,1]
	v_pk_fma_f32 v[224:225], v[32:33], v[200:201], v[224:225] op_sel_hi:[1,0,1]
	v_pk_fma_f32 v[226:227], v[34:35], v[200:201], v[226:227] op_sel_hi:[1,0,1]
	v_pk_fma_f32 v[228:229], v[32:33], v[208:209], v[228:229] op_sel_hi:[1,0,1]
	v_pk_fma_f32 v[230:231], v[34:35], v[208:209], v[230:231] op_sel_hi:[1,0,1]
	v_pk_fma_f32 v[212:213], v[36:37], v[176:177], v[212:213] op_sel:[0,1,0] op_sel_hi:[1,1,1]
	v_pk_fma_f32 v[214:215], v[38:39], v[176:177], v[214:215] op_sel:[0,1,0] op_sel_hi:[1,1,1]
	v_pk_fma_f32 v[216:217], v[36:37], v[184:185], v[216:217] op_sel:[0,1,0] op_sel_hi:[1,1,1]
	v_pk_fma_f32 v[218:219], v[38:39], v[184:185], v[218:219] op_sel:[0,1,0] op_sel_hi:[1,1,1]
	v_pk_fma_f32 v[220:221], v[36:37], v[192:193], v[220:221] op_sel:[0,1,0] op_sel_hi:[1,1,1]
	v_pk_fma_f32 v[222:223], v[38:39], v[192:193], v[222:223] op_sel:[0,1,0] op_sel_hi:[1,1,1]
	v_pk_fma_f32 v[224:225], v[36:37], v[200:201], v[224:225] op_sel:[0,1,0] op_sel_hi:[1,1,1]
	v_pk_fma_f32 v[226:227], v[38:39], v[200:201], v[226:227] op_sel:[0,1,0] op_sel_hi:[1,1,1]
	v_pk_fma_f32 v[228:229], v[36:37], v[208:209], v[228:229] op_sel:[0,1,0] op_sel_hi:[1,1,1]
	v_pk_fma_f32 v[230:231], v[38:39], v[208:209], v[230:231] op_sel:[0,1,0] op_sel_hi:[1,1,1]
	v_pk_fma_f32 v[212:213], v[40:41], v[178:179], v[212:213] op_sel_hi:[1,0,1]
	v_pk_fma_f32 v[214:215], v[42:43], v[178:179], v[214:215] op_sel_hi:[1,0,1]
	v_pk_fma_f32 v[216:217], v[40:41], v[186:187], v[216:217] op_sel_hi:[1,0,1]
	v_pk_fma_f32 v[218:219], v[42:43], v[186:187], v[218:219] op_sel_hi:[1,0,1]
	v_pk_fma_f32 v[220:221], v[40:41], v[194:195], v[220:221] op_sel_hi:[1,0,1]
	v_pk_fma_f32 v[222:223], v[42:43], v[194:195], v[222:223] op_sel_hi:[1,0,1]
	v_pk_fma_f32 v[224:225], v[40:41], v[202:203], v[224:225] op_sel_hi:[1,0,1]
; __device__ __forceinline__ void ada_item(const Params& P, int item, float* sm) {
;     ...
;     for (int kk = 0; kk < 64; ++kk) {
;         const f32x4 w4 = *(const f32x4*)(wp + (size_t)kk * 9216);
; #pragma unroll
;         for (int r = 0; r < 5; ++r) { const float s = sv[r * 1024 + kg * 64 + kk]; a[r] += w4 * s; }
	v_pk_fma_f32 v[226:227], v[42:43], v[202:203], v[226:227] op_sel_hi:[1,0,1]
	v_pk_fma_f32 v[228:229], v[40:41], v[210:211], v[228:229] op_sel_hi:[1,0,1]
	v_pk_fma_f32 v[230:231], v[42:43], v[210:211], v[230:231] op_sel_hi:[1,0,1]
	v_pk_fma_f32 v[212:213], v[44:45], v[178:179], v[212:213] op_sel:[0,1,0] op_sel_hi:[1,1,1]
	v_pk_fma_f32 v[214:215], v[46:47], v[178:179], v[214:215] op_sel:[0,1,0] op_sel_hi:[1,1,1]
	v_pk_fma_f32 v[216:217], v[44:45], v[186:187], v[216:217] op_sel:[0,1,0] op_sel_hi:[1,1,1]
	v_pk_fma_f32 v[218:219], v[46:47], v[186:187], v[218:219] op_sel:[0,1,0] op_sel_hi:[1,1,1]
	v_pk_fma_f32 v[220:221], v[44:45], v[194:195], v[220:221] op_sel:[0,1,0] op_sel_hi:[1,1,1]
	v_pk_fma_f32 v[222:223], v[46:47], v[194:195], v[222:223] op_sel:[0,1,0] op_sel_hi:[1,1,1]
	v_pk_fma_f32 v[224:225], v[44:45], v[202:203], v[224:225] op_sel:[0,1,0] op_sel_hi:[1,1,1]
	v_pk_fma_f32 v[226:227], v[46:47], v[202:203], v[226:227] op_sel:[0,1,0] op_sel_hi:[1,1,1]
	v_pk_fma_f32 v[228:229], v[44:45], v[210:211], v[228:229] op_sel:[0,1,0] op_sel_hi:[1,1,1]
	v_pk_fma_f32 v[230:231], v[46:47], v[210:211], v[230:231] op_sel:[0,1,0] op_sel_hi:[1,1,1]
	global_load_dwordx4 v[16:19], v4, s[6:7]
	s_add_u32 s6, s6, 0x48000
	s_addc_u32 s7, s7, 0
	global_load_dwordx4 v[20:23], v4, s[6:7]
	s_add_u32 s6, s6, 0x48000
	s_addc_u32 s7, s7, 0
	global_load_dwordx4 v[24:27], v4, s[6:7]
	s_add_u32 s6, s6, 0x48000
	s_addc_u32 s7, s7, 0
	global_load_dwordx4 v[28:31], v4, s[6:7]
	s_add_u32 s6, s6, 0x48000
	s_addc_u32 s7, s7, 0
	global_load_dwordx4 v[32:35], v4, s[6:7]
	s_add_u32 s6, s6, 0x48000
	s_addc_u32 s7, s7, 0
	global_load_dwordx4 v[36:39], v4, s[6:7]
	s_add_u32 s6, s6, 0x48000
	s_addc_u32 s7, s7, 0
	global_load_dwordx4 v[40:43], v4, s[6:7]
	s_add_u32 s6, s6, 0x48000
	s_addc_u32 s7, s7, 0
	global_load_dwordx4 v[44:47], v4, s[6:7]
	s_add_u32 s6, s6, 0x48000
	s_addc_u32 s7, s7, 0
	ds_read_b128 v[172:175], v5 offset:160
	ds_read_b128 v[176:179], v5 offset:176
	ds_read_b128 v[180:183], v5 offset:4384
	ds_read_b128 v[184:187], v5 offset:4400
	ds_read_b128 v[188:191], v5 offset:8608
	ds_read_b128 v[192:195], v5 offset:8624
	ds_read_b128 v[196:199], v5 offset:12832
	ds_read_b128 v[200:203], v5 offset:12848
	ds_read_b128 v[204:207], v5 offset:17056
	ds_read_b128 v[208:211], v5 offset:17072
	s_waitcnt vmcnt(24)
	s_waitcnt lgkmcnt(0)
	v_pk_fma_f32 v[212:213], v[48:49], v[172:173], v[212:213] op_sel_hi:[1,0,1]
	v_pk_fma_f32 v[214:215], v[50:51], v[172:173], v[214:215] op_sel_hi:[1,0,1]
	v_pk_fma_f32 v[216:217], v[48:49], v[180:181], v[216:217] op_sel_hi:[1,0,1]
	v_pk_fma_f32 v[218:219], v[50:51], v[180:181], v[218:219] op_sel_hi:[1,0,1]
	v_pk_fma_f32 v[220:221], v[48:49], v[188:189], v[220:221] op_sel_hi:[1,0,1]
	v_pk_fma_f32 v[222:223], v[50:51], v[188:189], v[222:223] op_sel_hi:[1,0,1]
	v_pk_fma_f32 v[224:225], v[48:49], v[196:197], v[224:225] op_sel_hi:[1,0,1]
	v_pk_fma_f32 v[226:227], v[50:51], v[196:197], v[226:227] op_sel_hi:[1,0,1]
	v_pk_fma_f32 v[228:229], v[48:49], v[204:205], v[228:229] op_sel_hi:[1,0,1]
	v_pk_fma_f32 v[230:231], v[50:51], v[204:205], v[230:231] op_sel_hi:[1,0,1]
	v_pk_fma_f32 v[212:213], v[52:53], v[172:173], v[212:213] op_sel:[0,1,0] op_sel_hi:[1,1,1]
	v_pk_fma_f32 v[214:215], v[54:55], v[172:173], v[214:215] op_sel:[0,1,0] op_sel_hi:[1,1,1]
	v_pk_fma_f32 v[216:217], v[52:53], v[180:181], v[216:217] op_sel:[0,1,0] op_sel_hi:[1,1,1]
	v_pk_fma_f32 v[218:219], v[54:55], v[180:181], v[218:219] op_sel:[0,1,0] op_sel_hi:[1,1,1]
	v_pk_fma_f32 v[220:221], v[52:53], v[188:189], v[220:221] op_sel:[0,1,0] op_sel_hi:[1,1,1]
	v_pk_fma_f32 v[222:223], v[54:55], v[188:189], v[222:223] op_sel:[0,1,0] op_sel_hi:[1,1,1]
	v_pk_fma_f32 v[224:225], v[52:53], v[196:197], v[224:225] op_sel:[0,1,0] op_sel_hi:[1,1,1]
	v_pk_fma_f32 v[226:227], v[54:55], v[196:197], v[226:227] op_sel:[0,1,0] op_sel_hi:[1,1,1]
	v_pk_fma_f32 v[228:229], v[52:53], v[204:205], v[228:229] op_sel:[0,1,0] op_sel_hi:[1,1,1]
	v_pk_fma_f32 v[230:231], v[54:55], v[204:205], v[230:231] op_sel:[0,1,0] op_sel_hi:[1,1,1]
	v_pk_fma_f32 v[212:213], v[56:57], v[174:175], v[212:213] op_sel_hi:[1,0,1]
	v_pk_fma_f32 v[214:215], v[58:59], v[174:175], v[214:215] op_sel_hi:[1,0,1]
	v_pk_fma_f32 v[216:217], v[56:57], v[182:183], v[216:217] op_sel_hi:[1,0,1]
	v_pk_fma_f32 v[218:219], v[58:59], v[182:183], v[218:219] op_sel_hi:[1,0,1]
	v_pk_fma_f32 v[220:221], v[56:57], v[190:191], v[220:221] op_sel_hi:[1,0,1]
	v_pk_fma_f32 v[222:223], v[58:59], v[190:191], v[222:223] op_sel_hi:[1,0,1]
	v_pk_fma_f32 v[224:225], v[56:57], v[198:199], v[224:225] op_sel_hi:[1,0,1]
	v_pk_fma_f32 v[226:227], v[58:59], v[198:199], v[226:227] op_sel_hi:[1,0,1]
	v_pk_fma_f32 v[228:229], v[56:57], v[206:207], v[228:229] op_sel_hi:[1,0,1]
	v_pk_fma_f32 v[230:231], v[58:59], v[206:207], v[230:231] op_sel_hi:[1,0,1]
	v_pk_fma_f32 v[212:213], v[60:61], v[174:175], v[212:213] op_sel:[0,1,0] op_sel_hi:[1,1,1]
	v_pk_fma_f32 v[214:215], v[62:63], v[174:175], v[214:215] op_sel:[0,1,0] op_sel_hi:[1,1,1]
	v_pk_fma_f32 v[216:217], v[60:61], v[182:183], v[216:217] op_sel:[0,1,0] op_sel_hi:[1,1,1]
	v_pk_fma_f32 v[218:219], v[62:63], v[182:183], v[218:219] op_sel:[0,1,0] op_sel_hi:[1,1,1]
	v_pk_fma_f32 v[220:221], v[60:61], v[190:191], v[220:221] op_sel:[0,1,0] op_sel_hi:[1,1,1]
	v_pk_fma_f32 v[222:223], v[62:63], v[190:191], v[222:223] op_sel:[0,1,0] op_sel_hi:[1,1,1]
	v_pk_fma_f32 v[224:225], v[60:61], v[198:199], v[224:225] op_sel:[0,1,0] op_sel_hi:[1,1,1]
	v_pk_fma_f32 v[226:227], v[62:63], v[198:199], v[226:227] op_sel:[0,1,0] op_sel_hi:[1,1,1]
	v_pk_fma_f32 v[228:229], v[60:61], v[206:207], v[228:229] op_sel:[0,1,0] op_sel_hi:[1,1,1]
; __device__ __forceinline__ void ada_item(const Params& P, int item, float* sm) {
;     ...
;     for (int kk = 0; kk < 64; ++kk) {
;         const f32x4 w4 = *(const f32x4*)(wp + (size_t)kk * 9216);
; #pragma unroll
;         for (int r = 0; r < 5; ++r) { const float s = sv[r * 1024 + kg * 64 + kk]; a[r] += w4 * s; }
	v_pk_fma_f32 v[230:231], v[62:63], v[206:207], v[230:231] op_sel:[0,1,0] op_sel_hi:[1,1,1]
	v_pk_fma_f32 v[212:213], v[64:65], v[176:177], v[212:213] op_sel_hi:[1,0,1]
	v_pk_fma_f32 v[214:215], v[66:67], v[176:177], v[214:215] op_sel_hi:[1,0,1]
	v_pk_fma_f32 v[216:217], v[64:65], v[184:185], v[216:217] op_sel_hi:[1,0,1]
	v_pk_fma_f32 v[218:219], v[66:67], v[184:185], v[218:219] op_sel_hi:[1,0,1]
	v_pk_fma_f32 v[220:221], v[64:65], v[192:193], v[220:221] op_sel_hi:[1,0,1]
	v_pk_fma_f32 v[222:223], v[66:67], v[192:193], v[222:223] op_sel_hi:[1,0,1]
	v_pk_fma_f32 v[224:225], v[64:65], v[200:201], v[224:225] op_sel_hi:[1,0,1]
	v_pk_fma_f32 v[226:227], v[66:67], v[200:201], v[226:227] op_sel_hi:[1,0,1]
	v_pk_fma_f32 v[228:229], v[64:65], v[208:209], v[228:229] op_sel_hi:[1,0,1]
	v_pk_fma_f32 v[230:231], v[66:67], v[208:209], v[230:231] op_sel_hi:[1,0,1]
	v_pk_fma_f32 v[212:213], v[68:69], v[176:177], v[212:213] op_sel:[0,1,0] op_sel_hi:[1,1,1]
	v_pk_fma_f32 v[214:215], v[70:71], v[176:177], v[214:215] op_sel:[0,1,0] op_sel_hi:[1,1,1]
	v_pk_fma_f32 v[216:217], v[68:69], v[184:185], v[216:217] op_sel:[0,1,0] op_sel_hi:[1,1,1]
	v_pk_fma_f32 v[218:219], v[70:71], v[184:185], v[218:219] op_sel:[0,1,0] op_sel_hi:[1,1,1]
	v_pk_fma_f32 v[220:221], v[68:69], v[192:193], v[220:221] op_sel:[0,1,0] op_sel_hi:[1,1,1]
	v_pk_fma_f32 v[222:223], v[70:71], v[192:193], v[222:223] op_sel:[0,1,0] op_sel_hi:[1,1,1]
	v_pk_fma_f32 v[224:225], v[68:69], v[200:201], v[224:225] op_sel:[0,1,0] op_sel_hi:[1,1,1]
	v_pk_fma_f32 v[226:227], v[70:71], v[200:201], v[226:227] op_sel:[0,1,0] op_sel_hi:[1,1,1]
	v_pk_fma_f32 v[228:229], v[68:69], v[208:209], v[228:229] op_sel:[0,1,0] op_sel_hi:[1,1,1]
	v_pk_fma_f32 v[230:231], v[70:71], v[208:209], v[230:231] op_sel:[0,1,0] op_sel_hi:[1,1,1]
	v_pk_fma_f32 v[212:213], v[72:73], v[178:179], v[212:213] op_sel_hi:[1,0,1]
	v_pk_fma_f32 v[214:215], v[74:75], v[178:179], v[214:215] op_sel_hi:[1,0,1]
	v_pk_fma_f32 v[216:217], v[72:73], v[186:187], v[216:217] op_sel_hi:[1,0,1]
	v_pk_fma_f32 v[218:219], v[74:75], v[186:187], v[218:219] op_sel_hi:[1,0,1]
	v_pk_fma_f32 v[220:221], v[72:73], v[194:195], v[220:221] op_sel_hi:[1,0,1]
	v_pk_fma_f32 v[222:223], v[74:75], v[194:195], v[222:223] op_sel_hi:[1,0,1]
	v_pk_fma_f32 v[224:225], v[72:73], v[202:203], v[224:225] op_sel_hi:[1,0,1]
	v_pk_fma_f32 v[226:227], v[74:75], v[202:203], v[226:227] op_sel_hi:[1,0,1]
	v_pk_fma_f32 v[228:229], v[72:73], v[210:211], v[228:229] op_sel_hi:[1,0,1]
	v_pk_fma_f32 v[230:231], v[74:75], v[210:211], v[230:231] op_sel_hi:[1,0,1]
	v_pk_fma_f32 v[212:213], v[76:77], v[178:179], v[212:213] op_sel:[0,1,0] op_sel_hi:[1,1,1]
	v_pk_fma_f32 v[214:215], v[78:79], v[178:179], v[214:215] op_sel:[0,1,0] op_sel_hi:[1,1,1]
	v_pk_fma_f32 v[216:217], v[76:77], v[186:187], v[216:217] op_sel:[0,1,0] op_sel_hi:[1,1,1]
	v_pk_fma_f32 v[218:219], v[78:79], v[186:187], v[218:219] op_sel:[0,1,0] op_sel_hi:[1,1,1]
	v_pk_fma_f32 v[220:221], v[76:77], v[194:195], v[220:221] op_sel:[0,1,0] op_sel_hi:[1,1,1]
	v_pk_fma_f32 v[222:223], v[78:79], v[194:195], v[222:223] op_sel:[0,1,0] op_sel_hi:[1,1,1]
	v_pk_fma_f32 v[224:225], v[76:77], v[202:203], v[224:225] op_sel:[0,1,0] op_sel_hi:[1,1,1]
	v_pk_fma_f32 v[226:227], v[78:79], v[202:203], v[226:227] op_sel:[0,1,0] op_sel_hi:[1,1,1]
	v_pk_fma_f32 v[228:229], v[76:77], v[210:211], v[228:229] op_sel:[0,1,0] op_sel_hi:[1,1,1]
	v_pk_fma_f32 v[230:231], v[78:79], v[210:211], v[230:231] op_sel:[0,1,0] op_sel_hi:[1,1,1]
	global_load_dwordx4 v[48:51], v4, s[6:7]
	s_add_u32 s6, s6, 0x48000
	s_addc_u32 s7, s7, 0
	global_load_dwordx4 v[52:55], v4, s[6:7]
	s_add_u32 s6, s6, 0x48000
	s_addc_u32 s7, s7, 0
	global_load_dwordx4 v[56:59], v4, s[6:7]
	s_add_u32 s6, s6, 0x48000
	s_addc_u32 s7, s7, 0
	global_load_dwordx4 v[60:63], v4, s[6:7]
	s_add_u32 s6, s6, 0x48000
	s_addc_u32 s7, s7, 0
	global_load_dwordx4 v[64:67], v4, s[6:7]
	s_add_u32 s6, s6, 0x48000
	s_addc_u32 s7, s7, 0
	global_load_dwordx4 v[68:71], v4, s[6:7]
	s_add_u32 s6, s6, 0x48000
	s_addc_u32 s7, s7, 0
	global_load_dwordx4 v[72:75], v4, s[6:7]
	s_add_u32 s6, s6, 0x48000
	s_addc_u32 s7, s7, 0
	global_load_dwordx4 v[76:79], v4, s[6:7]
	s_add_u32 s6, s6, 0x48000
	s_addc_u32 s7, s7, 0
	ds_read_b128 v[172:175], v5 offset:192
	ds_read_b128 v[176:179], v5 offset:208
	ds_read_b128 v[180:183], v5 offset:4416
	ds_read_b128 v[184:187], v5 offset:4432
	ds_read_b128 v[188:191], v5 offset:8640
	ds_read_b128 v[192:195], v5 offset:8656
	ds_read_b128 v[196:199], v5 offset:12864
	ds_read_b128 v[200:203], v5 offset:12880
	ds_read_b128 v[204:207], v5 offset:17088
	ds_read_b128 v[208:211], v5 offset:17104
	s_waitcnt vmcnt(24)
	s_waitcnt lgkmcnt(0)
; __device__ __forceinline__ void ada_item(const Params& P, int item, float* sm) {
;     ...
;     for (int kk = 0; kk < 64; ++kk) {
;         const f32x4 w4 = *(const f32x4*)(wp + (size_t)kk * 9216);
; #pragma unroll
;         for (int r = 0; r < 5; ++r) { const float s = sv[r * 1024 + kg * 64 + kk]; a[r] += w4 * s; }
	v_pk_fma_f32 v[212:213], v[80:81], v[172:173], v[212:213] op_sel_hi:[1,0,1]
	v_pk_fma_f32 v[214:215], v[82:83], v[172:173], v[214:215] op_sel_hi:[1,0,1]
	v_pk_fma_f32 v[216:217], v[80:81], v[180:181], v[216:217] op_sel_hi:[1,0,1]
	v_pk_fma_f32 v[218:219], v[82:83], v[180:181], v[218:219] op_sel_hi:[1,0,1]
	v_pk_fma_f32 v[220:221], v[80:81], v[188:189], v[220:221] op_sel_hi:[1,0,1]
	v_pk_fma_f32 v[222:223], v[82:83], v[188:189], v[222:223] op_sel_hi:[1,0,1]
	v_pk_fma_f32 v[224:225], v[80:81], v[196:197], v[224:225] op_sel_hi:[1,0,1]
	v_pk_fma_f32 v[226:227], v[82:83], v[196:197], v[226:227] op_sel_hi:[1,0,1]
	v_pk_fma_f32 v[228:229], v[80:81], v[204:205], v[228:229] op_sel_hi:[1,0,1]
	v_pk_fma_f32 v[230:231], v[82:83], v[204:205], v[230:231] op_sel_hi:[1,0,1]
	v_pk_fma_f32 v[212:213], v[84:85], v[172:173], v[212:213] op_sel:[0,1,0] op_sel_hi:[1,1,1]
	v_pk_fma_f32 v[214:215], v[86:87], v[172:173], v[214:215] op_sel:[0,1,0] op_sel_hi:[1,1,1]
	v_pk_fma_f32 v[216:217], v[84:85], v[180:181], v[216:217] op_sel:[0,1,0] op_sel_hi:[1,1,1]
	v_pk_fma_f32 v[218:219], v[86:87], v[180:181], v[218:219] op_sel:[0,1,0] op_sel_hi:[1,1,1]
	v_pk_fma_f32 v[220:221], v[84:85], v[188:189], v[220:221] op_sel:[0,1,0] op_sel_hi:[1,1,1]
	v_pk_fma_f32 v[222:223], v[86:87], v[188:189], v[222:223] op_sel:[0,1,0] op_sel_hi:[1,1,1]
	v_pk_fma_f32 v[224:225], v[84:85], v[196:197], v[224:225] op_sel:[0,1,0] op_sel_hi:[1,1,1]
	v_pk_fma_f32 v[226:227], v[86:87], v[196:197], v[226:227] op_sel:[0,1,0] op_sel_hi:[1,1,1]
	v_pk_fma_f32 v[228:229], v[84:85], v[204:205], v[228:229] op_sel:[0,1,0] op_sel_hi:[1,1,1]
	v_pk_fma_f32 v[230:231], v[86:87], v[204:205], v[230:231] op_sel:[0,1,0] op_sel_hi:[1,1,1]
	v_pk_fma_f32 v[212:213], v[88:89], v[174:175], v[212:213] op_sel_hi:[1,0,1]
	v_pk_fma_f32 v[214:215], v[90:91], v[174:175], v[214:215] op_sel_hi:[1,0,1]
	v_pk_fma_f32 v[216:217], v[88:89], v[182:183], v[216:217] op_sel_hi:[1,0,1]
	v_pk_fma_f32 v[218:219], v[90:91], v[182:183], v[218:219] op_sel_hi:[1,0,1]
	v_pk_fma_f32 v[220:221], v[88:89], v[190:191], v[220:221] op_sel_hi:[1,0,1]
	v_pk_fma_f32 v[222:223], v[90:91], v[190:191], v[222:223] op_sel_hi:[1,0,1]
	v_pk_fma_f32 v[224:225], v[88:89], v[198:199], v[224:225] op_sel_hi:[1,0,1]
	v_pk_fma_f32 v[226:227], v[90:91], v[198:199], v[226:227] op_sel_hi:[1,0,1]
	v_pk_fma_f32 v[228:229], v[88:89], v[206:207], v[228:229] op_sel_hi:[1,0,1]
	v_pk_fma_f32 v[230:231], v[90:91], v[206:207], v[230:231] op_sel_hi:[1,0,1]
	v_pk_fma_f32 v[212:213], v[92:93], v[174:175], v[212:213] op_sel:[0,1,0] op_sel_hi:[1,1,1]
	v_pk_fma_f32 v[214:215], v[94:95], v[174:175], v[214:215] op_sel:[0,1,0] op_sel_hi:[1,1,1]
	v_pk_fma_f32 v[216:217], v[92:93], v[182:183], v[216:217] op_sel:[0,1,0] op_sel_hi:[1,1,1]
	v_pk_fma_f32 v[218:219], v[94:95], v[182:183], v[218:219] op_sel:[0,1,0] op_sel_hi:[1,1,1]
	v_pk_fma_f32 v[220:221], v[92:93], v[190:191], v[220:221] op_sel:[0,1,0] op_sel_hi:[1,1,1]
	v_pk_fma_f32 v[222:223], v[94:95], v[190:191], v[222:223] op_sel:[0,1,0] op_sel_hi:[1,1,1]
	v_pk_fma_f32 v[224:225], v[92:93], v[198:199], v[224:225] op_sel:[0,1,0] op_sel_hi:[1,1,1]
	v_pk_fma_f32 v[226:227], v[94:95], v[198:199], v[226:227] op_sel:[0,1,0] op_sel_hi:[1,1,1]
	v_pk_fma_f32 v[228:229], v[92:93], v[206:207], v[228:229] op_sel:[0,1,0] op_sel_hi:[1,1,1]
	v_pk_fma_f32 v[230:231], v[94:95], v[206:207], v[230:231] op_sel:[0,1,0] op_sel_hi:[1,1,1]
	v_pk_fma_f32 v[212:213], v[96:97], v[176:177], v[212:213] op_sel_hi:[1,0,1]
	v_pk_fma_f32 v[214:215], v[98:99], v[176:177], v[214:215] op_sel_hi:[1,0,1]
	v_pk_fma_f32 v[216:217], v[96:97], v[184:185], v[216:217] op_sel_hi:[1,0,1]
	v_pk_fma_f32 v[218:219], v[98:99], v[184:185], v[218:219] op_sel_hi:[1,0,1]
	v_pk_fma_f32 v[220:221], v[96:97], v[192:193], v[220:221] op_sel_hi:[1,0,1]
	v_pk_fma_f32 v[222:223], v[98:99], v[192:193], v[222:223] op_sel_hi:[1,0,1]
	v_pk_fma_f32 v[224:225], v[96:97], v[200:201], v[224:225] op_sel_hi:[1,0,1]
	v_pk_fma_f32 v[226:227], v[98:99], v[200:201], v[226:227] op_sel_hi:[1,0,1]
	v_pk_fma_f32 v[228:229], v[96:97], v[208:209], v[228:229] op_sel_hi:[1,0,1]
	v_pk_fma_f32 v[230:231], v[98:99], v[208:209], v[230:231] op_sel_hi:[1,0,1]
	v_pk_fma_f32 v[212:213], v[100:101], v[176:177], v[212:213] op_sel:[0,1,0] op_sel_hi:[1,1,1]
	v_pk_fma_f32 v[214:215], v[102:103], v[176:177], v[214:215] op_sel:[0,1,0] op_sel_hi:[1,1,1]
	v_pk_fma_f32 v[216:217], v[100:101], v[184:185], v[216:217] op_sel:[0,1,0] op_sel_hi:[1,1,1]
	v_pk_fma_f32 v[218:219], v[102:103], v[184:185], v[218:219] op_sel:[0,1,0] op_sel_hi:[1,1,1]
	v_pk_fma_f32 v[220:221], v[100:101], v[192:193], v[220:221] op_sel:[0,1,0] op_sel_hi:[1,1,1]
	v_pk_fma_f32 v[222:223], v[102:103], v[192:193], v[222:223] op_sel:[0,1,0] op_sel_hi:[1,1,1]
	v_pk_fma_f32 v[224:225], v[100:101], v[200:201], v[224:225] op_sel:[0,1,0] op_sel_hi:[1,1,1]
	v_pk_fma_f32 v[226:227], v[102:103], v[200:201], v[226:227] op_sel:[0,1,0] op_sel_hi:[1,1,1]
	v_pk_fma_f32 v[228:229], v[100:101], v[208:209], v[228:229] op_sel:[0,1,0] op_sel_hi:[1,1,1]
	v_pk_fma_f32 v[230:231], v[102:103], v[208:209], v[230:231] op_sel:[0,1,0] op_sel_hi:[1,1,1]
	v_pk_fma_f32 v[212:213], v[104:105], v[178:179], v[212:213] op_sel_hi:[1,0,1]
	v_pk_fma_f32 v[214:215], v[106:107], v[178:179], v[214:215] op_sel_hi:[1,0,1]
	v_pk_fma_f32 v[216:217], v[104:105], v[186:187], v[216:217] op_sel_hi:[1,0,1]
	v_pk_fma_f32 v[218:219], v[106:107], v[186:187], v[218:219] op_sel_hi:[1,0,1]
	v_pk_fma_f32 v[220:221], v[104:105], v[194:195], v[220:221] op_sel_hi:[1,0,1]
	v_pk_fma_f32 v[222:223], v[106:107], v[194:195], v[222:223] op_sel_hi:[1,0,1]
	v_pk_fma_f32 v[224:225], v[104:105], v[202:203], v[224:225] op_sel_hi:[1,0,1]
; __device__ __forceinline__ void ada_item(const Params& P, int item, float* sm) {
;     ...
;     for (int kk = 0; kk < 64; ++kk) {
;         const f32x4 w4 = *(const f32x4*)(wp + (size_t)kk * 9216);
; #pragma unroll
;         for (int r = 0; r < 5; ++r) { const float s = sv[r * 1024 + kg * 64 + kk]; a[r] += w4 * s; }
	v_pk_fma_f32 v[226:227], v[106:107], v[202:203], v[226:227] op_sel_hi:[1,0,1]
	v_pk_fma_f32 v[228:229], v[104:105], v[210:211], v[228:229] op_sel_hi:[1,0,1]
	v_pk_fma_f32 v[230:231], v[106:107], v[210:211], v[230:231] op_sel_hi:[1,0,1]
	v_pk_fma_f32 v[212:213], v[108:109], v[178:179], v[212:213] op_sel:[0,1,0] op_sel_hi:[1,1,1]
	v_pk_fma_f32 v[214:215], v[110:111], v[178:179], v[214:215] op_sel:[0,1,0] op_sel_hi:[1,1,1]
	v_pk_fma_f32 v[216:217], v[108:109], v[186:187], v[216:217] op_sel:[0,1,0] op_sel_hi:[1,1,1]
	v_pk_fma_f32 v[218:219], v[110:111], v[186:187], v[218:219] op_sel:[0,1,0] op_sel_hi:[1,1,1]
	v_pk_fma_f32 v[220:221], v[108:109], v[194:195], v[220:221] op_sel:[0,1,0] op_sel_hi:[1,1,1]
	v_pk_fma_f32 v[222:223], v[110:111], v[194:195], v[222:223] op_sel:[0,1,0] op_sel_hi:[1,1,1]
	v_pk_fma_f32 v[224:225], v[108:109], v[202:203], v[224:225] op_sel:[0,1,0] op_sel_hi:[1,1,1]
	v_pk_fma_f32 v[226:227], v[110:111], v[202:203], v[226:227] op_sel:[0,1,0] op_sel_hi:[1,1,1]
	v_pk_fma_f32 v[228:229], v[108:109], v[210:211], v[228:229] op_sel:[0,1,0] op_sel_hi:[1,1,1]
	v_pk_fma_f32 v[230:231], v[110:111], v[210:211], v[230:231] op_sel:[0,1,0] op_sel_hi:[1,1,1]
	global_load_dwordx4 v[80:83], v4, s[6:7]
	s_add_u32 s6, s6, 0x48000
	s_addc_u32 s7, s7, 0
	global_load_dwordx4 v[84:87], v4, s[6:7]
	s_add_u32 s6, s6, 0x48000
	s_addc_u32 s7, s7, 0
	global_load_dwordx4 v[88:91], v4, s[6:7]
	s_add_u32 s6, s6, 0x48000
	s_addc_u32 s7, s7, 0
	global_load_dwordx4 v[92:95], v4, s[6:7]
	s_add_u32 s6, s6, 0x48000
	s_addc_u32 s7, s7, 0
	global_load_dwordx4 v[96:99], v4, s[6:7]
	s_add_u32 s6, s6, 0x48000
	s_addc_u32 s7, s7, 0
	global_load_dwordx4 v[100:103], v4, s[6:7]
	s_add_u32 s6, s6, 0x48000
	s_addc_u32 s7, s7, 0
	global_load_dwordx4 v[104:107], v4, s[6:7]
	s_add_u32 s6, s6, 0x48000
	s_addc_u32 s7, s7, 0
	global_load_dwordx4 v[108:111], v4, s[6:7]
	s_add_u32 s6, s6, 0x48000
	s_addc_u32 s7, s7, 0
	ds_read_b128 v[172:175], v5 offset:224
	ds_read_b128 v[176:179], v5 offset:240
	ds_read_b128 v[180:183], v5 offset:4448
	ds_read_b128 v[184:187], v5 offset:4464
	ds_read_b128 v[188:191], v5 offset:8672
	ds_read_b128 v[192:195], v5 offset:8688
	ds_read_b128 v[196:199], v5 offset:12896
	ds_read_b128 v[200:203], v5 offset:12912
	ds_read_b128 v[204:207], v5 offset:17120
	ds_read_b128 v[208:211], v5 offset:17136
	s_waitcnt vmcnt(24)
	s_waitcnt lgkmcnt(0)
	v_pk_fma_f32 v[212:213], v[112:113], v[172:173], v[212:213] op_sel_hi:[1,0,1]
	v_pk_fma_f32 v[214:215], v[114:115], v[172:173], v[214:215] op_sel_hi:[1,0,1]
	v_pk_fma_f32 v[216:217], v[112:113], v[180:181], v[216:217] op_sel_hi:[1,0,1]
	v_pk_fma_f32 v[218:219], v[114:115], v[180:181], v[218:219] op_sel_hi:[1,0,1]
	v_pk_fma_f32 v[220:221], v[112:113], v[188:189], v[220:221] op_sel_hi:[1,0,1]
	v_pk_fma_f32 v[222:223], v[114:115], v[188:189], v[222:223] op_sel_hi:[1,0,1]
	v_pk_fma_f32 v[224:225], v[112:113], v[196:197], v[224:225] op_sel_hi:[1,0,1]
	v_pk_fma_f32 v[226:227], v[114:115], v[196:197], v[226:227] op_sel_hi:[1,0,1]
	v_pk_fma_f32 v[228:229], v[112:113], v[204:205], v[228:229] op_sel_hi:[1,0,1]
	v_pk_fma_f32 v[230:231], v[114:115], v[204:205], v[230:231] op_sel_hi:[1,0,1]
	v_pk_fma_f32 v[212:213], v[116:117], v[172:173], v[212:213] op_sel:[0,1,0] op_sel_hi:[1,1,1]
	v_pk_fma_f32 v[214:215], v[118:119], v[172:173], v[214:215] op_sel:[0,1,0] op_sel_hi:[1,1,1]
	v_pk_fma_f32 v[216:217], v[116:117], v[180:181], v[216:217] op_sel:[0,1,0] op_sel_hi:[1,1,1]
	v_pk_fma_f32 v[218:219], v[118:119], v[180:181], v[218:219] op_sel:[0,1,0] op_sel_hi:[1,1,1]
	v_pk_fma_f32 v[220:221], v[116:117], v[188:189], v[220:221] op_sel:[0,1,0] op_sel_hi:[1,1,1]
	v_pk_fma_f32 v[222:223], v[118:119], v[188:189], v[222:223] op_sel:[0,1,0] op_sel_hi:[1,1,1]
	v_pk_fma_f32 v[224:225], v[116:117], v[196:197], v[224:225] op_sel:[0,1,0] op_sel_hi:[1,1,1]
	v_pk_fma_f32 v[226:227], v[118:119], v[196:197], v[226:227] op_sel:[0,1,0] op_sel_hi:[1,1,1]
	v_pk_fma_f32 v[228:229], v[116:117], v[204:205], v[228:229] op_sel:[0,1,0] op_sel_hi:[1,1,1]
	v_pk_fma_f32 v[230:231], v[118:119], v[204:205], v[230:231] op_sel:[0,1,0] op_sel_hi:[1,1,1]
	v_pk_fma_f32 v[212:213], v[120:121], v[174:175], v[212:213] op_sel_hi:[1,0,1]
	v_pk_fma_f32 v[214:215], v[122:123], v[174:175], v[214:215] op_sel_hi:[1,0,1]
	v_pk_fma_f32 v[216:217], v[120:121], v[182:183], v[216:217] op_sel_hi:[1,0,1]
	v_pk_fma_f32 v[218:219], v[122:123], v[182:183], v[218:219] op_sel_hi:[1,0,1]
	v_pk_fma_f32 v[220:221], v[120:121], v[190:191], v[220:221] op_sel_hi:[1,0,1]
	v_pk_fma_f32 v[222:223], v[122:123], v[190:191], v[222:223] op_sel_hi:[1,0,1]
	v_pk_fma_f32 v[224:225], v[120:121], v[198:199], v[224:225] op_sel_hi:[1,0,1]
	v_pk_fma_f32 v[226:227], v[122:123], v[198:199], v[226:227] op_sel_hi:[1,0,1]
	v_pk_fma_f32 v[228:229], v[120:121], v[206:207], v[228:229] op_sel_hi:[1,0,1]
	v_pk_fma_f32 v[230:231], v[122:123], v[206:207], v[230:231] op_sel_hi:[1,0,1]
	v_pk_fma_f32 v[212:213], v[124:125], v[174:175], v[212:213] op_sel:[0,1,0] op_sel_hi:[1,1,1]
	v_pk_fma_f32 v[214:215], v[126:127], v[174:175], v[214:215] op_sel:[0,1,0] op_sel_hi:[1,1,1]
	v_pk_fma_f32 v[216:217], v[124:125], v[182:183], v[216:217] op_sel:[0,1,0] op_sel_hi:[1,1,1]
	v_pk_fma_f32 v[218:219], v[126:127], v[182:183], v[218:219] op_sel:[0,1,0] op_sel_hi:[1,1,1]
	v_pk_fma_f32 v[220:221], v[124:125], v[190:191], v[220:221] op_sel:[0,1,0] op_sel_hi:[1,1,1]
	v_pk_fma_f32 v[222:223], v[126:127], v[190:191], v[222:223] op_sel:[0,1,0] op_sel_hi:[1,1,1]
	v_pk_fma_f32 v[224:225], v[124:125], v[198:199], v[224:225] op_sel:[0,1,0] op_sel_hi:[1,1,1]
	v_pk_fma_f32 v[226:227], v[126:127], v[198:199], v[226:227] op_sel:[0,1,0] op_sel_hi:[1,1,1]
; __device__ __forceinline__ void ada_item(const Params& P, int item, float* sm) {
;     ...
;     for (int kk = 0; kk < 64; ++kk) {
;         const f32x4 w4 = *(const f32x4*)(wp + (size_t)kk * 9216);
; #pragma unroll
;         for (int r = 0; r < 5; ++r) { const float s = sv[r * 1024 + kg * 64 + kk]; a[r] += w4 * s; }
	v_pk_fma_f32 v[228:229], v[124:125], v[206:207], v[228:229] op_sel:[0,1,0] op_sel_hi:[1,1,1]
	v_pk_fma_f32 v[230:231], v[126:127], v[206:207], v[230:231] op_sel:[0,1,0] op_sel_hi:[1,1,1]
	v_pk_fma_f32 v[212:213], v[128:129], v[176:177], v[212:213] op_sel_hi:[1,0,1]
	v_pk_fma_f32 v[214:215], v[130:131], v[176:177], v[214:215] op_sel_hi:[1,0,1]
	v_pk_fma_f32 v[216:217], v[128:129], v[184:185], v[216:217] op_sel_hi:[1,0,1]
	v_pk_fma_f32 v[218:219], v[130:131], v[184:185], v[218:219] op_sel_hi:[1,0,1]
	v_pk_fma_f32 v[220:221], v[128:129], v[192:193], v[220:221] op_sel_hi:[1,0,1]
	v_pk_fma_f32 v[222:223], v[130:131], v[192:193], v[222:223] op_sel_hi:[1,0,1]
	v_pk_fma_f32 v[224:225], v[128:129], v[200:201], v[224:225] op_sel_hi:[1,0,1]
	v_pk_fma_f32 v[226:227], v[130:131], v[200:201], v[226:227] op_sel_hi:[1,0,1]
	v_pk_fma_f32 v[228:229], v[128:129], v[208:209], v[228:229] op_sel_hi:[1,0,1]
	v_pk_fma_f32 v[230:231], v[130:131], v[208:209], v[230:231] op_sel_hi:[1,0,1]
	v_pk_fma_f32 v[212:213], v[132:133], v[176:177], v[212:213] op_sel:[0,1,0] op_sel_hi:[1,1,1]
	v_pk_fma_f32 v[214:215], v[134:135], v[176:177], v[214:215] op_sel:[0,1,0] op_sel_hi:[1,1,1]
	v_pk_fma_f32 v[216:217], v[132:133], v[184:185], v[216:217] op_sel:[0,1,0] op_sel_hi:[1,1,1]
	v_pk_fma_f32 v[218:219], v[134:135], v[184:185], v[218:219] op_sel:[0,1,0] op_sel_hi:[1,1,1]
	v_pk_fma_f32 v[220:221], v[132:133], v[192:193], v[220:221] op_sel:[0,1,0] op_sel_hi:[1,1,1]
	v_pk_fma_f32 v[222:223], v[134:135], v[192:193], v[222:223] op_sel:[0,1,0] op_sel_hi:[1,1,1]
	v_pk_fma_f32 v[224:225], v[132:133], v[200:201], v[224:225] op_sel:[0,1,0] op_sel_hi:[1,1,1]
	v_pk_fma_f32 v[226:227], v[134:135], v[200:201], v[226:227] op_sel:[0,1,0] op_sel_hi:[1,1,1]
	v_pk_fma_f32 v[228:229], v[132:133], v[208:209], v[228:229] op_sel:[0,1,0] op_sel_hi:[1,1,1]
	v_pk_fma_f32 v[230:231], v[134:135], v[208:209], v[230:231] op_sel:[0,1,0] op_sel_hi:[1,1,1]
	v_pk_fma_f32 v[212:213], v[136:137], v[178:179], v[212:213] op_sel_hi:[1,0,1]
	v_pk_fma_f32 v[214:215], v[138:139], v[178:179], v[214:215] op_sel_hi:[1,0,1]
	v_pk_fma_f32 v[216:217], v[136:137], v[186:187], v[216:217] op_sel_hi:[1,0,1]
	v_pk_fma_f32 v[218:219], v[138:139], v[186:187], v[218:219] op_sel_hi:[1,0,1]
	v_pk_fma_f32 v[220:221], v[136:137], v[194:195], v[220:221] op_sel_hi:[1,0,1]
	v_pk_fma_f32 v[222:223], v[138:139], v[194:195], v[222:223] op_sel_hi:[1,0,1]
	v_pk_fma_f32 v[224:225], v[136:137], v[202:203], v[224:225] op_sel_hi:[1,0,1]
	v_pk_fma_f32 v[226:227], v[138:139], v[202:203], v[226:227] op_sel_hi:[1,0,1]
	v_pk_fma_f32 v[228:229], v[136:137], v[210:211], v[228:229] op_sel_hi:[1,0,1]
	v_pk_fma_f32 v[230:231], v[138:139], v[210:211], v[230:231] op_sel_hi:[1,0,1]
	v_pk_fma_f32 v[212:213], v[140:141], v[178:179], v[212:213] op_sel:[0,1,0] op_sel_hi:[1,1,1]
	v_pk_fma_f32 v[214:215], v[142:143], v[178:179], v[214:215] op_sel:[0,1,0] op_sel_hi:[1,1,1]
	v_pk_fma_f32 v[216:217], v[140:141], v[186:187], v[216:217] op_sel:[0,1,0] op_sel_hi:[1,1,1]
	v_pk_fma_f32 v[218:219], v[142:143], v[186:187], v[218:219] op_sel:[0,1,0] op_sel_hi:[1,1,1]
	v_pk_fma_f32 v[220:221], v[140:141], v[194:195], v[220:221] op_sel:[0,1,0] op_sel_hi:[1,1,1]
	v_pk_fma_f32 v[222:223], v[142:143], v[194:195], v[222:223] op_sel:[0,1,0] op_sel_hi:[1,1,1]
	v_pk_fma_f32 v[224:225], v[140:141], v[202:203], v[224:225] op_sel:[0,1,0] op_sel_hi:[1,1,1]
	v_pk_fma_f32 v[226:227], v[142:143], v[202:203], v[226:227] op_sel:[0,1,0] op_sel_hi:[1,1,1]
	v_pk_fma_f32 v[228:229], v[140:141], v[210:211], v[228:229] op_sel:[0,1,0] op_sel_hi:[1,1,1]
	v_pk_fma_f32 v[230:231], v[142:143], v[210:211], v[230:231] op_sel:[0,1,0] op_sel_hi:[1,1,1]
	global_load_dwordx4 v[112:115], v4, s[6:7]
	s_add_u32 s6, s6, 0x48000
	s_addc_u32 s7, s7, 0
	global_load_dwordx4 v[116:119], v4, s[6:7]
	s_add_u32 s6, s6, 0x48000
	s_addc_u32 s7, s7, 0
	global_load_dwordx4 v[120:123], v4, s[6:7]
	s_add_u32 s6, s6, 0x48000
	s_addc_u32 s7, s7, 0
	global_load_dwordx4 v[124:127], v4, s[6:7]
	s_add_u32 s6, s6, 0x48000
	s_addc_u32 s7, s7, 0
	global_load_dwordx4 v[128:131], v4, s[6:7]
	s_add_u32 s6, s6, 0x48000
	s_addc_u32 s7, s7, 0
	global_load_dwordx4 v[132:135], v4, s[6:7]
	s_add_u32 s6, s6, 0x48000
	s_addc_u32 s7, s7, 0
	global_load_dwordx4 v[136:139], v4, s[6:7]
	s_add_u32 s6, s6, 0x48000
	s_addc_u32 s7, s7, 0
	global_load_dwordx4 v[140:143], v4, s[6:7]
	s_add_u32 s6, s6, 0x48000
	s_addc_u32 s7, s7, 0
	ds_read_b128 v[172:175], v5 offset:256
	ds_read_b128 v[176:179], v5 offset:272
	ds_read_b128 v[180:183], v5 offset:4480
	ds_read_b128 v[184:187], v5 offset:4496
	ds_read_b128 v[188:191], v5 offset:8704
	ds_read_b128 v[192:195], v5 offset:8720
	ds_read_b128 v[196:199], v5 offset:12928
	ds_read_b128 v[200:203], v5 offset:12944
	ds_read_b128 v[204:207], v5 offset:17152
	ds_read_b128 v[208:211], v5 offset:17168
	s_waitcnt vmcnt(24)
	s_waitcnt lgkmcnt(0)
; __device__ __forceinline__ void ada_item(const Params& P, int item, float* sm) {
;     ...
;     for (int kk = 0; kk < 64; ++kk) {
;         const f32x4 w4 = *(const f32x4*)(wp + (size_t)kk * 9216);
; #pragma unroll
;         for (int r = 0; r < 5; ++r) { const float s = sv[r * 1024 + kg * 64 + kk]; a[r] += w4 * s; }
	v_pk_fma_f32 v[212:213], v[16:17], v[172:173], v[212:213] op_sel_hi:[1,0,1]
	v_pk_fma_f32 v[214:215], v[18:19], v[172:173], v[214:215] op_sel_hi:[1,0,1]
	v_pk_fma_f32 v[216:217], v[16:17], v[180:181], v[216:217] op_sel_hi:[1,0,1]
	v_pk_fma_f32 v[218:219], v[18:19], v[180:181], v[218:219] op_sel_hi:[1,0,1]
	v_pk_fma_f32 v[220:221], v[16:17], v[188:189], v[220:221] op_sel_hi:[1,0,1]
	v_pk_fma_f32 v[222:223], v[18:19], v[188:189], v[222:223] op_sel_hi:[1,0,1]
	v_pk_fma_f32 v[224:225], v[16:17], v[196:197], v[224:225] op_sel_hi:[1,0,1]
	v_pk_fma_f32 v[226:227], v[18:19], v[196:197], v[226:227] op_sel_hi:[1,0,1]
	v_pk_fma_f32 v[228:229], v[16:17], v[204:205], v[228:229] op_sel_hi:[1,0,1]
	v_pk_fma_f32 v[230:231], v[18:19], v[204:205], v[230:231] op_sel_hi:[1,0,1]
	v_pk_fma_f32 v[212:213], v[20:21], v[172:173], v[212:213] op_sel:[0,1,0] op_sel_hi:[1,1,1]
	v_pk_fma_f32 v[214:215], v[22:23], v[172:173], v[214:215] op_sel:[0,1,0] op_sel_hi:[1,1,1]
	v_pk_fma_f32 v[216:217], v[20:21], v[180:181], v[216:217] op_sel:[0,1,0] op_sel_hi:[1,1,1]
	v_pk_fma_f32 v[218:219], v[22:23], v[180:181], v[218:219] op_sel:[0,1,0] op_sel_hi:[1,1,1]
	v_pk_fma_f32 v[220:221], v[20:21], v[188:189], v[220:221] op_sel:[0,1,0] op_sel_hi:[1,1,1]
	v_pk_fma_f32 v[222:223], v[22:23], v[188:189], v[222:223] op_sel:[0,1,0] op_sel_hi:[1,1,1]
	v_pk_fma_f32 v[224:225], v[20:21], v[196:197], v[224:225] op_sel:[0,1,0] op_sel_hi:[1,1,1]
	v_pk_fma_f32 v[226:227], v[22:23], v[196:197], v[226:227] op_sel:[0,1,0] op_sel_hi:[1,1,1]
	v_pk_fma_f32 v[228:229], v[20:21], v[204:205], v[228:229] op_sel:[0,1,0] op_sel_hi:[1,1,1]
	v_pk_fma_f32 v[230:231], v[22:23], v[204:205], v[230:231] op_sel:[0,1,0] op_sel_hi:[1,1,1]
	v_pk_fma_f32 v[212:213], v[24:25], v[174:175], v[212:213] op_sel_hi:[1,0,1]
	v_pk_fma_f32 v[214:215], v[26:27], v[174:175], v[214:215] op_sel_hi:[1,0,1]
	v_pk_fma_f32 v[216:217], v[24:25], v[182:183], v[216:217] op_sel_hi:[1,0,1]
	v_pk_fma_f32 v[218:219], v[26:27], v[182:183], v[218:219] op_sel_hi:[1,0,1]
	v_pk_fma_f32 v[220:221], v[24:25], v[190:191], v[220:221] op_sel_hi:[1,0,1]
	v_pk_fma_f32 v[222:223], v[26:27], v[190:191], v[222:223] op_sel_hi:[1,0,1]
	v_pk_fma_f32 v[224:225], v[24:25], v[198:199], v[224:225] op_sel_hi:[1,0,1]
	v_pk_fma_f32 v[226:227], v[26:27], v[198:199], v[226:227] op_sel_hi:[1,0,1]
	v_pk_fma_f32 v[228:229], v[24:25], v[206:207], v[228:229] op_sel_hi:[1,0,1]
	v_pk_fma_f32 v[230:231], v[26:27], v[206:207], v[230:231] op_sel_hi:[1,0,1]
	v_pk_fma_f32 v[212:213], v[28:29], v[174:175], v[212:213] op_sel:[0,1,0] op_sel_hi:[1,1,1]
	v_pk_fma_f32 v[214:215], v[30:31], v[174:175], v[214:215] op_sel:[0,1,0] op_sel_hi:[1,1,1]
	v_pk_fma_f32 v[216:217], v[28:29], v[182:183], v[216:217] op_sel:[0,1,0] op_sel_hi:[1,1,1]
	v_pk_fma_f32 v[218:219], v[30:31], v[182:183], v[218:219] op_sel:[0,1,0] op_sel_hi:[1,1,1]
	v_pk_fma_f32 v[220:221], v[28:29], v[190:191], v[220:221] op_sel:[0,1,0] op_sel_hi:[1,1,1]
	v_pk_fma_f32 v[222:223], v[30:31], v[190:191], v[222:223] op_sel:[0,1,0] op_sel_hi:[1,1,1]
	v_pk_fma_f32 v[224:225], v[28:29], v[198:199], v[224:225] op_sel:[0,1,0] op_sel_hi:[1,1,1]
	v_pk_fma_f32 v[226:227], v[30:31], v[198:199], v[226:227] op_sel:[0,1,0] op_sel_hi:[1,1,1]
	v_pk_fma_f32 v[228:229], v[28:29], v[206:207], v[228:229] op_sel:[0,1,0] op_sel_hi:[1,1,1]
	v_pk_fma_f32 v[230:231], v[30:31], v[206:207], v[230:231] op_sel:[0,1,0] op_sel_hi:[1,1,1]
	v_pk_fma_f32 v[212:213], v[32:33], v[176:177], v[212:213] op_sel_hi:[1,0,1]
	v_pk_fma_f32 v[214:215], v[34:35], v[176:177], v[214:215] op_sel_hi:[1,0,1]
	v_pk_fma_f32 v[216:217], v[32:33], v[184:185], v[216:217] op_sel_hi:[1,0,1]
	v_pk_fma_f32 v[218:219], v[34:35], v[184:185], v[218:219] op_sel_hi:[1,0,1]
	v_pk_fma_f32 v[220:221], v[32:33], v[192:193], v[220:221] op_sel_hi:[1,0,1]
	v_pk_fma_f32 v[222:223], v[34:35], v[192:193], v[222:223] op_sel_hi:[1,0,1]
	v_pk_fma_f32 v[224:225], v[32:33], v[200:201], v[224:225] op_sel_hi:[1,0,1]
	v_pk_fma_f32 v[226:227], v[34:35], v[200:201], v[226:227] op_sel_hi:[1,0,1]
	v_pk_fma_f32 v[228:229], v[32:33], v[208:209], v[228:229] op_sel_hi:[1,0,1]
	v_pk_fma_f32 v[230:231], v[34:35], v[208:209], v[230:231] op_sel_hi:[1,0,1]
	v_pk_fma_f32 v[212:213], v[36:37], v[176:177], v[212:213] op_sel:[0,1,0] op_sel_hi:[1,1,1]
	v_pk_fma_f32 v[214:215], v[38:39], v[176:177], v[214:215] op_sel:[0,1,0] op_sel_hi:[1,1,1]
	v_pk_fma_f32 v[216:217], v[36:37], v[184:185], v[216:217] op_sel:[0,1,0] op_sel_hi:[1,1,1]
	v_pk_fma_f32 v[218:219], v[38:39], v[184:185], v[218:219] op_sel:[0,1,0] op_sel_hi:[1,1,1]
	v_pk_fma_f32 v[220:221], v[36:37], v[192:193], v[220:221] op_sel:[0,1,0] op_sel_hi:[1,1,1]
	v_pk_fma_f32 v[222:223], v[38:39], v[192:193], v[222:223] op_sel:[0,1,0] op_sel_hi:[1,1,1]
	v_pk_fma_f32 v[224:225], v[36:37], v[200:201], v[224:225] op_sel:[0,1,0] op_sel_hi:[1,1,1]
	v_pk_fma_f32 v[226:227], v[38:39], v[200:201], v[226:227] op_sel:[0,1,0] op_sel_hi:[1,1,1]
	v_pk_fma_f32 v[228:229], v[36:37], v[208:209], v[228:229] op_sel:[0,1,0] op_sel_hi:[1,1,1]
	v_pk_fma_f32 v[230:231], v[38:39], v[208:209], v[230:231] op_sel:[0,1,0] op_sel_hi:[1,1,1]
	v_pk_fma_f32 v[212:213], v[40:41], v[178:179], v[212:213] op_sel_hi:[1,0,1]
	v_pk_fma_f32 v[214:215], v[42:43], v[178:179], v[214:215] op_sel_hi:[1,0,1]
	v_pk_fma_f32 v[216:217], v[40:41], v[186:187], v[216:217] op_sel_hi:[1,0,1]
	v_pk_fma_f32 v[218:219], v[42:43], v[186:187], v[218:219] op_sel_hi:[1,0,1]
	v_pk_fma_f32 v[220:221], v[40:41], v[194:195], v[220:221] op_sel_hi:[1,0,1]
	v_pk_fma_f32 v[222:223], v[42:43], v[194:195], v[222:223] op_sel_hi:[1,0,1]
	v_pk_fma_f32 v[224:225], v[40:41], v[202:203], v[224:225] op_sel_hi:[1,0,1]
; __device__ __forceinline__ void ada_item(const Params& P, int item, float* sm) {
;     ...
;     for (int kk = 0; kk < 64; ++kk) {
;         const f32x4 w4 = *(const f32x4*)(wp + (size_t)kk * 9216);
; #pragma unroll
;         for (int r = 0; r < 5; ++r) { const float s = sv[r * 1024 + kg * 64 + kk]; a[r] += w4 * s; }
	v_pk_fma_f32 v[226:227], v[42:43], v[202:203], v[226:227] op_sel_hi:[1,0,1]
	v_pk_fma_f32 v[228:229], v[40:41], v[210:211], v[228:229] op_sel_hi:[1,0,1]
	v_pk_fma_f32 v[230:231], v[42:43], v[210:211], v[230:231] op_sel_hi:[1,0,1]
	v_pk_fma_f32 v[212:213], v[44:45], v[178:179], v[212:213] op_sel:[0,1,0] op_sel_hi:[1,1,1]
	v_pk_fma_f32 v[214:215], v[46:47], v[178:179], v[214:215] op_sel:[0,1,0] op_sel_hi:[1,1,1]
	v_pk_fma_f32 v[216:217], v[44:45], v[186:187], v[216:217] op_sel:[0,1,0] op_sel_hi:[1,1,1]
	v_pk_fma_f32 v[218:219], v[46:47], v[186:187], v[218:219] op_sel:[0,1,0] op_sel_hi:[1,1,1]
	v_pk_fma_f32 v[220:221], v[44:45], v[194:195], v[220:221] op_sel:[0,1,0] op_sel_hi:[1,1,1]
	v_pk_fma_f32 v[222:223], v[46:47], v[194:195], v[222:223] op_sel:[0,1,0] op_sel_hi:[1,1,1]
	v_pk_fma_f32 v[224:225], v[44:45], v[202:203], v[224:225] op_sel:[0,1,0] op_sel_hi:[1,1,1]
	v_pk_fma_f32 v[226:227], v[46:47], v[202:203], v[226:227] op_sel:[0,1,0] op_sel_hi:[1,1,1]
	v_pk_fma_f32 v[228:229], v[44:45], v[210:211], v[228:229] op_sel:[0,1,0] op_sel_hi:[1,1,1]
	v_pk_fma_f32 v[230:231], v[46:47], v[210:211], v[230:231] op_sel:[0,1,0] op_sel_hi:[1,1,1]
	global_load_dwordx4 v[16:19], v4, s[6:7]
	s_add_u32 s6, s6, 0x48000
	s_addc_u32 s7, s7, 0
	global_load_dwordx4 v[20:23], v4, s[6:7]
	s_add_u32 s6, s6, 0x48000
	s_addc_u32 s7, s7, 0
	global_load_dwordx4 v[24:27], v4, s[6:7]
	s_add_u32 s6, s6, 0x48000
	s_addc_u32 s7, s7, 0
	global_load_dwordx4 v[28:31], v4, s[6:7]
	s_add_u32 s6, s6, 0x48000
	s_addc_u32 s7, s7, 0
	global_load_dwordx4 v[32:35], v4, s[6:7]
	s_add_u32 s6, s6, 0x48000
	s_addc_u32 s7, s7, 0
	global_load_dwordx4 v[36:39], v4, s[6:7]
	s_add_u32 s6, s6, 0x48000
	s_addc_u32 s7, s7, 0
	global_load_dwordx4 v[40:43], v4, s[6:7]
	s_add_u32 s6, s6, 0x48000
	s_addc_u32 s7, s7, 0
	global_load_dwordx4 v[44:47], v4, s[6:7]
	s_add_u32 s6, s6, 0x48000
	s_addc_u32 s7, s7, 0
	ds_read_b128 v[172:175], v5 offset:288
	ds_read_b128 v[176:179], v5 offset:304
	ds_read_b128 v[180:183], v5 offset:4512
	ds_read_b128 v[184:187], v5 offset:4528
	ds_read_b128 v[188:191], v5 offset:8736
	ds_read_b128 v[192:195], v5 offset:8752
	ds_read_b128 v[196:199], v5 offset:12960
	ds_read_b128 v[200:203], v5 offset:12976
	ds_read_b128 v[204:207], v5 offset:17184
	ds_read_b128 v[208:211], v5 offset:17200
	s_waitcnt vmcnt(24)
	s_waitcnt lgkmcnt(0)
	v_pk_fma_f32 v[212:213], v[48:49], v[172:173], v[212:213] op_sel_hi:[1,0,1]
	v_pk_fma_f32 v[214:215], v[50:51], v[172:173], v[214:215] op_sel_hi:[1,0,1]
	v_pk_fma_f32 v[216:217], v[48:49], v[180:181], v[216:217] op_sel_hi:[1,0,1]
	v_pk_fma_f32 v[218:219], v[50:51], v[180:181], v[218:219] op_sel_hi:[1,0,1]
	v_pk_fma_f32 v[220:221], v[48:49], v[188:189], v[220:221] op_sel_hi:[1,0,1]
	v_pk_fma_f32 v[222:223], v[50:51], v[188:189], v[222:223] op_sel_hi:[1,0,1]
	v_pk_fma_f32 v[224:225], v[48:49], v[196:197], v[224:225] op_sel_hi:[1,0,1]
	v_pk_fma_f32 v[226:227], v[50:51], v[196:197], v[226:227] op_sel_hi:[1,0,1]
	v_pk_fma_f32 v[228:229], v[48:49], v[204:205], v[228:229] op_sel_hi:[1,0,1]
	v_pk_fma_f32 v[230:231], v[50:51], v[204:205], v[230:231] op_sel_hi:[1,0,1]
	v_pk_fma_f32 v[212:213], v[52:53], v[172:173], v[212:213] op_sel:[0,1,0] op_sel_hi:[1,1,1]
	v_pk_fma_f32 v[214:215], v[54:55], v[172:173], v[214:215] op_sel:[0,1,0] op_sel_hi:[1,1,1]
	v_pk_fma_f32 v[216:217], v[52:53], v[180:181], v[216:217] op_sel:[0,1,0] op_sel_hi:[1,1,1]
	v_pk_fma_f32 v[218:219], v[54:55], v[180:181], v[218:219] op_sel:[0,1,0] op_sel_hi:[1,1,1]
	v_pk_fma_f32 v[220:221], v[52:53], v[188:189], v[220:221] op_sel:[0,1,0] op_sel_hi:[1,1,1]
	v_pk_fma_f32 v[222:223], v[54:55], v[188:189], v[222:223] op_sel:[0,1,0] op_sel_hi:[1,1,1]
	v_pk_fma_f32 v[224:225], v[52:53], v[196:197], v[224:225] op_sel:[0,1,0] op_sel_hi:[1,1,1]
	v_pk_fma_f32 v[226:227], v[54:55], v[196:197], v[226:227] op_sel:[0,1,0] op_sel_hi:[1,1,1]
	v_pk_fma_f32 v[228:229], v[52:53], v[204:205], v[228:229] op_sel:[0,1,0] op_sel_hi:[1,1,1]
	v_pk_fma_f32 v[230:231], v[54:55], v[204:205], v[230:231] op_sel:[0,1,0] op_sel_hi:[1,1,1]
	v_pk_fma_f32 v[212:213], v[56:57], v[174:175], v[212:213] op_sel_hi:[1,0,1]
	v_pk_fma_f32 v[214:215], v[58:59], v[174:175], v[214:215] op_sel_hi:[1,0,1]
	v_pk_fma_f32 v[216:217], v[56:57], v[182:183], v[216:217] op_sel_hi:[1,0,1]
	v_pk_fma_f32 v[218:219], v[58:59], v[182:183], v[218:219] op_sel_hi:[1,0,1]
	v_pk_fma_f32 v[220:221], v[56:57], v[190:191], v[220:221] op_sel_hi:[1,0,1]
	v_pk_fma_f32 v[222:223], v[58:59], v[190:191], v[222:223] op_sel_hi:[1,0,1]
	v_pk_fma_f32 v[224:225], v[56:57], v[198:199], v[224:225] op_sel_hi:[1,0,1]
	v_pk_fma_f32 v[226:227], v[58:59], v[198:199], v[226:227] op_sel_hi:[1,0,1]
	v_pk_fma_f32 v[228:229], v[56:57], v[206:207], v[228:229] op_sel_hi:[1,0,1]
	v_pk_fma_f32 v[230:231], v[58:59], v[206:207], v[230:231] op_sel_hi:[1,0,1]
	v_pk_fma_f32 v[212:213], v[60:61], v[174:175], v[212:213] op_sel:[0,1,0] op_sel_hi:[1,1,1]
	v_pk_fma_f32 v[214:215], v[62:63], v[174:175], v[214:215] op_sel:[0,1,0] op_sel_hi:[1,1,1]
	v_pk_fma_f32 v[216:217], v[60:61], v[182:183], v[216:217] op_sel:[0,1,0] op_sel_hi:[1,1,1]
	v_pk_fma_f32 v[218:219], v[62:63], v[182:183], v[218:219] op_sel:[0,1,0] op_sel_hi:[1,1,1]
	v_pk_fma_f32 v[220:221], v[60:61], v[190:191], v[220:221] op_sel:[0,1,0] op_sel_hi:[1,1,1]
	v_pk_fma_f32 v[222:223], v[62:63], v[190:191], v[222:223] op_sel:[0,1,0] op_sel_hi:[1,1,1]
	v_pk_fma_f32 v[224:225], v[60:61], v[198:199], v[224:225] op_sel:[0,1,0] op_sel_hi:[1,1,1]
	v_pk_fma_f32 v[226:227], v[62:63], v[198:199], v[226:227] op_sel:[0,1,0] op_sel_hi:[1,1,1]
	v_pk_fma_f32 v[228:229], v[60:61], v[206:207], v[228:229] op_sel:[0,1,0] op_sel_hi:[1,1,1]
; __device__ __forceinline__ void ada_item(const Params& P, int item, float* sm) {
;     ...
;     for (int kk = 0; kk < 64; ++kk) {
;         const f32x4 w4 = *(const f32x4*)(wp + (size_t)kk * 9216);
; #pragma unroll
;         for (int r = 0; r < 5; ++r) { const float s = sv[r * 1024 + kg * 64 + kk]; a[r] += w4 * s; }
	v_pk_fma_f32 v[230:231], v[62:63], v[206:207], v[230:231] op_sel:[0,1,0] op_sel_hi:[1,1,1]
	v_pk_fma_f32 v[212:213], v[64:65], v[176:177], v[212:213] op_sel_hi:[1,0,1]
	v_pk_fma_f32 v[214:215], v[66:67], v[176:177], v[214:215] op_sel_hi:[1,0,1]
	v_pk_fma_f32 v[216:217], v[64:65], v[184:185], v[216:217] op_sel_hi:[1,0,1]
	v_pk_fma_f32 v[218:219], v[66:67], v[184:185], v[218:219] op_sel_hi:[1,0,1]
	v_pk_fma_f32 v[220:221], v[64:65], v[192:193], v[220:221] op_sel_hi:[1,0,1]
	v_pk_fma_f32 v[222:223], v[66:67], v[192:193], v[222:223] op_sel_hi:[1,0,1]
	v_pk_fma_f32 v[224:225], v[64:65], v[200:201], v[224:225] op_sel_hi:[1,0,1]
	v_pk_fma_f32 v[226:227], v[66:67], v[200:201], v[226:227] op_sel_hi:[1,0,1]
	v_pk_fma_f32 v[228:229], v[64:65], v[208:209], v[228:229] op_sel_hi:[1,0,1]
	v_pk_fma_f32 v[230:231], v[66:67], v[208:209], v[230:231] op_sel_hi:[1,0,1]
	v_pk_fma_f32 v[212:213], v[68:69], v[176:177], v[212:213] op_sel:[0,1,0] op_sel_hi:[1,1,1]
	v_pk_fma_f32 v[214:215], v[70:71], v[176:177], v[214:215] op_sel:[0,1,0] op_sel_hi:[1,1,1]
	v_pk_fma_f32 v[216:217], v[68:69], v[184:185], v[216:217] op_sel:[0,1,0] op_sel_hi:[1,1,1]
	v_pk_fma_f32 v[218:219], v[70:71], v[184:185], v[218:219] op_sel:[0,1,0] op_sel_hi:[1,1,1]
	v_pk_fma_f32 v[220:221], v[68:69], v[192:193], v[220:221] op_sel:[0,1,0] op_sel_hi:[1,1,1]
	v_pk_fma_f32 v[222:223], v[70:71], v[192:193], v[222:223] op_sel:[0,1,0] op_sel_hi:[1,1,1]
	v_pk_fma_f32 v[224:225], v[68:69], v[200:201], v[224:225] op_sel:[0,1,0] op_sel_hi:[1,1,1]
	v_pk_fma_f32 v[226:227], v[70:71], v[200:201], v[226:227] op_sel:[0,1,0] op_sel_hi:[1,1,1]
	v_pk_fma_f32 v[228:229], v[68:69], v[208:209], v[228:229] op_sel:[0,1,0] op_sel_hi:[1,1,1]
	v_pk_fma_f32 v[230:231], v[70:71], v[208:209], v[230:231] op_sel:[0,1,0] op_sel_hi:[1,1,1]
	v_pk_fma_f32 v[212:213], v[72:73], v[178:179], v[212:213] op_sel_hi:[1,0,1]
	v_pk_fma_f32 v[214:215], v[74:75], v[178:179], v[214:215] op_sel_hi:[1,0,1]
	v_pk_fma_f32 v[216:217], v[72:73], v[186:187], v[216:217] op_sel_hi:[1,0,1]
	v_pk_fma_f32 v[218:219], v[74:75], v[186:187], v[218:219] op_sel_hi:[1,0,1]
	v_pk_fma_f32 v[220:221], v[72:73], v[194:195], v[220:221] op_sel_hi:[1,0,1]
	v_pk_fma_f32 v[222:223], v[74:75], v[194:195], v[222:223] op_sel_hi:[1,0,1]
	v_pk_fma_f32 v[224:225], v[72:73], v[202:203], v[224:225] op_sel_hi:[1,0,1]
	v_pk_fma_f32 v[226:227], v[74:75], v[202:203], v[226:227] op_sel_hi:[1,0,1]
	v_pk_fma_f32 v[228:229], v[72:73], v[210:211], v[228:229] op_sel_hi:[1,0,1]
	v_pk_fma_f32 v[230:231], v[74:75], v[210:211], v[230:231] op_sel_hi:[1,0,1]
	v_pk_fma_f32 v[212:213], v[76:77], v[178:179], v[212:213] op_sel:[0,1,0] op_sel_hi:[1,1,1]
	v_pk_fma_f32 v[214:215], v[78:79], v[178:179], v[214:215] op_sel:[0,1,0] op_sel_hi:[1,1,1]
	v_pk_fma_f32 v[216:217], v[76:77], v[186:187], v[216:217] op_sel:[0,1,0] op_sel_hi:[1,1,1]
	v_pk_fma_f32 v[218:219], v[78:79], v[186:187], v[218:219] op_sel:[0,1,0] op_sel_hi:[1,1,1]
	v_pk_fma_f32 v[220:221], v[76:77], v[194:195], v[220:221] op_sel:[0,1,0] op_sel_hi:[1,1,1]
	v_pk_fma_f32 v[222:223], v[78:79], v[194:195], v[222:223] op_sel:[0,1,0] op_sel_hi:[1,1,1]
	v_pk_fma_f32 v[224:225], v[76:77], v[202:203], v[224:225] op_sel:[0,1,0] op_sel_hi:[1,1,1]
	v_pk_fma_f32 v[226:227], v[78:79], v[202:203], v[226:227] op_sel:[0,1,0] op_sel_hi:[1,1,1]
	v_pk_fma_f32 v[228:229], v[76:77], v[210:211], v[228:229] op_sel:[0,1,0] op_sel_hi:[1,1,1]
	v_pk_fma_f32 v[230:231], v[78:79], v[210:211], v[230:231] op_sel:[0,1,0] op_sel_hi:[1,1,1]
	global_load_dwordx4 v[48:51], v4, s[6:7]
	s_add_u32 s6, s6, 0x48000
	s_addc_u32 s7, s7, 0
	global_load_dwordx4 v[52:55], v4, s[6:7]
	s_add_u32 s6, s6, 0x48000
	s_addc_u32 s7, s7, 0
	global_load_dwordx4 v[56:59], v4, s[6:7]
	s_add_u32 s6, s6, 0x48000
	s_addc_u32 s7, s7, 0
	global_load_dwordx4 v[60:63], v4, s[6:7]
	s_add_u32 s6, s6, 0x48000
	s_addc_u32 s7, s7, 0
	global_load_dwordx4 v[64:67], v4, s[6:7]
	s_add_u32 s6, s6, 0x48000
	s_addc_u32 s7, s7, 0
	global_load_dwordx4 v[68:71], v4, s[6:7]
	s_add_u32 s6, s6, 0x48000
	s_addc_u32 s7, s7, 0
	global_load_dwordx4 v[72:75], v4, s[6:7]
	s_add_u32 s6, s6, 0x48000
	s_addc_u32 s7, s7, 0
	global_load_dwordx4 v[76:79], v4, s[6:7]
	s_add_u32 s6, s6, 0x48000
	s_addc_u32 s7, s7, 0
	ds_read_b128 v[172:175], v5 offset:320
	ds_read_b128 v[176:179], v5 offset:336
	ds_read_b128 v[180:183], v5 offset:4544
	ds_read_b128 v[184:187], v5 offset:4560
	ds_read_b128 v[188:191], v5 offset:8768
	ds_read_b128 v[192:195], v5 offset:8784
	ds_read_b128 v[196:199], v5 offset:12992
	ds_read_b128 v[200:203], v5 offset:13008
	ds_read_b128 v[204:207], v5 offset:17216
	ds_read_b128 v[208:211], v5 offset:17232
	s_waitcnt vmcnt(24)
	s_waitcnt lgkmcnt(0)
; __device__ __forceinline__ void ada_item(const Params& P, int item, float* sm) {
;     ...
;     for (int kk = 0; kk < 64; ++kk) {
;         const f32x4 w4 = *(const f32x4*)(wp + (size_t)kk * 9216);
; #pragma unroll
;         for (int r = 0; r < 5; ++r) { const float s = sv[r * 1024 + kg * 64 + kk]; a[r] += w4 * s; }
	v_pk_fma_f32 v[212:213], v[80:81], v[172:173], v[212:213] op_sel_hi:[1,0,1]
	v_pk_fma_f32 v[214:215], v[82:83], v[172:173], v[214:215] op_sel_hi:[1,0,1]
	v_pk_fma_f32 v[216:217], v[80:81], v[180:181], v[216:217] op_sel_hi:[1,0,1]
	v_pk_fma_f32 v[218:219], v[82:83], v[180:181], v[218:219] op_sel_hi:[1,0,1]
	v_pk_fma_f32 v[220:221], v[80:81], v[188:189], v[220:221] op_sel_hi:[1,0,1]
	v_pk_fma_f32 v[222:223], v[82:83], v[188:189], v[222:223] op_sel_hi:[1,0,1]
	v_pk_fma_f32 v[224:225], v[80:81], v[196:197], v[224:225] op_sel_hi:[1,0,1]
	v_pk_fma_f32 v[226:227], v[82:83], v[196:197], v[226:227] op_sel_hi:[1,0,1]
	v_pk_fma_f32 v[228:229], v[80:81], v[204:205], v[228:229] op_sel_hi:[1,0,1]
	v_pk_fma_f32 v[230:231], v[82:83], v[204:205], v[230:231] op_sel_hi:[1,0,1]
	v_pk_fma_f32 v[212:213], v[84:85], v[172:173], v[212:213] op_sel:[0,1,0] op_sel_hi:[1,1,1]
	v_pk_fma_f32 v[214:215], v[86:87], v[172:173], v[214:215] op_sel:[0,1,0] op_sel_hi:[1,1,1]
	v_pk_fma_f32 v[216:217], v[84:85], v[180:181], v[216:217] op_sel:[0,1,0] op_sel_hi:[1,1,1]
	v_pk_fma_f32 v[218:219], v[86:87], v[180:181], v[218:219] op_sel:[0,1,0] op_sel_hi:[1,1,1]
	v_pk_fma_f32 v[220:221], v[84:85], v[188:189], v[220:221] op_sel:[0,1,0] op_sel_hi:[1,1,1]
	v_pk_fma_f32 v[222:223], v[86:87], v[188:189], v[222:223] op_sel:[0,1,0] op_sel_hi:[1,1,1]
	v_pk_fma_f32 v[224:225], v[84:85], v[196:197], v[224:225] op_sel:[0,1,0] op_sel_hi:[1,1,1]
	v_pk_fma_f32 v[226:227], v[86:87], v[196:197], v[226:227] op_sel:[0,1,0] op_sel_hi:[1,1,1]
	v_pk_fma_f32 v[228:229], v[84:85], v[204:205], v[228:229] op_sel:[0,1,0] op_sel_hi:[1,1,1]
	v_pk_fma_f32 v[230:231], v[86:87], v[204:205], v[230:231] op_sel:[0,1,0] op_sel_hi:[1,1,1]
	v_pk_fma_f32 v[212:213], v[88:89], v[174:175], v[212:213] op_sel_hi:[1,0,1]
	v_pk_fma_f32 v[214:215], v[90:91], v[174:175], v[214:215] op_sel_hi:[1,0,1]
	v_pk_fma_f32 v[216:217], v[88:89], v[182:183], v[216:217] op_sel_hi:[1,0,1]
	v_pk_fma_f32 v[218:219], v[90:91], v[182:183], v[218:219] op_sel_hi:[1,0,1]
	v_pk_fma_f32 v[220:221], v[88:89], v[190:191], v[220:221] op_sel_hi:[1,0,1]
	v_pk_fma_f32 v[222:223], v[90:91], v[190:191], v[222:223] op_sel_hi:[1,0,1]
	v_pk_fma_f32 v[224:225], v[88:89], v[198:199], v[224:225] op_sel_hi:[1,0,1]
	v_pk_fma_f32 v[226:227], v[90:91], v[198:199], v[226:227] op_sel_hi:[1,0,1]
	v_pk_fma_f32 v[228:229], v[88:89], v[206:207], v[228:229] op_sel_hi:[1,0,1]
	v_pk_fma_f32 v[230:231], v[90:91], v[206:207], v[230:231] op_sel_hi:[1,0,1]
	v_pk_fma_f32 v[212:213], v[92:93], v[174:175], v[212:213] op_sel:[0,1,0] op_sel_hi:[1,1,1]
	v_pk_fma_f32 v[214:215], v[94:95], v[174:175], v[214:215] op_sel:[0,1,0] op_sel_hi:[1,1,1]
	v_pk_fma_f32 v[216:217], v[92:93], v[182:183], v[216:217] op_sel:[0,1,0] op_sel_hi:[1,1,1]
	v_pk_fma_f32 v[218:219], v[94:95], v[182:183], v[218:219] op_sel:[0,1,0] op_sel_hi:[1,1,1]
	v_pk_fma_f32 v[220:221], v[92:93], v[190:191], v[220:221] op_sel:[0,1,0] op_sel_hi:[1,1,1]
	v_pk_fma_f32 v[222:223], v[94:95], v[190:191], v[222:223] op_sel:[0,1,0] op_sel_hi:[1,1,1]
	v_pk_fma_f32 v[224:225], v[92:93], v[198:199], v[224:225] op_sel:[0,1,0] op_sel_hi:[1,1,1]
	v_pk_fma_f32 v[226:227], v[94:95], v[198:199], v[226:227] op_sel:[0,1,0] op_sel_hi:[1,1,1]
	v_pk_fma_f32 v[228:229], v[92:93], v[206:207], v[228:229] op_sel:[0,1,0] op_sel_hi:[1,1,1]
	v_pk_fma_f32 v[230:231], v[94:95], v[206:207], v[230:231] op_sel:[0,1,0] op_sel_hi:[1,1,1]
	v_pk_fma_f32 v[212:213], v[96:97], v[176:177], v[212:213] op_sel_hi:[1,0,1]
	v_pk_fma_f32 v[214:215], v[98:99], v[176:177], v[214:215] op_sel_hi:[1,0,1]
	v_pk_fma_f32 v[216:217], v[96:97], v[184:185], v[216:217] op_sel_hi:[1,0,1]
	v_pk_fma_f32 v[218:219], v[98:99], v[184:185], v[218:219] op_sel_hi:[1,0,1]
	v_pk_fma_f32 v[220:221], v[96:97], v[192:193], v[220:221] op_sel_hi:[1,0,1]
	v_pk_fma_f32 v[222:223], v[98:99], v[192:193], v[222:223] op_sel_hi:[1,0,1]
	v_pk_fma_f32 v[224:225], v[96:97], v[200:201], v[224:225] op_sel_hi:[1,0,1]
	v_pk_fma_f32 v[226:227], v[98:99], v[200:201], v[226:227] op_sel_hi:[1,0,1]
	v_pk_fma_f32 v[228:229], v[96:97], v[208:209], v[228:229] op_sel_hi:[1,0,1]
	v_pk_fma_f32 v[230:231], v[98:99], v[208:209], v[230:231] op_sel_hi:[1,0,1]
	v_pk_fma_f32 v[212:213], v[100:101], v[176:177], v[212:213] op_sel:[0,1,0] op_sel_hi:[1,1,1]
	v_pk_fma_f32 v[214:215], v[102:103], v[176:177], v[214:215] op_sel:[0,1,0] op_sel_hi:[1,1,1]
	v_pk_fma_f32 v[216:217], v[100:101], v[184:185], v[216:217] op_sel:[0,1,0] op_sel_hi:[1,1,1]
	v_pk_fma_f32 v[218:219], v[102:103], v[184:185], v[218:219] op_sel:[0,1,0] op_sel_hi:[1,1,1]
	v_pk_fma_f32 v[220:221], v[100:101], v[192:193], v[220:221] op_sel:[0,1,0] op_sel_hi:[1,1,1]
	v_pk_fma_f32 v[222:223], v[102:103], v[192:193], v[222:223] op_sel:[0,1,0] op_sel_hi:[1,1,1]
	v_pk_fma_f32 v[224:225], v[100:101], v[200:201], v[224:225] op_sel:[0,1,0] op_sel_hi:[1,1,1]
	v_pk_fma_f32 v[226:227], v[102:103], v[200:201], v[226:227] op_sel:[0,1,0] op_sel_hi:[1,1,1]
	v_pk_fma_f32 v[228:229], v[100:101], v[208:209], v[228:229] op_sel:[0,1,0] op_sel_hi:[1,1,1]
	v_pk_fma_f32 v[230:231], v[102:103], v[208:209], v[230:231] op_sel:[0,1,0] op_sel_hi:[1,1,1]
	v_pk_fma_f32 v[212:213], v[104:105], v[178:179], v[212:213] op_sel_hi:[1,0,1]
	v_pk_fma_f32 v[214:215], v[106:107], v[178:179], v[214:215] op_sel_hi:[1,0,1]
	v_pk_fma_f32 v[216:217], v[104:105], v[186:187], v[216:217] op_sel_hi:[1,0,1]
	v_pk_fma_f32 v[218:219], v[106:107], v[186:187], v[218:219] op_sel_hi:[1,0,1]
	v_pk_fma_f32 v[220:221], v[104:105], v[194:195], v[220:221] op_sel_hi:[1,0,1]
	v_pk_fma_f32 v[222:223], v[106:107], v[194:195], v[222:223] op_sel_hi:[1,0,1]
	v_pk_fma_f32 v[224:225], v[104:105], v[202:203], v[224:225] op_sel_hi:[1,0,1]
; __device__ __forceinline__ void ada_item(const Params& P, int item, float* sm) {
;     ...
;     for (int kk = 0; kk < 64; ++kk) {
;         const f32x4 w4 = *(const f32x4*)(wp + (size_t)kk * 9216);
; #pragma unroll
;         for (int r = 0; r < 5; ++r) { const float s = sv[r * 1024 + kg * 64 + kk]; a[r] += w4 * s; }
	v_pk_fma_f32 v[226:227], v[106:107], v[202:203], v[226:227] op_sel_hi:[1,0,1]
	v_pk_fma_f32 v[228:229], v[104:105], v[210:211], v[228:229] op_sel_hi:[1,0,1]
	v_pk_fma_f32 v[230:231], v[106:107], v[210:211], v[230:231] op_sel_hi:[1,0,1]
	v_pk_fma_f32 v[212:213], v[108:109], v[178:179], v[212:213] op_sel:[0,1,0] op_sel_hi:[1,1,1]
	v_pk_fma_f32 v[214:215], v[110:111], v[178:179], v[214:215] op_sel:[0,1,0] op_sel_hi:[1,1,1]
	v_pk_fma_f32 v[216:217], v[108:109], v[186:187], v[216:217] op_sel:[0,1,0] op_sel_hi:[1,1,1]
	v_pk_fma_f32 v[218:219], v[110:111], v[186:187], v[218:219] op_sel:[0,1,0] op_sel_hi:[1,1,1]
	v_pk_fma_f32 v[220:221], v[108:109], v[194:195], v[220:221] op_sel:[0,1,0] op_sel_hi:[1,1,1]
	v_pk_fma_f32 v[222:223], v[110:111], v[194:195], v[222:223] op_sel:[0,1,0] op_sel_hi:[1,1,1]
	v_pk_fma_f32 v[224:225], v[108:109], v[202:203], v[224:225] op_sel:[0,1,0] op_sel_hi:[1,1,1]
	v_pk_fma_f32 v[226:227], v[110:111], v[202:203], v[226:227] op_sel:[0,1,0] op_sel_hi:[1,1,1]
	v_pk_fma_f32 v[228:229], v[108:109], v[210:211], v[228:229] op_sel:[0,1,0] op_sel_hi:[1,1,1]
	v_pk_fma_f32 v[230:231], v[110:111], v[210:211], v[230:231] op_sel:[0,1,0] op_sel_hi:[1,1,1]
	global_load_dwordx4 v[80:83], v4, s[6:7]
	s_add_u32 s6, s6, 0x48000
	s_addc_u32 s7, s7, 0
	global_load_dwordx4 v[84:87], v4, s[6:7]
	s_add_u32 s6, s6, 0x48000
	s_addc_u32 s7, s7, 0
	global_load_dwordx4 v[88:91], v4, s[6:7]
	s_add_u32 s6, s6, 0x48000
	s_addc_u32 s7, s7, 0
	global_load_dwordx4 v[92:95], v4, s[6:7]
	s_add_u32 s6, s6, 0x48000
	s_addc_u32 s7, s7, 0
	global_load_dwordx4 v[96:99], v4, s[6:7]
	s_add_u32 s6, s6, 0x48000
	s_addc_u32 s7, s7, 0
	global_load_dwordx4 v[100:103], v4, s[6:7]
	s_add_u32 s6, s6, 0x48000
	s_addc_u32 s7, s7, 0
	global_load_dwordx4 v[104:107], v4, s[6:7]
	s_add_u32 s6, s6, 0x48000
	s_addc_u32 s7, s7, 0
	global_load_dwordx4 v[108:111], v4, s[6:7]
	s_add_u32 s6, s6, 0x48000
	s_addc_u32 s7, s7, 0
	ds_read_b128 v[172:175], v5 offset:352
	ds_read_b128 v[176:179], v5 offset:368
	ds_read_b128 v[180:183], v5 offset:4576
	ds_read_b128 v[184:187], v5 offset:4592
	ds_read_b128 v[188:191], v5 offset:8800
	ds_read_b128 v[192:195], v5 offset:8816
	ds_read_b128 v[196:199], v5 offset:13024
	ds_read_b128 v[200:203], v5 offset:13040
	ds_read_b128 v[204:207], v5 offset:17248
	ds_read_b128 v[208:211], v5 offset:17264
	s_waitcnt vmcnt(24)
	s_waitcnt lgkmcnt(0)
	v_pk_fma_f32 v[212:213], v[112:113], v[172:173], v[212:213] op_sel_hi:[1,0,1]
	v_pk_fma_f32 v[214:215], v[114:115], v[172:173], v[214:215] op_sel_hi:[1,0,1]
	v_pk_fma_f32 v[216:217], v[112:113], v[180:181], v[216:217] op_sel_hi:[1,0,1]
	v_pk_fma_f32 v[218:219], v[114:115], v[180:181], v[218:219] op_sel_hi:[1,0,1]
	v_pk_fma_f32 v[220:221], v[112:113], v[188:189], v[220:221] op_sel_hi:[1,0,1]
	v_pk_fma_f32 v[222:223], v[114:115], v[188:189], v[222:223] op_sel_hi:[1,0,1]
	v_pk_fma_f32 v[224:225], v[112:113], v[196:197], v[224:225] op_sel_hi:[1,0,1]
	v_pk_fma_f32 v[226:227], v[114:115], v[196:197], v[226:227] op_sel_hi:[1,0,1]
	v_pk_fma_f32 v[228:229], v[112:113], v[204:205], v[228:229] op_sel_hi:[1,0,1]
	v_pk_fma_f32 v[230:231], v[114:115], v[204:205], v[230:231] op_sel_hi:[1,0,1]
	v_pk_fma_f32 v[212:213], v[116:117], v[172:173], v[212:213] op_sel:[0,1,0] op_sel_hi:[1,1,1]
	v_pk_fma_f32 v[214:215], v[118:119], v[172:173], v[214:215] op_sel:[0,1,0] op_sel_hi:[1,1,1]
	v_pk_fma_f32 v[216:217], v[116:117], v[180:181], v[216:217] op_sel:[0,1,0] op_sel_hi:[1,1,1]
	v_pk_fma_f32 v[218:219], v[118:119], v[180:181], v[218:219] op_sel:[0,1,0] op_sel_hi:[1,1,1]
	v_pk_fma_f32 v[220:221], v[116:117], v[188:189], v[220:221] op_sel:[0,1,0] op_sel_hi:[1,1,1]
	v_pk_fma_f32 v[222:223], v[118:119], v[188:189], v[222:223] op_sel:[0,1,0] op_sel_hi:[1,1,1]
	v_pk_fma_f32 v[224:225], v[116:117], v[196:197], v[224:225] op_sel:[0,1,0] op_sel_hi:[1,1,1]
	v_pk_fma_f32 v[226:227], v[118:119], v[196:197], v[226:227] op_sel:[0,1,0] op_sel_hi:[1,1,1]
	v_pk_fma_f32 v[228:229], v[116:117], v[204:205], v[228:229] op_sel:[0,1,0] op_sel_hi:[1,1,1]
	v_pk_fma_f32 v[230:231], v[118:119], v[204:205], v[230:231] op_sel:[0,1,0] op_sel_hi:[1,1,1]
	v_pk_fma_f32 v[212:213], v[120:121], v[174:175], v[212:213] op_sel_hi:[1,0,1]
	v_pk_fma_f32 v[214:215], v[122:123], v[174:175], v[214:215] op_sel_hi:[1,0,1]
	v_pk_fma_f32 v[216:217], v[120:121], v[182:183], v[216:217] op_sel_hi:[1,0,1]
	v_pk_fma_f32 v[218:219], v[122:123], v[182:183], v[218:219] op_sel_hi:[1,0,1]
	v_pk_fma_f32 v[220:221], v[120:121], v[190:191], v[220:221] op_sel_hi:[1,0,1]
	v_pk_fma_f32 v[222:223], v[122:123], v[190:191], v[222:223] op_sel_hi:[1,0,1]
	v_pk_fma_f32 v[224:225], v[120:121], v[198:199], v[224:225] op_sel_hi:[1,0,1]
	v_pk_fma_f32 v[226:227], v[122:123], v[198:199], v[226:227] op_sel_hi:[1,0,1]
	v_pk_fma_f32 v[228:229], v[120:121], v[206:207], v[228:229] op_sel_hi:[1,0,1]
	v_pk_fma_f32 v[230:231], v[122:123], v[206:207], v[230:231] op_sel_hi:[1,0,1]
	v_pk_fma_f32 v[212:213], v[124:125], v[174:175], v[212:213] op_sel:[0,1,0] op_sel_hi:[1,1,1]
	v_pk_fma_f32 v[214:215], v[126:127], v[174:175], v[214:215] op_sel:[0,1,0] op_sel_hi:[1,1,1]
	v_pk_fma_f32 v[216:217], v[124:125], v[182:183], v[216:217] op_sel:[0,1,0] op_sel_hi:[1,1,1]
	v_pk_fma_f32 v[218:219], v[126:127], v[182:183], v[218:219] op_sel:[0,1,0] op_sel_hi:[1,1,1]
	v_pk_fma_f32 v[220:221], v[124:125], v[190:191], v[220:221] op_sel:[0,1,0] op_sel_hi:[1,1,1]
	v_pk_fma_f32 v[222:223], v[126:127], v[190:191], v[222:223] op_sel:[0,1,0] op_sel_hi:[1,1,1]
	v_pk_fma_f32 v[224:225], v[124:125], v[198:199], v[224:225] op_sel:[0,1,0] op_sel_hi:[1,1,1]
	v_pk_fma_f32 v[226:227], v[126:127], v[198:199], v[226:227] op_sel:[0,1,0] op_sel_hi:[1,1,1]
; __device__ __forceinline__ void ada_item(const Params& P, int item, float* sm) {
;     ...
;     for (int kk = 0; kk < 64; ++kk) {
;         const f32x4 w4 = *(const f32x4*)(wp + (size_t)kk * 9216);
; #pragma unroll
;         for (int r = 0; r < 5; ++r) { const float s = sv[r * 1024 + kg * 64 + kk]; a[r] += w4 * s; }
	v_pk_fma_f32 v[228:229], v[124:125], v[206:207], v[228:229] op_sel:[0,1,0] op_sel_hi:[1,1,1]
	v_pk_fma_f32 v[230:231], v[126:127], v[206:207], v[230:231] op_sel:[0,1,0] op_sel_hi:[1,1,1]
	v_pk_fma_f32 v[212:213], v[128:129], v[176:177], v[212:213] op_sel_hi:[1,0,1]
	v_pk_fma_f32 v[214:215], v[130:131], v[176:177], v[214:215] op_sel_hi:[1,0,1]
	v_pk_fma_f32 v[216:217], v[128:129], v[184:185], v[216:217] op_sel_hi:[1,0,1]
	v_pk_fma_f32 v[218:219], v[130:131], v[184:185], v[218:219] op_sel_hi:[1,0,1]
	v_pk_fma_f32 v[220:221], v[128:129], v[192:193], v[220:221] op_sel_hi:[1,0,1]
	v_pk_fma_f32 v[222:223], v[130:131], v[192:193], v[222:223] op_sel_hi:[1,0,1]
	v_pk_fma_f32 v[224:225], v[128:129], v[200:201], v[224:225] op_sel_hi:[1,0,1]
	v_pk_fma_f32 v[226:227], v[130:131], v[200:201], v[226:227] op_sel_hi:[1,0,1]
	v_pk_fma_f32 v[228:229], v[128:129], v[208:209], v[228:229] op_sel_hi:[1,0,1]
	v_pk_fma_f32 v[230:231], v[130:131], v[208:209], v[230:231] op_sel_hi:[1,0,1]
	v_pk_fma_f32 v[212:213], v[132:133], v[176:177], v[212:213] op_sel:[0,1,0] op_sel_hi:[1,1,1]
	v_pk_fma_f32 v[214:215], v[134:135], v[176:177], v[214:215] op_sel:[0,1,0] op_sel_hi:[1,1,1]
	v_pk_fma_f32 v[216:217], v[132:133], v[184:185], v[216:217] op_sel:[0,1,0] op_sel_hi:[1,1,1]
	v_pk_fma_f32 v[218:219], v[134:135], v[184:185], v[218:219] op_sel:[0,1,0] op_sel_hi:[1,1,1]
	v_pk_fma_f32 v[220:221], v[132:133], v[192:193], v[220:221] op_sel:[0,1,0] op_sel_hi:[1,1,1]
	v_pk_fma_f32 v[222:223], v[134:135], v[192:193], v[222:223] op_sel:[0,1,0] op_sel_hi:[1,1,1]
	v_pk_fma_f32 v[224:225], v[132:133], v[200:201], v[224:225] op_sel:[0,1,0] op_sel_hi:[1,1,1]
	v_pk_fma_f32 v[226:227], v[134:135], v[200:201], v[226:227] op_sel:[0,1,0] op_sel_hi:[1,1,1]
	v_pk_fma_f32 v[228:229], v[132:133], v[208:209], v[228:229] op_sel:[0,1,0] op_sel_hi:[1,1,1]
	v_pk_fma_f32 v[230:231], v[134:135], v[208:209], v[230:231] op_sel:[0,1,0] op_sel_hi:[1,1,1]
	v_pk_fma_f32 v[212:213], v[136:137], v[178:179], v[212:213] op_sel_hi:[1,0,1]
	v_pk_fma_f32 v[214:215], v[138:139], v[178:179], v[214:215] op_sel_hi:[1,0,1]
	v_pk_fma_f32 v[216:217], v[136:137], v[186:187], v[216:217] op_sel_hi:[1,0,1]
	v_pk_fma_f32 v[218:219], v[138:139], v[186:187], v[218:219] op_sel_hi:[1,0,1]
	v_pk_fma_f32 v[220:221], v[136:137], v[194:195], v[220:221] op_sel_hi:[1,0,1]
	v_pk_fma_f32 v[222:223], v[138:139], v[194:195], v[222:223] op_sel_hi:[1,0,1]
	v_pk_fma_f32 v[224:225], v[136:137], v[202:203], v[224:225] op_sel_hi:[1,0,1]
	v_pk_fma_f32 v[226:227], v[138:139], v[202:203], v[226:227] op_sel_hi:[1,0,1]
	v_pk_fma_f32 v[228:229], v[136:137], v[210:211], v[228:229] op_sel_hi:[1,0,1]
	v_pk_fma_f32 v[230:231], v[138:139], v[210:211], v[230:231] op_sel_hi:[1,0,1]
	v_pk_fma_f32 v[212:213], v[140:141], v[178:179], v[212:213] op_sel:[0,1,0] op_sel_hi:[1,1,1]
	v_pk_fma_f32 v[214:215], v[142:143], v[178:179], v[214:215] op_sel:[0,1,0] op_sel_hi:[1,1,1]
	v_pk_fma_f32 v[216:217], v[140:141], v[186:187], v[216:217] op_sel:[0,1,0] op_sel_hi:[1,1,1]
	v_pk_fma_f32 v[218:219], v[142:143], v[186:187], v[218:219] op_sel:[0,1,0] op_sel_hi:[1,1,1]
	v_pk_fma_f32 v[220:221], v[140:141], v[194:195], v[220:221] op_sel:[0,1,0] op_sel_hi:[1,1,1]
	v_pk_fma_f32 v[222:223], v[142:143], v[194:195], v[222:223] op_sel:[0,1,0] op_sel_hi:[1,1,1]
	v_pk_fma_f32 v[224:225], v[140:141], v[202:203], v[224:225] op_sel:[0,1,0] op_sel_hi:[1,1,1]
	v_pk_fma_f32 v[226:227], v[142:143], v[202:203], v[226:227] op_sel:[0,1,0] op_sel_hi:[1,1,1]
	v_pk_fma_f32 v[228:229], v[140:141], v[210:211], v[228:229] op_sel:[0,1,0] op_sel_hi:[1,1,1]
	v_pk_fma_f32 v[230:231], v[142:143], v[210:211], v[230:231] op_sel:[0,1,0] op_sel_hi:[1,1,1]
	global_load_dwordx4 v[112:115], v4, s[6:7]
	s_add_u32 s6, s6, 0x48000
	s_addc_u32 s7, s7, 0
	global_load_dwordx4 v[116:119], v4, s[6:7]
	s_add_u32 s6, s6, 0x48000
	s_addc_u32 s7, s7, 0
	global_load_dwordx4 v[120:123], v4, s[6:7]
	s_add_u32 s6, s6, 0x48000
	s_addc_u32 s7, s7, 0
	global_load_dwordx4 v[124:127], v4, s[6:7]
	s_add_u32 s6, s6, 0x48000
	s_addc_u32 s7, s7, 0
	global_load_dwordx4 v[128:131], v4, s[6:7]
	s_add_u32 s6, s6, 0x48000
	s_addc_u32 s7, s7, 0
	global_load_dwordx4 v[132:135], v4, s[6:7]
	s_add_u32 s6, s6, 0x48000
	s_addc_u32 s7, s7, 0
	global_load_dwordx4 v[136:139], v4, s[6:7]
	s_add_u32 s6, s6, 0x48000
	s_addc_u32 s7, s7, 0
	global_load_dwordx4 v[140:143], v4, s[6:7]
	s_add_u32 s6, s6, 0x48000
	s_addc_u32 s7, s7, 0
	ds_read_b128 v[172:175], v5 offset:384
	ds_read_b128 v[176:179], v5 offset:400
	ds_read_b128 v[180:183], v5 offset:4608
	ds_read_b128 v[184:187], v5 offset:4624
	ds_read_b128 v[188:191], v5 offset:8832
	ds_read_b128 v[192:195], v5 offset:8848
	ds_read_b128 v[196:199], v5 offset:13056
	ds_read_b128 v[200:203], v5 offset:13072
	ds_read_b128 v[204:207], v5 offset:17280
	ds_read_b128 v[208:211], v5 offset:17296
	s_waitcnt vmcnt(24)
	s_waitcnt lgkmcnt(0)
; __device__ __forceinline__ void ada_item(const Params& P, int item, float* sm) {
;     ...
;     for (int kk = 0; kk < 64; ++kk) {
;         const f32x4 w4 = *(const f32x4*)(wp + (size_t)kk * 9216);
; #pragma unroll
;         for (int r = 0; r < 5; ++r) { const float s = sv[r * 1024 + kg * 64 + kk]; a[r] += w4 * s; }
	v_pk_fma_f32 v[212:213], v[16:17], v[172:173], v[212:213] op_sel_hi:[1,0,1]
	v_pk_fma_f32 v[214:215], v[18:19], v[172:173], v[214:215] op_sel_hi:[1,0,1]
	v_pk_fma_f32 v[216:217], v[16:17], v[180:181], v[216:217] op_sel_hi:[1,0,1]
	v_pk_fma_f32 v[218:219], v[18:19], v[180:181], v[218:219] op_sel_hi:[1,0,1]
	v_pk_fma_f32 v[220:221], v[16:17], v[188:189], v[220:221] op_sel_hi:[1,0,1]
	v_pk_fma_f32 v[222:223], v[18:19], v[188:189], v[222:223] op_sel_hi:[1,0,1]
	v_pk_fma_f32 v[224:225], v[16:17], v[196:197], v[224:225] op_sel_hi:[1,0,1]
	v_pk_fma_f32 v[226:227], v[18:19], v[196:197], v[226:227] op_sel_hi:[1,0,1]
	v_pk_fma_f32 v[228:229], v[16:17], v[204:205], v[228:229] op_sel_hi:[1,0,1]
	v_pk_fma_f32 v[230:231], v[18:19], v[204:205], v[230:231] op_sel_hi:[1,0,1]
	v_pk_fma_f32 v[212:213], v[20:21], v[172:173], v[212:213] op_sel:[0,1,0] op_sel_hi:[1,1,1]
	v_pk_fma_f32 v[214:215], v[22:23], v[172:173], v[214:215] op_sel:[0,1,0] op_sel_hi:[1,1,1]
	v_pk_fma_f32 v[216:217], v[20:21], v[180:181], v[216:217] op_sel:[0,1,0] op_sel_hi:[1,1,1]
	v_pk_fma_f32 v[218:219], v[22:23], v[180:181], v[218:219] op_sel:[0,1,0] op_sel_hi:[1,1,1]
	v_pk_fma_f32 v[220:221], v[20:21], v[188:189], v[220:221] op_sel:[0,1,0] op_sel_hi:[1,1,1]
	v_pk_fma_f32 v[222:223], v[22:23], v[188:189], v[222:223] op_sel:[0,1,0] op_sel_hi:[1,1,1]
	v_pk_fma_f32 v[224:225], v[20:21], v[196:197], v[224:225] op_sel:[0,1,0] op_sel_hi:[1,1,1]
	v_pk_fma_f32 v[226:227], v[22:23], v[196:197], v[226:227] op_sel:[0,1,0] op_sel_hi:[1,1,1]
	v_pk_fma_f32 v[228:229], v[20:21], v[204:205], v[228:229] op_sel:[0,1,0] op_sel_hi:[1,1,1]
	v_pk_fma_f32 v[230:231], v[22:23], v[204:205], v[230:231] op_sel:[0,1,0] op_sel_hi:[1,1,1]
	v_pk_fma_f32 v[212:213], v[24:25], v[174:175], v[212:213] op_sel_hi:[1,0,1]
	v_pk_fma_f32 v[214:215], v[26:27], v[174:175], v[214:215] op_sel_hi:[1,0,1]
	v_pk_fma_f32 v[216:217], v[24:25], v[182:183], v[216:217] op_sel_hi:[1,0,1]
	v_pk_fma_f32 v[218:219], v[26:27], v[182:183], v[218:219] op_sel_hi:[1,0,1]
	v_pk_fma_f32 v[220:221], v[24:25], v[190:191], v[220:221] op_sel_hi:[1,0,1]
	v_pk_fma_f32 v[222:223], v[26:27], v[190:191], v[222:223] op_sel_hi:[1,0,1]
	v_pk_fma_f32 v[224:225], v[24:25], v[198:199], v[224:225] op_sel_hi:[1,0,1]
	v_pk_fma_f32 v[226:227], v[26:27], v[198:199], v[226:227] op_sel_hi:[1,0,1]
	v_pk_fma_f32 v[228:229], v[24:25], v[206:207], v[228:229] op_sel_hi:[1,0,1]
	v_pk_fma_f32 v[230:231], v[26:27], v[206:207], v[230:231] op_sel_hi:[1,0,1]
	v_pk_fma_f32 v[212:213], v[28:29], v[174:175], v[212:213] op_sel:[0,1,0] op_sel_hi:[1,1,1]
	v_pk_fma_f32 v[214:215], v[30:31], v[174:175], v[214:215] op_sel:[0,1,0] op_sel_hi:[1,1,1]
	v_pk_fma_f32 v[216:217], v[28:29], v[182:183], v[216:217] op_sel:[0,1,0] op_sel_hi:[1,1,1]
	v_pk_fma_f32 v[218:219], v[30:31], v[182:183], v[218:219] op_sel:[0,1,0] op_sel_hi:[1,1,1]
	v_pk_fma_f32 v[220:221], v[28:29], v[190:191], v[220:221] op_sel:[0,1,0] op_sel_hi:[1,1,1]
	v_pk_fma_f32 v[222:223], v[30:31], v[190:191], v[222:223] op_sel:[0,1,0] op_sel_hi:[1,1,1]
	v_pk_fma_f32 v[224:225], v[28:29], v[198:199], v[224:225] op_sel:[0,1,0] op_sel_hi:[1,1,1]
	v_pk_fma_f32 v[226:227], v[30:31], v[198:199], v[226:227] op_sel:[0,1,0] op_sel_hi:[1,1,1]
	v_pk_fma_f32 v[228:229], v[28:29], v[206:207], v[228:229] op_sel:[0,1,0] op_sel_hi:[1,1,1]
	v_pk_fma_f32 v[230:231], v[30:31], v[206:207], v[230:231] op_sel:[0,1,0] op_sel_hi:[1,1,1]
	v_pk_fma_f32 v[212:213], v[32:33], v[176:177], v[212:213] op_sel_hi:[1,0,1]
	v_pk_fma_f32 v[214:215], v[34:35], v[176:177], v[214:215] op_sel_hi:[1,0,1]
	v_pk_fma_f32 v[216:217], v[32:33], v[184:185], v[216:217] op_sel_hi:[1,0,1]
	v_pk_fma_f32 v[218:219], v[34:35], v[184:185], v[218:219] op_sel_hi:[1,0,1]
	v_pk_fma_f32 v[220:221], v[32:33], v[192:193], v[220:221] op_sel_hi:[1,0,1]
	v_pk_fma_f32 v[222:223], v[34:35], v[192:193], v[222:223] op_sel_hi:[1,0,1]
	v_pk_fma_f32 v[224:225], v[32:33], v[200:201], v[224:225] op_sel_hi:[1,0,1]
	v_pk_fma_f32 v[226:227], v[34:35], v[200:201], v[226:227] op_sel_hi:[1,0,1]
	v_pk_fma_f32 v[228:229], v[32:33], v[208:209], v[228:229] op_sel_hi:[1,0,1]
	v_pk_fma_f32 v[230:231], v[34:35], v[208:209], v[230:231] op_sel_hi:[1,0,1]
	v_pk_fma_f32 v[212:213], v[36:37], v[176:177], v[212:213] op_sel:[0,1,0] op_sel_hi:[1,1,1]
	v_pk_fma_f32 v[214:215], v[38:39], v[176:177], v[214:215] op_sel:[0,1,0] op_sel_hi:[1,1,1]
	v_pk_fma_f32 v[216:217], v[36:37], v[184:185], v[216:217] op_sel:[0,1,0] op_sel_hi:[1,1,1]
	v_pk_fma_f32 v[218:219], v[38:39], v[184:185], v[218:219] op_sel:[0,1,0] op_sel_hi:[1,1,1]
	v_pk_fma_f32 v[220:221], v[36:37], v[192:193], v[220:221] op_sel:[0,1,0] op_sel_hi:[1,1,1]
	v_pk_fma_f32 v[222:223], v[38:39], v[192:193], v[222:223] op_sel:[0,1,0] op_sel_hi:[1,1,1]
	v_pk_fma_f32 v[224:225], v[36:37], v[200:201], v[224:225] op_sel:[0,1,0] op_sel_hi:[1,1,1]
	v_pk_fma_f32 v[226:227], v[38:39], v[200:201], v[226:227] op_sel:[0,1,0] op_sel_hi:[1,1,1]
	v_pk_fma_f32 v[228:229], v[36:37], v[208:209], v[228:229] op_sel:[0,1,0] op_sel_hi:[1,1,1]
	v_pk_fma_f32 v[230:231], v[38:39], v[208:209], v[230:231] op_sel:[0,1,0] op_sel_hi:[1,1,1]
	v_pk_fma_f32 v[212:213], v[40:41], v[178:179], v[212:213] op_sel_hi:[1,0,1]
	v_pk_fma_f32 v[214:215], v[42:43], v[178:179], v[214:215] op_sel_hi:[1,0,1]
	v_pk_fma_f32 v[216:217], v[40:41], v[186:187], v[216:217] op_sel_hi:[1,0,1]
	v_pk_fma_f32 v[218:219], v[42:43], v[186:187], v[218:219] op_sel_hi:[1,0,1]
	v_pk_fma_f32 v[220:221], v[40:41], v[194:195], v[220:221] op_sel_hi:[1,0,1]
	v_pk_fma_f32 v[222:223], v[42:43], v[194:195], v[222:223] op_sel_hi:[1,0,1]
	v_pk_fma_f32 v[224:225], v[40:41], v[202:203], v[224:225] op_sel_hi:[1,0,1]
; __device__ __forceinline__ void ada_item(const Params& P, int item, float* sm) {
;     ...
;     for (int kk = 0; kk < 64; ++kk) {
;         const f32x4 w4 = *(const f32x4*)(wp + (size_t)kk * 9216);
; #pragma unroll
;         for (int r = 0; r < 5; ++r) { const float s = sv[r * 1024 + kg * 64 + kk]; a[r] += w4 * s; }
	v_pk_fma_f32 v[226:227], v[42:43], v[202:203], v[226:227] op_sel_hi:[1,0,1]
	v_pk_fma_f32 v[228:229], v[40:41], v[210:211], v[228:229] op_sel_hi:[1,0,1]
	v_pk_fma_f32 v[230:231], v[42:43], v[210:211], v[230:231] op_sel_hi:[1,0,1]
	v_pk_fma_f32 v[212:213], v[44:45], v[178:179], v[212:213] op_sel:[0,1,0] op_sel_hi:[1,1,1]
	v_pk_fma_f32 v[214:215], v[46:47], v[178:179], v[214:215] op_sel:[0,1,0] op_sel_hi:[1,1,1]
	v_pk_fma_f32 v[216:217], v[44:45], v[186:187], v[216:217] op_sel:[0,1,0] op_sel_hi:[1,1,1]
	v_pk_fma_f32 v[218:219], v[46:47], v[186:187], v[218:219] op_sel:[0,1,0] op_sel_hi:[1,1,1]
	v_pk_fma_f32 v[220:221], v[44:45], v[194:195], v[220:221] op_sel:[0,1,0] op_sel_hi:[1,1,1]
	v_pk_fma_f32 v[222:223], v[46:47], v[194:195], v[222:223] op_sel:[0,1,0] op_sel_hi:[1,1,1]
	v_pk_fma_f32 v[224:225], v[44:45], v[202:203], v[224:225] op_sel:[0,1,0] op_sel_hi:[1,1,1]
	v_pk_fma_f32 v[226:227], v[46:47], v[202:203], v[226:227] op_sel:[0,1,0] op_sel_hi:[1,1,1]
	v_pk_fma_f32 v[228:229], v[44:45], v[210:211], v[228:229] op_sel:[0,1,0] op_sel_hi:[1,1,1]
	v_pk_fma_f32 v[230:231], v[46:47], v[210:211], v[230:231] op_sel:[0,1,0] op_sel_hi:[1,1,1]
	ds_read_b128 v[172:175], v5 offset:416
	ds_read_b128 v[176:179], v5 offset:432
	ds_read_b128 v[180:183], v5 offset:4640
	ds_read_b128 v[184:187], v5 offset:4656
	ds_read_b128 v[188:191], v5 offset:8864
	ds_read_b128 v[192:195], v5 offset:8880
	ds_read_b128 v[196:199], v5 offset:13088
	ds_read_b128 v[200:203], v5 offset:13104
	ds_read_b128 v[204:207], v5 offset:17312
	ds_read_b128 v[208:211], v5 offset:17328
	s_waitcnt vmcnt(16)
	s_waitcnt lgkmcnt(0)
	v_pk_fma_f32 v[212:213], v[48:49], v[172:173], v[212:213] op_sel_hi:[1,0,1]
	v_pk_fma_f32 v[214:215], v[50:51], v[172:173], v[214:215] op_sel_hi:[1,0,1]
	v_pk_fma_f32 v[216:217], v[48:49], v[180:181], v[216:217] op_sel_hi:[1,0,1]
	v_pk_fma_f32 v[218:219], v[50:51], v[180:181], v[218:219] op_sel_hi:[1,0,1]
	v_pk_fma_f32 v[220:221], v[48:49], v[188:189], v[220:221] op_sel_hi:[1,0,1]
	v_pk_fma_f32 v[222:223], v[50:51], v[188:189], v[222:223] op_sel_hi:[1,0,1]
	v_pk_fma_f32 v[224:225], v[48:49], v[196:197], v[224:225] op_sel_hi:[1,0,1]
	v_pk_fma_f32 v[226:227], v[50:51], v[196:197], v[226:227] op_sel_hi:[1,0,1]
	v_pk_fma_f32 v[228:229], v[48:49], v[204:205], v[228:229] op_sel_hi:[1,0,1]
	v_pk_fma_f32 v[230:231], v[50:51], v[204:205], v[230:231] op_sel_hi:[1,0,1]
	v_pk_fma_f32 v[212:213], v[52:53], v[172:173], v[212:213] op_sel:[0,1,0] op_sel_hi:[1,1,1]
	v_pk_fma_f32 v[214:215], v[54:55], v[172:173], v[214:215] op_sel:[0,1,0] op_sel_hi:[1,1,1]
	v_pk_fma_f32 v[216:217], v[52:53], v[180:181], v[216:217] op_sel:[0,1,0] op_sel_hi:[1,1,1]
	v_pk_fma_f32 v[218:219], v[54:55], v[180:181], v[218:219] op_sel:[0,1,0] op_sel_hi:[1,1,1]
	v_pk_fma_f32 v[220:221], v[52:53], v[188:189], v[220:221] op_sel:[0,1,0] op_sel_hi:[1,1,1]
	v_pk_fma_f32 v[222:223], v[54:55], v[188:189], v[222:223] op_sel:[0,1,0] op_sel_hi:[1,1,1]
	v_pk_fma_f32 v[224:225], v[52:53], v[196:197], v[224:225] op_sel:[0,1,0] op_sel_hi:[1,1,1]
	v_pk_fma_f32 v[226:227], v[54:55], v[196:197], v[226:227] op_sel:[0,1,0] op_sel_hi:[1,1,1]
	v_pk_fma_f32 v[228:229], v[52:53], v[204:205], v[228:229] op_sel:[0,1,0] op_sel_hi:[1,1,1]
	v_pk_fma_f32 v[230:231], v[54:55], v[204:205], v[230:231] op_sel:[0,1,0] op_sel_hi:[1,1,1]
	v_pk_fma_f32 v[212:213], v[56:57], v[174:175], v[212:213] op_sel_hi:[1,0,1]
	v_pk_fma_f32 v[214:215], v[58:59], v[174:175], v[214:215] op_sel_hi:[1,0,1]
	v_pk_fma_f32 v[216:217], v[56:57], v[182:183], v[216:217] op_sel_hi:[1,0,1]
	v_pk_fma_f32 v[218:219], v[58:59], v[182:183], v[218:219] op_sel_hi:[1,0,1]
	v_pk_fma_f32 v[220:221], v[56:57], v[190:191], v[220:221] op_sel_hi:[1,0,1]
	v_pk_fma_f32 v[222:223], v[58:59], v[190:191], v[222:223] op_sel_hi:[1,0,1]
	v_pk_fma_f32 v[224:225], v[56:57], v[198:199], v[224:225] op_sel_hi:[1,0,1]
	v_pk_fma_f32 v[226:227], v[58:59], v[198:199], v[226:227] op_sel_hi:[1,0,1]
	v_pk_fma_f32 v[228:229], v[56:57], v[206:207], v[228:229] op_sel_hi:[1,0,1]
	v_pk_fma_f32 v[230:231], v[58:59], v[206:207], v[230:231] op_sel_hi:[1,0,1]
	v_pk_fma_f32 v[212:213], v[60:61], v[174:175], v[212:213] op_sel:[0,1,0] op_sel_hi:[1,1,1]
	v_pk_fma_f32 v[214:215], v[62:63], v[174:175], v[214:215] op_sel:[0,1,0] op_sel_hi:[1,1,1]
	v_pk_fma_f32 v[216:217], v[60:61], v[182:183], v[216:217] op_sel:[0,1,0] op_sel_hi:[1,1,1]
	v_pk_fma_f32 v[218:219], v[62:63], v[182:183], v[218:219] op_sel:[0,1,0] op_sel_hi:[1,1,1]
	v_pk_fma_f32 v[220:221], v[60:61], v[190:191], v[220:221] op_sel:[0,1,0] op_sel_hi:[1,1,1]
	v_pk_fma_f32 v[222:223], v[62:63], v[190:191], v[222:223] op_sel:[0,1,0] op_sel_hi:[1,1,1]
	v_pk_fma_f32 v[224:225], v[60:61], v[198:199], v[224:225] op_sel:[0,1,0] op_sel_hi:[1,1,1]
	v_pk_fma_f32 v[226:227], v[62:63], v[198:199], v[226:227] op_sel:[0,1,0] op_sel_hi:[1,1,1]
	v_pk_fma_f32 v[228:229], v[60:61], v[206:207], v[228:229] op_sel:[0,1,0] op_sel_hi:[1,1,1]
	v_pk_fma_f32 v[230:231], v[62:63], v[206:207], v[230:231] op_sel:[0,1,0] op_sel_hi:[1,1,1]
	v_pk_fma_f32 v[212:213], v[64:65], v[176:177], v[212:213] op_sel_hi:[1,0,1]
	v_pk_fma_f32 v[214:215], v[66:67], v[176:177], v[214:215] op_sel_hi:[1,0,1]
	v_pk_fma_f32 v[216:217], v[64:65], v[184:185], v[216:217] op_sel_hi:[1,0,1]
	v_pk_fma_f32 v[218:219], v[66:67], v[184:185], v[218:219] op_sel_hi:[1,0,1]
	v_pk_fma_f32 v[220:221], v[64:65], v[192:193], v[220:221] op_sel_hi:[1,0,1]
	v_pk_fma_f32 v[222:223], v[66:67], v[192:193], v[222:223] op_sel_hi:[1,0,1]
	v_pk_fma_f32 v[224:225], v[64:65], v[200:201], v[224:225] op_sel_hi:[1,0,1]
	v_pk_fma_f32 v[226:227], v[66:67], v[200:201], v[226:227] op_sel_hi:[1,0,1]
; __device__ __forceinline__ void ada_item(const Params& P, int item, float* sm) {
;     ...
;     for (int kk = 0; kk < 64; ++kk) {
;         const f32x4 w4 = *(const f32x4*)(wp + (size_t)kk * 9216);
; #pragma unroll
;         for (int r = 0; r < 5; ++r) { const float s = sv[r * 1024 + kg * 64 + kk]; a[r] += w4 * s; }
	v_pk_fma_f32 v[228:229], v[64:65], v[208:209], v[228:229] op_sel_hi:[1,0,1]
	v_pk_fma_f32 v[230:231], v[66:67], v[208:209], v[230:231] op_sel_hi:[1,0,1]
	v_pk_fma_f32 v[212:213], v[68:69], v[176:177], v[212:213] op_sel:[0,1,0] op_sel_hi:[1,1,1]
	v_pk_fma_f32 v[214:215], v[70:71], v[176:177], v[214:215] op_sel:[0,1,0] op_sel_hi:[1,1,1]
	v_pk_fma_f32 v[216:217], v[68:69], v[184:185], v[216:217] op_sel:[0,1,0] op_sel_hi:[1,1,1]
	v_pk_fma_f32 v[218:219], v[70:71], v[184:185], v[218:219] op_sel:[0,1,0] op_sel_hi:[1,1,1]
	v_pk_fma_f32 v[220:221], v[68:69], v[192:193], v[220:221] op_sel:[0,1,0] op_sel_hi:[1,1,1]
	v_pk_fma_f32 v[222:223], v[70:71], v[192:193], v[222:223] op_sel:[0,1,0] op_sel_hi:[1,1,1]
	v_pk_fma_f32 v[224:225], v[68:69], v[200:201], v[224:225] op_sel:[0,1,0] op_sel_hi:[1,1,1]
	v_pk_fma_f32 v[226:227], v[70:71], v[200:201], v[226:227] op_sel:[0,1,0] op_sel_hi:[1,1,1]
	v_pk_fma_f32 v[228:229], v[68:69], v[208:209], v[228:229] op_sel:[0,1,0] op_sel_hi:[1,1,1]
	v_pk_fma_f32 v[230:231], v[70:71], v[208:209], v[230:231] op_sel:[0,1,0] op_sel_hi:[1,1,1]
	v_pk_fma_f32 v[212:213], v[72:73], v[178:179], v[212:213] op_sel_hi:[1,0,1]
	v_pk_fma_f32 v[214:215], v[74:75], v[178:179], v[214:215] op_sel_hi:[1,0,1]
	v_pk_fma_f32 v[216:217], v[72:73], v[186:187], v[216:217] op_sel_hi:[1,0,1]
	v_pk_fma_f32 v[218:219], v[74:75], v[186:187], v[218:219] op_sel_hi:[1,0,1]
	v_pk_fma_f32 v[220:221], v[72:73], v[194:195], v[220:221] op_sel_hi:[1,0,1]
	v_pk_fma_f32 v[222:223], v[74:75], v[194:195], v[222:223] op_sel_hi:[1,0,1]
	v_pk_fma_f32 v[224:225], v[72:73], v[202:203], v[224:225] op_sel_hi:[1,0,1]
	v_pk_fma_f32 v[226:227], v[74:75], v[202:203], v[226:227] op_sel_hi:[1,0,1]
	v_pk_fma_f32 v[228:229], v[72:73], v[210:211], v[228:229] op_sel_hi:[1,0,1]
	v_pk_fma_f32 v[230:231], v[74:75], v[210:211], v[230:231] op_sel_hi:[1,0,1]
	v_pk_fma_f32 v[212:213], v[76:77], v[178:179], v[212:213] op_sel:[0,1,0] op_sel_hi:[1,1,1]
	v_pk_fma_f32 v[214:215], v[78:79], v[178:179], v[214:215] op_sel:[0,1,0] op_sel_hi:[1,1,1]
	v_pk_fma_f32 v[216:217], v[76:77], v[186:187], v[216:217] op_sel:[0,1,0] op_sel_hi:[1,1,1]
	v_pk_fma_f32 v[218:219], v[78:79], v[186:187], v[218:219] op_sel:[0,1,0] op_sel_hi:[1,1,1]
	v_pk_fma_f32 v[220:221], v[76:77], v[194:195], v[220:221] op_sel:[0,1,0] op_sel_hi:[1,1,1]
	v_pk_fma_f32 v[222:223], v[78:79], v[194:195], v[222:223] op_sel:[0,1,0] op_sel_hi:[1,1,1]
	v_pk_fma_f32 v[224:225], v[76:77], v[202:203], v[224:225] op_sel:[0,1,0] op_sel_hi:[1,1,1]
	v_pk_fma_f32 v[226:227], v[78:79], v[202:203], v[226:227] op_sel:[0,1,0] op_sel_hi:[1,1,1]
	v_pk_fma_f32 v[228:229], v[76:77], v[210:211], v[228:229] op_sel:[0,1,0] op_sel_hi:[1,1,1]
	v_pk_fma_f32 v[230:231], v[78:79], v[210:211], v[230:231] op_sel:[0,1,0] op_sel_hi:[1,1,1]
	ds_read_b128 v[172:175], v5 offset:448
	ds_read_b128 v[176:179], v5 offset:464
	ds_read_b128 v[180:183], v5 offset:4672
	ds_read_b128 v[184:187], v5 offset:4688
	ds_read_b128 v[188:191], v5 offset:8896
	ds_read_b128 v[192:195], v5 offset:8912
	ds_read_b128 v[196:199], v5 offset:13120
	ds_read_b128 v[200:203], v5 offset:13136
	ds_read_b128 v[204:207], v5 offset:17344
	ds_read_b128 v[208:211], v5 offset:17360
	s_waitcnt vmcnt(8)
	s_waitcnt lgkmcnt(0)
	v_pk_fma_f32 v[212:213], v[80:81], v[172:173], v[212:213] op_sel_hi:[1,0,1]
	v_pk_fma_f32 v[214:215], v[82:83], v[172:173], v[214:215] op_sel_hi:[1,0,1]
	v_pk_fma_f32 v[216:217], v[80:81], v[180:181], v[216:217] op_sel_hi:[1,0,1]
	v_pk_fma_f32 v[218:219], v[82:83], v[180:181], v[218:219] op_sel_hi:[1,0,1]
	v_pk_fma_f32 v[220:221], v[80:81], v[188:189], v[220:221] op_sel_hi:[1,0,1]
	v_pk_fma_f32 v[222:223], v[82:83], v[188:189], v[222:223] op_sel_hi:[1,0,1]
	v_pk_fma_f32 v[224:225], v[80:81], v[196:197], v[224:225] op_sel_hi:[1,0,1]
	v_pk_fma_f32 v[226:227], v[82:83], v[196:197], v[226:227] op_sel_hi:[1,0,1]
	v_pk_fma_f32 v[228:229], v[80:81], v[204:205], v[228:229] op_sel_hi:[1,0,1]
	v_pk_fma_f32 v[230:231], v[82:83], v[204:205], v[230:231] op_sel_hi:[1,0,1]
	v_pk_fma_f32 v[212:213], v[84:85], v[172:173], v[212:213] op_sel:[0,1,0] op_sel_hi:[1,1,1]
	v_pk_fma_f32 v[214:215], v[86:87], v[172:173], v[214:215] op_sel:[0,1,0] op_sel_hi:[1,1,1]
	v_pk_fma_f32 v[216:217], v[84:85], v[180:181], v[216:217] op_sel:[0,1,0] op_sel_hi:[1,1,1]
	v_pk_fma_f32 v[218:219], v[86:87], v[180:181], v[218:219] op_sel:[0,1,0] op_sel_hi:[1,1,1]
	v_pk_fma_f32 v[220:221], v[84:85], v[188:189], v[220:221] op_sel:[0,1,0] op_sel_hi:[1,1,1]
	v_pk_fma_f32 v[222:223], v[86:87], v[188:189], v[222:223] op_sel:[0,1,0] op_sel_hi:[1,1,1]
	v_pk_fma_f32 v[224:225], v[84:85], v[196:197], v[224:225] op_sel:[0,1,0] op_sel_hi:[1,1,1]
	v_pk_fma_f32 v[226:227], v[86:87], v[196:197], v[226:227] op_sel:[0,1,0] op_sel_hi:[1,1,1]
	v_pk_fma_f32 v[228:229], v[84:85], v[204:205], v[228:229] op_sel:[0,1,0] op_sel_hi:[1,1,1]
	v_pk_fma_f32 v[230:231], v[86:87], v[204:205], v[230:231] op_sel:[0,1,0] op_sel_hi:[1,1,1]
	v_pk_fma_f32 v[212:213], v[88:89], v[174:175], v[212:213] op_sel_hi:[1,0,1]
	v_pk_fma_f32 v[214:215], v[90:91], v[174:175], v[214:215] op_sel_hi:[1,0,1]
	v_pk_fma_f32 v[216:217], v[88:89], v[182:183], v[216:217] op_sel_hi:[1,0,1]
	v_pk_fma_f32 v[218:219], v[90:91], v[182:183], v[218:219] op_sel_hi:[1,0,1]
	v_pk_fma_f32 v[220:221], v[88:89], v[190:191], v[220:221] op_sel_hi:[1,0,1]
	v_pk_fma_f32 v[222:223], v[90:91], v[190:191], v[222:223] op_sel_hi:[1,0,1]
	v_pk_fma_f32 v[224:225], v[88:89], v[198:199], v[224:225] op_sel_hi:[1,0,1]
	v_pk_fma_f32 v[226:227], v[90:91], v[198:199], v[226:227] op_sel_hi:[1,0,1]
	v_pk_fma_f32 v[228:229], v[88:89], v[206:207], v[228:229] op_sel_hi:[1,0,1]
	v_pk_fma_f32 v[230:231], v[90:91], v[206:207], v[230:231] op_sel_hi:[1,0,1]
; __device__ __forceinline__ void ada_item(const Params& P, int item, float* sm) {
;     ...
;     for (int kk = 0; kk < 64; ++kk) {
;         const f32x4 w4 = *(const f32x4*)(wp + (size_t)kk * 9216);
; #pragma unroll
;         for (int r = 0; r < 5; ++r) { const float s = sv[r * 1024 + kg * 64 + kk]; a[r] += w4 * s; }
	v_pk_fma_f32 v[212:213], v[92:93], v[174:175], v[212:213] op_sel:[0,1,0] op_sel_hi:[1,1,1]
	v_pk_fma_f32 v[214:215], v[94:95], v[174:175], v[214:215] op_sel:[0,1,0] op_sel_hi:[1,1,1]
	v_pk_fma_f32 v[216:217], v[92:93], v[182:183], v[216:217] op_sel:[0,1,0] op_sel_hi:[1,1,1]
	v_pk_fma_f32 v[218:219], v[94:95], v[182:183], v[218:219] op_sel:[0,1,0] op_sel_hi:[1,1,1]
	v_pk_fma_f32 v[220:221], v[92:93], v[190:191], v[220:221] op_sel:[0,1,0] op_sel_hi:[1,1,1]
	v_pk_fma_f32 v[222:223], v[94:95], v[190:191], v[222:223] op_sel:[0,1,0] op_sel_hi:[1,1,1]
	v_pk_fma_f32 v[224:225], v[92:93], v[198:199], v[224:225] op_sel:[0,1,0] op_sel_hi:[1,1,1]
	v_pk_fma_f32 v[226:227], v[94:95], v[198:199], v[226:227] op_sel:[0,1,0] op_sel_hi:[1,1,1]
	v_pk_fma_f32 v[228:229], v[92:93], v[206:207], v[228:229] op_sel:[0,1,0] op_sel_hi:[1,1,1]
	v_pk_fma_f32 v[230:231], v[94:95], v[206:207], v[230:231] op_sel:[0,1,0] op_sel_hi:[1,1,1]
	v_pk_fma_f32 v[212:213], v[96:97], v[176:177], v[212:213] op_sel_hi:[1,0,1]
	v_pk_fma_f32 v[214:215], v[98:99], v[176:177], v[214:215] op_sel_hi:[1,0,1]
	v_pk_fma_f32 v[216:217], v[96:97], v[184:185], v[216:217] op_sel_hi:[1,0,1]
	v_pk_fma_f32 v[218:219], v[98:99], v[184:185], v[218:219] op_sel_hi:[1,0,1]
	v_pk_fma_f32 v[220:221], v[96:97], v[192:193], v[220:221] op_sel_hi:[1,0,1]
	v_pk_fma_f32 v[222:223], v[98:99], v[192:193], v[222:223] op_sel_hi:[1,0,1]
	v_pk_fma_f32 v[224:225], v[96:97], v[200:201], v[224:225] op_sel_hi:[1,0,1]
	v_pk_fma_f32 v[226:227], v[98:99], v[200:201], v[226:227] op_sel_hi:[1,0,1]
	v_pk_fma_f32 v[228:229], v[96:97], v[208:209], v[228:229] op_sel_hi:[1,0,1]
	v_pk_fma_f32 v[230:231], v[98:99], v[208:209], v[230:231] op_sel_hi:[1,0,1]
	v_pk_fma_f32 v[212:213], v[100:101], v[176:177], v[212:213] op_sel:[0,1,0] op_sel_hi:[1,1,1]
	v_pk_fma_f32 v[214:215], v[102:103], v[176:177], v[214:215] op_sel:[0,1,0] op_sel_hi:[1,1,1]
	v_pk_fma_f32 v[216:217], v[100:101], v[184:185], v[216:217] op_sel:[0,1,0] op_sel_hi:[1,1,1]
	v_pk_fma_f32 v[218:219], v[102:103], v[184:185], v[218:219] op_sel:[0,1,0] op_sel_hi:[1,1,1]
	v_pk_fma_f32 v[220:221], v[100:101], v[192:193], v[220:221] op_sel:[0,1,0] op_sel_hi:[1,1,1]
	v_pk_fma_f32 v[222:223], v[102:103], v[192:193], v[222:223] op_sel:[0,1,0] op_sel_hi:[1,1,1]
	v_pk_fma_f32 v[224:225], v[100:101], v[200:201], v[224:225] op_sel:[0,1,0] op_sel_hi:[1,1,1]
	v_pk_fma_f32 v[226:227], v[102:103], v[200:201], v[226:227] op_sel:[0,1,0] op_sel_hi:[1,1,1]
	v_pk_fma_f32 v[228:229], v[100:101], v[208:209], v[228:229] op_sel:[0,1,0] op_sel_hi:[1,1,1]
	v_pk_fma_f32 v[230:231], v[102:103], v[208:209], v[230:231] op_sel:[0,1,0] op_sel_hi:[1,1,1]
	v_pk_fma_f32 v[212:213], v[104:105], v[178:179], v[212:213] op_sel_hi:[1,0,1]
	v_pk_fma_f32 v[214:215], v[106:107], v[178:179], v[214:215] op_sel_hi:[1,0,1]
	v_pk_fma_f32 v[216:217], v[104:105], v[186:187], v[216:217] op_sel_hi:[1,0,1]
	v_pk_fma_f32 v[218:219], v[106:107], v[186:187], v[218:219] op_sel_hi:[1,0,1]
	v_pk_fma_f32 v[220:221], v[104:105], v[194:195], v[220:221] op_sel_hi:[1,0,1]
	v_pk_fma_f32 v[222:223], v[106:107], v[194:195], v[222:223] op_sel_hi:[1,0,1]
	v_pk_fma_f32 v[224:225], v[104:105], v[202:203], v[224:225] op_sel_hi:[1,0,1]
	v_pk_fma_f32 v[226:227], v[106:107], v[202:203], v[226:227] op_sel_hi:[1,0,1]
	v_pk_fma_f32 v[228:229], v[104:105], v[210:211], v[228:229] op_sel_hi:[1,0,1]
	v_pk_fma_f32 v[230:231], v[106:107], v[210:211], v[230:231] op_sel_hi:[1,0,1]
	v_pk_fma_f32 v[212:213], v[108:109], v[178:179], v[212:213] op_sel:[0,1,0] op_sel_hi:[1,1,1]
	v_pk_fma_f32 v[214:215], v[110:111], v[178:179], v[214:215] op_sel:[0,1,0] op_sel_hi:[1,1,1]
	v_pk_fma_f32 v[216:217], v[108:109], v[186:187], v[216:217] op_sel:[0,1,0] op_sel_hi:[1,1,1]
	v_pk_fma_f32 v[218:219], v[110:111], v[186:187], v[218:219] op_sel:[0,1,0] op_sel_hi:[1,1,1]
	v_pk_fma_f32 v[220:221], v[108:109], v[194:195], v[220:221] op_sel:[0,1,0] op_sel_hi:[1,1,1]
	v_pk_fma_f32 v[222:223], v[110:111], v[194:195], v[222:223] op_sel:[0,1,0] op_sel_hi:[1,1,1]
	v_pk_fma_f32 v[224:225], v[108:109], v[202:203], v[224:225] op_sel:[0,1,0] op_sel_hi:[1,1,1]
	v_pk_fma_f32 v[226:227], v[110:111], v[202:203], v[226:227] op_sel:[0,1,0] op_sel_hi:[1,1,1]
	v_pk_fma_f32 v[228:229], v[108:109], v[210:211], v[228:229] op_sel:[0,1,0] op_sel_hi:[1,1,1]
	v_pk_fma_f32 v[230:231], v[110:111], v[210:211], v[230:231] op_sel:[0,1,0] op_sel_hi:[1,1,1]
	ds_read_b128 v[172:175], v5 offset:480
	ds_read_b128 v[176:179], v5 offset:496
	ds_read_b128 v[180:183], v5 offset:4704
	ds_read_b128 v[184:187], v5 offset:4720
	ds_read_b128 v[188:191], v5 offset:8928
	ds_read_b128 v[192:195], v5 offset:8944
	ds_read_b128 v[196:199], v5 offset:13152
	ds_read_b128 v[200:203], v5 offset:13168
	ds_read_b128 v[204:207], v5 offset:17376
	ds_read_b128 v[208:211], v5 offset:17392
	s_waitcnt vmcnt(0)
	s_waitcnt lgkmcnt(0)
; __device__ __forceinline__ void ada_item(const Params& P, int item, float* sm) {
;     ...
;     for (int kk = 0; kk < 64; ++kk) {
;         const f32x4 w4 = *(const f32x4*)(wp + (size_t)kk * 9216);
; #pragma unroll
;         for (int r = 0; r < 5; ++r) { const float s = sv[r * 1024 + kg * 64 + kk]; a[r] += w4 * s; }
	v_pk_fma_f32 v[212:213], v[112:113], v[172:173], v[212:213] op_sel_hi:[1,0,1]
	v_pk_fma_f32 v[214:215], v[114:115], v[172:173], v[214:215] op_sel_hi:[1,0,1]
	v_pk_fma_f32 v[216:217], v[112:113], v[180:181], v[216:217] op_sel_hi:[1,0,1]
	v_pk_fma_f32 v[218:219], v[114:115], v[180:181], v[218:219] op_sel_hi:[1,0,1]
	v_pk_fma_f32 v[220:221], v[112:113], v[188:189], v[220:221] op_sel_hi:[1,0,1]
	v_pk_fma_f32 v[222:223], v[114:115], v[188:189], v[222:223] op_sel_hi:[1,0,1]
	v_pk_fma_f32 v[224:225], v[112:113], v[196:197], v[224:225] op_sel_hi:[1,0,1]
	v_pk_fma_f32 v[226:227], v[114:115], v[196:197], v[226:227] op_sel_hi:[1,0,1]
	v_pk_fma_f32 v[228:229], v[112:113], v[204:205], v[228:229] op_sel_hi:[1,0,1]
	v_pk_fma_f32 v[230:231], v[114:115], v[204:205], v[230:231] op_sel_hi:[1,0,1]
	v_pk_fma_f32 v[212:213], v[116:117], v[172:173], v[212:213] op_sel:[0,1,0] op_sel_hi:[1,1,1]
	v_pk_fma_f32 v[214:215], v[118:119], v[172:173], v[214:215] op_sel:[0,1,0] op_sel_hi:[1,1,1]
	v_pk_fma_f32 v[216:217], v[116:117], v[180:181], v[216:217] op_sel:[0,1,0] op_sel_hi:[1,1,1]
	v_pk_fma_f32 v[218:219], v[118:119], v[180:181], v[218:219] op_sel:[0,1,0] op_sel_hi:[1,1,1]
	v_pk_fma_f32 v[220:221], v[116:117], v[188:189], v[220:221] op_sel:[0,1,0] op_sel_hi:[1,1,1]
	v_pk_fma_f32 v[222:223], v[118:119], v[188:189], v[222:223] op_sel:[0,1,0] op_sel_hi:[1,1,1]
	v_pk_fma_f32 v[224:225], v[116:117], v[196:197], v[224:225] op_sel:[0,1,0] op_sel_hi:[1,1,1]
	v_pk_fma_f32 v[226:227], v[118:119], v[196:197], v[226:227] op_sel:[0,1,0] op_sel_hi:[1,1,1]
	v_pk_fma_f32 v[228:229], v[116:117], v[204:205], v[228:229] op_sel:[0,1,0] op_sel_hi:[1,1,1]
	v_pk_fma_f32 v[230:231], v[118:119], v[204:205], v[230:231] op_sel:[0,1,0] op_sel_hi:[1,1,1]
	v_pk_fma_f32 v[212:213], v[120:121], v[174:175], v[212:213] op_sel_hi:[1,0,1]
	v_pk_fma_f32 v[214:215], v[122:123], v[174:175], v[214:215] op_sel_hi:[1,0,1]
	v_pk_fma_f32 v[216:217], v[120:121], v[182:183], v[216:217] op_sel_hi:[1,0,1]
	v_pk_fma_f32 v[218:219], v[122:123], v[182:183], v[218:219] op_sel_hi:[1,0,1]
	v_pk_fma_f32 v[220:221], v[120:121], v[190:191], v[220:221] op_sel_hi:[1,0,1]
	v_pk_fma_f32 v[222:223], v[122:123], v[190:191], v[222:223] op_sel_hi:[1,0,1]
	v_pk_fma_f32 v[224:225], v[120:121], v[198:199], v[224:225] op_sel_hi:[1,0,1]
	v_pk_fma_f32 v[226:227], v[122:123], v[198:199], v[226:227] op_sel_hi:[1,0,1]
	v_pk_fma_f32 v[228:229], v[120:121], v[206:207], v[228:229] op_sel_hi:[1,0,1]
	v_pk_fma_f32 v[230:231], v[122:123], v[206:207], v[230:231] op_sel_hi:[1,0,1]
	v_pk_fma_f32 v[212:213], v[124:125], v[174:175], v[212:213] op_sel:[0,1,0] op_sel_hi:[1,1,1]
	v_pk_fma_f32 v[214:215], v[126:127], v[174:175], v[214:215] op_sel:[0,1,0] op_sel_hi:[1,1,1]
	v_pk_fma_f32 v[216:217], v[124:125], v[182:183], v[216:217] op_sel:[0,1,0] op_sel_hi:[1,1,1]
	v_pk_fma_f32 v[218:219], v[126:127], v[182:183], v[218:219] op_sel:[0,1,0] op_sel_hi:[1,1,1]
	v_pk_fma_f32 v[220:221], v[124:125], v[190:191], v[220:221] op_sel:[0,1,0] op_sel_hi:[1,1,1]
	v_pk_fma_f32 v[222:223], v[126:127], v[190:191], v[222:223] op_sel:[0,1,0] op_sel_hi:[1,1,1]
	v_pk_fma_f32 v[224:225], v[124:125], v[198:199], v[224:225] op_sel:[0,1,0] op_sel_hi:[1,1,1]
	v_pk_fma_f32 v[226:227], v[126:127], v[198:199], v[226:227] op_sel:[0,1,0] op_sel_hi:[1,1,1]
	v_pk_fma_f32 v[228:229], v[124:125], v[206:207], v[228:229] op_sel:[0,1,0] op_sel_hi:[1,1,1]
	v_pk_fma_f32 v[230:231], v[126:127], v[206:207], v[230:231] op_sel:[0,1,0] op_sel_hi:[1,1,1]
	v_pk_fma_f32 v[212:213], v[128:129], v[176:177], v[212:213] op_sel_hi:[1,0,1]
	v_pk_fma_f32 v[214:215], v[130:131], v[176:177], v[214:215] op_sel_hi:[1,0,1]
	v_pk_fma_f32 v[216:217], v[128:129], v[184:185], v[216:217] op_sel_hi:[1,0,1]
	v_pk_fma_f32 v[218:219], v[130:131], v[184:185], v[218:219] op_sel_hi:[1,0,1]
	v_pk_fma_f32 v[220:221], v[128:129], v[192:193], v[220:221] op_sel_hi:[1,0,1]
	v_pk_fma_f32 v[222:223], v[130:131], v[192:193], v[222:223] op_sel_hi:[1,0,1]
	v_pk_fma_f32 v[224:225], v[128:129], v[200:201], v[224:225] op_sel_hi:[1,0,1]
	v_pk_fma_f32 v[226:227], v[130:131], v[200:201], v[226:227] op_sel_hi:[1,0,1]
	v_pk_fma_f32 v[228:229], v[128:129], v[208:209], v[228:229] op_sel_hi:[1,0,1]
	v_pk_fma_f32 v[230:231], v[130:131], v[208:209], v[230:231] op_sel_hi:[1,0,1]
	v_pk_fma_f32 v[212:213], v[132:133], v[176:177], v[212:213] op_sel:[0,1,0] op_sel_hi:[1,1,1]
	v_pk_fma_f32 v[214:215], v[134:135], v[176:177], v[214:215] op_sel:[0,1,0] op_sel_hi:[1,1,1]
	v_pk_fma_f32 v[216:217], v[132:133], v[184:185], v[216:217] op_sel:[0,1,0] op_sel_hi:[1,1,1]
	v_pk_fma_f32 v[218:219], v[134:135], v[184:185], v[218:219] op_sel:[0,1,0] op_sel_hi:[1,1,1]
	v_pk_fma_f32 v[220:221], v[132:133], v[192:193], v[220:221] op_sel:[0,1,0] op_sel_hi:[1,1,1]
	v_pk_fma_f32 v[222:223], v[134:135], v[192:193], v[222:223] op_sel:[0,1,0] op_sel_hi:[1,1,1]
	v_pk_fma_f32 v[224:225], v[132:133], v[200:201], v[224:225] op_sel:[0,1,0] op_sel_hi:[1,1,1]
	v_pk_fma_f32 v[226:227], v[134:135], v[200:201], v[226:227] op_sel:[0,1,0] op_sel_hi:[1,1,1]
	v_pk_fma_f32 v[228:229], v[132:133], v[208:209], v[228:229] op_sel:[0,1,0] op_sel_hi:[1,1,1]
	v_pk_fma_f32 v[230:231], v[134:135], v[208:209], v[230:231] op_sel:[0,1,0] op_sel_hi:[1,1,1]
	v_pk_fma_f32 v[212:213], v[136:137], v[178:179], v[212:213] op_sel_hi:[1,0,1]
	v_pk_fma_f32 v[214:215], v[138:139], v[178:179], v[214:215] op_sel_hi:[1,0,1]
	v_pk_fma_f32 v[216:217], v[136:137], v[186:187], v[216:217] op_sel_hi:[1,0,1]
	v_pk_fma_f32 v[218:219], v[138:139], v[186:187], v[218:219] op_sel_hi:[1,0,1]
	v_pk_fma_f32 v[220:221], v[136:137], v[194:195], v[220:221] op_sel_hi:[1,0,1]
	v_pk_fma_f32 v[222:223], v[138:139], v[194:195], v[222:223] op_sel_hi:[1,0,1]
; __device__ __forceinline__ void ada_item(const Params& P, int item, float* sm) {
;     ...
;         for (int r = 0; r < 5; ++r) { const float s = sv[r * 1024 + kg * 64 + kk]; a[r] += w4 * s; }
;     }
; #pragma unroll
;     for (int r = 0; r < 5; ++r) *(f32x4*)(red + (kg * 5 + r) * 64 + cgp * 4) = a[r];
;     __syncthreads();
;     for (int e = tid; e < 320; e += 256) {
;         const int r = e >> 6, col = e & 63; float s = P.in[5][n0 + col];
; #pragma unroll
;         for (int g = 0; g < 16; ++g) s += red[(g * 5 + r) * 64 + col];
;         ((float*)(P.ws + OFF_MOD))[r * 9216 + n0 + col] = s;
;     }
	v_pk_fma_f32 v[224:225], v[136:137], v[202:203], v[224:225] op_sel_hi:[1,0,1]
	v_pk_fma_f32 v[226:227], v[138:139], v[202:203], v[226:227] op_sel_hi:[1,0,1]
	v_pk_fma_f32 v[228:229], v[136:137], v[210:211], v[228:229] op_sel_hi:[1,0,1]
	v_pk_fma_f32 v[230:231], v[138:139], v[210:211], v[230:231] op_sel_hi:[1,0,1]
	v_pk_fma_f32 v[212:213], v[140:141], v[178:179], v[212:213] op_sel:[0,1,0] op_sel_hi:[1,1,1]
	v_pk_fma_f32 v[214:215], v[142:143], v[178:179], v[214:215] op_sel:[0,1,0] op_sel_hi:[1,1,1]
	v_pk_fma_f32 v[216:217], v[140:141], v[186:187], v[216:217] op_sel:[0,1,0] op_sel_hi:[1,1,1]
	v_pk_fma_f32 v[218:219], v[142:143], v[186:187], v[218:219] op_sel:[0,1,0] op_sel_hi:[1,1,1]
	v_pk_fma_f32 v[220:221], v[140:141], v[194:195], v[220:221] op_sel:[0,1,0] op_sel_hi:[1,1,1]
	v_pk_fma_f32 v[222:223], v[142:143], v[194:195], v[222:223] op_sel:[0,1,0] op_sel_hi:[1,1,1]
	v_pk_fma_f32 v[224:225], v[140:141], v[202:203], v[224:225] op_sel:[0,1,0] op_sel_hi:[1,1,1]
	v_pk_fma_f32 v[226:227], v[142:143], v[202:203], v[226:227] op_sel:[0,1,0] op_sel_hi:[1,1,1]
	v_pk_fma_f32 v[228:229], v[140:141], v[210:211], v[228:229] op_sel:[0,1,0] op_sel_hi:[1,1,1]
	v_pk_fma_f32 v[230:231], v[142:143], v[210:211], v[230:231] op_sel:[0,1,0] op_sel_hi:[1,1,1]
	s_nop 1
	v_add_f32_dpp v172, v212, v212 row_ror:8 row_mask:0xf bank_mask:0xf
	v_add_f32_dpp v173, v213, v213 row_ror:8 row_mask:0xf bank_mask:0xf
	v_add_f32_dpp v174, v214, v214 row_ror:8 row_mask:0xf bank_mask:0xf
	v_add_f32_dpp v175, v215, v215 row_ror:8 row_mask:0xf bank_mask:0xf
	v_add_f32_dpp v176, v216, v216 row_ror:8 row_mask:0xf bank_mask:0xf
	v_add_f32_dpp v177, v217, v217 row_ror:8 row_mask:0xf bank_mask:0xf
	v_add_f32_dpp v178, v218, v218 row_ror:8 row_mask:0xf bank_mask:0xf
	v_add_f32_dpp v179, v219, v219 row_ror:8 row_mask:0xf bank_mask:0xf
	v_add_f32_dpp v180, v220, v220 row_ror:8 row_mask:0xf bank_mask:0xf
	v_add_f32_dpp v181, v221, v221 row_ror:8 row_mask:0xf bank_mask:0xf
	v_add_f32_dpp v182, v222, v222 row_ror:8 row_mask:0xf bank_mask:0xf
	v_add_f32_dpp v183, v223, v223 row_ror:8 row_mask:0xf bank_mask:0xf
	v_add_f32_dpp v184, v224, v224 row_ror:8 row_mask:0xf bank_mask:0xf
	v_add_f32_dpp v185, v225, v225 row_ror:8 row_mask:0xf bank_mask:0xf
	v_add_f32_dpp v186, v226, v226 row_ror:8 row_mask:0xf bank_mask:0xf
	v_add_f32_dpp v187, v227, v227 row_ror:8 row_mask:0xf bank_mask:0xf
	v_add_f32_dpp v188, v228, v228 row_ror:8 row_mask:0xf bank_mask:0xf
	v_add_f32_dpp v189, v229, v229 row_ror:8 row_mask:0xf bank_mask:0xf
	v_add_f32_dpp v190, v230, v230 row_ror:8 row_mask:0xf bank_mask:0xf
	v_add_f32_dpp v191, v231, v231 row_ror:8 row_mask:0xf bank_mask:0xf
	ds_bpermute_b32 v16, v6, v172
	ds_bpermute_b32 v17, v6, v173
	ds_bpermute_b32 v18, v6, v174
	ds_bpermute_b32 v19, v6, v175
	ds_bpermute_b32 v20, v6, v176
	ds_bpermute_b32 v21, v6, v177
	ds_bpermute_b32 v22, v6, v178
	ds_bpermute_b32 v23, v6, v179
	ds_bpermute_b32 v24, v6, v180
	ds_bpermute_b32 v25, v6, v181
	ds_bpermute_b32 v26, v6, v182
	ds_bpermute_b32 v27, v6, v183
	ds_bpermute_b32 v28, v6, v184
	ds_bpermute_b32 v29, v6, v185
	ds_bpermute_b32 v30, v6, v186
	ds_bpermute_b32 v31, v6, v187
	ds_bpermute_b32 v32, v6, v188
	ds_bpermute_b32 v33, v6, v189
	ds_bpermute_b32 v34, v6, v190
	ds_bpermute_b32 v35, v6, v191
	s_waitcnt lgkmcnt(0)
	v_add_f32_e32 v212, v172, v16
	v_add_f32_e32 v213, v173, v17
	v_add_f32_e32 v214, v174, v18
	v_add_f32_e32 v215, v175, v19
	v_add_f32_e32 v216, v176, v20
	v_add_f32_e32 v217, v177, v21
	v_add_f32_e32 v218, v178, v22
	v_add_f32_e32 v219, v179, v23
	v_add_f32_e32 v220, v180, v24
	v_add_f32_e32 v221, v181, v25
	v_add_f32_e32 v222, v182, v26
	v_add_f32_e32 v223, v183, v27
	v_add_f32_e32 v224, v184, v28
	v_add_f32_e32 v225, v185, v29
	v_add_f32_e32 v226, v186, v30
	v_add_f32_e32 v227, v187, v31
	v_add_f32_e32 v228, v188, v32
	v_add_f32_e32 v229, v189, v33
	v_add_f32_e32 v230, v190, v34
	v_add_f32_e32 v231, v191, v35
	ds_bpermute_b32 v16, v7, v212
	ds_bpermute_b32 v17, v7, v213
	ds_bpermute_b32 v18, v7, v214
	ds_bpermute_b32 v19, v7, v215
	ds_bpermute_b32 v20, v7, v216
	ds_bpermute_b32 v21, v7, v217
	ds_bpermute_b32 v22, v7, v218
	ds_bpermute_b32 v23, v7, v219
	ds_bpermute_b32 v24, v7, v220
	ds_bpermute_b32 v25, v7, v221
	ds_bpermute_b32 v26, v7, v222
	ds_bpermute_b32 v27, v7, v223
	ds_bpermute_b32 v28, v7, v224
	ds_bpermute_b32 v29, v7, v225
	ds_bpermute_b32 v30, v7, v226
	ds_bpermute_b32 v31, v7, v227
	ds_bpermute_b32 v32, v7, v228
	ds_bpermute_b32 v33, v7, v229
	ds_bpermute_b32 v34, v7, v230
	ds_bpermute_b32 v35, v7, v231
	s_waitcnt lgkmcnt(0)
	v_add_f32_e32 v172, v212, v16
	v_add_f32_e32 v173, v213, v17
	v_add_f32_e32 v174, v214, v18
	v_add_f32_e32 v175, v215, v19
	v_add_f32_e32 v176, v216, v20
	v_add_f32_e32 v177, v217, v21
	v_add_f32_e32 v178, v218, v22
	v_add_f32_e32 v179, v219, v23
	v_add_f32_e32 v180, v220, v24
	v_add_f32_e32 v181, v221, v25
	v_add_f32_e32 v182, v222, v26
	v_add_f32_e32 v183, v223, v27
	v_add_f32_e32 v184, v224, v28
	v_add_f32_e32 v185, v225, v29
	v_add_f32_e32 v186, v226, v30
	v_add_f32_e32 v187, v227, v31
	v_add_f32_e32 v188, v228, v32
	v_add_f32_e32 v189, v229, v33
	v_add_f32_e32 v190, v230, v34
	v_add_f32_e32 v191, v231, v35
	s_mov_b64 exec, 0xff
	s_add_u32 s6, s46, s2
	s_addc_u32 s7, s47, 0
	global_load_dwordx4 v[10:13], v8, s[6:7]
	s_add_u32 s6, s68, s2
	s_addc_u32 s7, s69, 0
	s_add_u32 s6, s6, 0x5188000
	s_addc_u32 s7, s7, 0
	s_waitcnt vmcnt(0)
	v_add_f32_e32 v172, v10, v172
	v_add_f32_e32 v173, v11, v173
	v_add_f32_e32 v174, v12, v174
	v_add_f32_e32 v175, v13, v175
	global_store_dwordx4 v8, v[172:175], s[6:7]
	s_add_u32 s6, s6, 0x9000
	s_addc_u32 s7, s7, 0
	v_add_f32_e32 v176, v10, v176
	v_add_f32_e32 v177, v11, v177
	v_add_f32_e32 v178, v12, v178
	v_add_f32_e32 v179, v13, v179
	global_store_dwordx4 v8, v[176:179], s[6:7]
	s_add_u32 s6, s6, 0x9000
	s_addc_u32 s7, s7, 0
	v_add_f32_e32 v180, v10, v180
	v_add_f32_e32 v181, v11, v181
	v_add_f32_e32 v182, v12, v182
	v_add_f32_e32 v183, v13, v183
	global_store_dwordx4 v8, v[180:183], s[6:7]
	s_add_u32 s6, s6, 0x9000
	s_addc_u32 s7, s7, 0
	v_add_f32_e32 v184, v10, v184
	v_add_f32_e32 v185, v11, v185
	v_add_f32_e32 v186, v12, v186
	v_add_f32_e32 v187, v13, v187
	global_store_dwordx4 v8, v[184:187], s[6:7]
	s_add_u32 s6, s6, 0x9000
	s_addc_u32 s7, s7, 0
	v_add_f32_e32 v188, v10, v188
	v_add_f32_e32 v189, v11, v189
	v_add_f32_e32 v190, v12, v190
	v_add_f32_e32 v191, v13, v191
	global_store_dwordx4 v8, v[188:191], s[6:7]
	s_mov_b64 exec, -1
	s_branch .Lada_pad
	s_nop 0
	s_nop 0
	s_nop 0
	s_nop 0
	s_nop 0
	s_nop 0
	s_nop 0
	s_nop 0
; __device__ __forceinline__ void transpose_store(const TItem& t, const float (&v)[8], float* scr) {
;     const int tid = threadIdx.x & 255;
; #pragma unroll
;     for (int i = 0; i < 8; ++i) scr[((tid >> 5) + 8 * i) * 33 + (tid & 31)] = v[i];
;     __syncthreads();
;     const int n = tid >> 3, kc = (tid & 7) * 8;
;     const float* s = scr + kc * 33 + n;
; __device__ __forceinline__ void phase0(const Params& P, unsigned char* smem) {
;     ...
;     {
;         const int stride = gridDim.x * 2;
;         int it = blockIdx.x * 2 + hb;
;         TItem cur, nxt; int Nc = 0, Nn = 0; float vn[8];
;         if (blockIdx.x * 2 < total) { lookup(it, nxt, Nn); transpose_load(nxt, Nn, vn); }
;         for (int base = blockIdx.x * 2; base < total; base += stride) {
;             float v[8];
; #pragma unroll
;             for (int i = 0; i < 8; ++i) v[i] = vn[i];
;             cur = nxt; Nc = Nn;
;             if (base + stride < total) { lookup(it + stride, nxt, Nn); transpose_load(nxt, Nn, vn); }
;             transpose_store(cur, v, scr);
;             it += stride;
;         }
;     }
.Lada_pad:
.LBB0_20:
	v_and_b32_e32 v1, 63, v168
	v_lshrrev_b32_e32 v14, 6, v168
	s_nop 1
	v_readfirstlane_b32 s0, v14
	s_nop 3
	v_lshrrev_b32_e32 v2, 3, v1
	v_and_b32_e32 v3, 7, v1
	v_lshrrev_b32_e32 v4, 2, v2
	v_and_b32_e32 v14, 3, v2
	v_lshl_or_b32 v4, v4, 3, v14
	s_mulk_i32 s0, 0x2100
	s_add_u32 s3, s0, 16
	v_mul_u32_u24_e32 v5, 0x84, v2
	v_lshl_add_u32 v5, v3, 4, v5
	v_add_u32_e32 v5, s3, v5
	v_add_u32_e32 v6, 0x420, v5
	v_add_u32_e32 v7, 0x420, v6
	v_add_u32_e32 v8, 0x420, v7
	v_add_u32_e32 v9, 0x420, v8
	v_add_u32_e32 v10, 0x420, v9
	v_add_u32_e32 v11, 0x420, v10
	v_add_u32_e32 v12, 0x420, v11
	v_mul_u32_u24_e32 v13, 0x420, v3
	v_lshl_add_u32 v13, v2, 2, v13
	v_add_u32_e32 v13, s3, v13
	v_lshlrev_b32_e32 v3, 4, v3
	v_lshrrev_b32_e32 v14, 6, v168
	s_nop 1
	v_readfirstlane_b32 s0, v14
	s_nop 3
	s_lshl_b32 s4, s33, 3
	s_add_u32 s0, s0, s4
	s_and_b32 s3, s0, 7
	s_cmp_lt_u32 s33, 32
	s_cbranch_scc0 .Ltr_ib
	s_mul_i32 s18, s33, 6
	s_add_u32 s18, s18, s3
	s_sub_u32 s18, s18, 2
	s_cmp_lt_u32 s3, 2
	s_cselect_b32 s17, 1, 0
	s_branch .Ltr_ic
.Ltr_ib:
	s_sub_u32 s18, s33, 32
	s_mul_i32 s18, s18, 7
	s_add_u32 s18, s18, s3
	s_add_u32 s18, s18, 0xbf
	s_cmp_eq_u32 s3, 0
	s_cselect_b32 s17, 1, 0
.Ltr_ic:
	s_mov_b32 s1, s0
	s_mov_b32 s2, 0
	s_cmpk_lt_u32 s1, 0x580
	s_cbranch_scc1 .Ltr1_m0
	s_cmpk_lt_u32 s1, 0xb00
	s_cbranch_scc1 .Ltr1_m1
	s_cmpk_lt_u32 s1, 0x1080
	s_cbranch_scc1 .Ltr1_m2
	s_cmpk_lt_u32 s1, 0x1600
	s_cbranch_scc1 .Ltr1_m3
	s_cmpk_lt_u32 s1, 0x1b80
	s_cbranch_scc1 .Ltr1_m4
	s_cmpk_lt_u32 s1, 0x2100
	s_cbranch_scc1 .Ltr1_m5
	s_cmpk_lt_u32 s1, 0x2910
	s_cbranch_scc1 .Ltr1_m6
	s_cmpk_lt_u32 s1, 0x2990
	s_cbranch_scc1 .Ltr1_m7
	s_cmpk_lt_u32 s1, 0x2a90
	s_cbranch_scc1 .Ltr1_m8
	s_cmpk_lt_u32 s1, 0x2b90
	s_cbranch_scc1 .Ltr1_m9
	s_sub_u32 s3, s1, 0x2b90
	v_readlane_b32 s6, v251, 43
	v_readlane_b32 s7, v251, 44
	s_mov_b32 s13, 0x2c00000
	s_mov_b32 s14, 0
	s_branch .Ltr1_c1024_1024

; __device__ __forceinline__ void transpose_load(const TItem& t, int N, float (&v)[8]) {
; #pragma unroll
;     for (int i = 0; i < 8; ++i) v[i] = t.src[(size_t)(8 * i) * N];
; }
; __device__ __forceinline__ void phase0(const Params& P, unsigned char* smem) {
;     ...
;         for (int base = blockIdx.x * 2; base < total; base += stride) {
;             float v[8];
; #pragma unroll
;             for (int i = 0; i < 8; ++i) v[i] = vn[i];
;             cur = nxt; Nc = Nn;
;             if (base + stride < total) { lookup(it + stride, nxt, Nn); transpose_load(nxt, Nn, vn); }
;             transpose_store(cur, v, scr);
;             it += stride;
;         }
.Ltr_ld1:
	global_load_dwordx4 v[16:19], v96, s[6:7]
	global_load_dwordx4 v[20:23], v97, s[6:7]
	global_load_dwordx4 v[24:27], v98, s[6:7]
	global_load_dwordx4 v[28:31], v99, s[6:7]
	global_load_dwordx4 v[32:35], v100, s[6:7]
	global_load_dwordx4 v[36:39], v101, s[6:7]
	global_load_dwordx4 v[40:43], v102, s[6:7]
	global_load_dwordx4 v[44:47], v103, s[6:7]
.Ltr_le1:
	s_add_u32 s2, s2, 1
	s_cmp_lt_u32 s2, 4
	s_cbranch_scc1 .Ltr2_common
	s_cmp_lg_u32 s17, 0
	s_cbranch_scc1 .Ltr_last0f
	s_cmp_eq_u32 s2, 4
	s_cbranch_scc0 .Ltr2_stride
	s_add_u32 s1, s18, 0x2000
	s_branch .Ltr2_chk
.Ltr2_stride:
	s_add_u32 s1, s1, 0x6e0
	s_branch .Ltr2_chk

; __device__ __forceinline__ unsigned pk2(float a, float b) { const f32x2_t v = {a, b}; const bf16x2_t r = __builtin_convertvector(v, bf16x2_t); return __builtin_bit_cast(unsigned, r); }
; __device__ __forceinline__ void transpose_store(const TItem& t, const float (&v)[8], float* scr) {
;     const int tid = threadIdx.x & 255;
; #pragma unroll
;     for (int i = 0; i < 8; ++i) scr[((tid >> 5) + 8 * i) * 33 + (tid & 31)] = v[i];
;     __syncthreads();
;     const int n = tid >> 3, kc = (tid & 7) * 8;
;     const float* s = scr + kc * 33 + n;
;     uint4 o; o.x = pk2(s[0], s[33]); o.y = pk2(s[66], s[99]); o.z = pk2(s[132], s[165]); o.w = pk2(s[198], s[231]);
;     const int nd = map_row(t.mode, t.n0 + n);
;     *(uint4*)(t.dst + (size_t)nd * t.K) = o;
;     __syncthreads();
; }
; __device__ __forceinline__ void phase0(const Params& P, unsigned char* smem) {
;     ...
;         for (int base = blockIdx.x * 2; base < total; base += stride) {
;             float v[8];
; #pragma unroll
;             for (int i = 0; i < 8; ++i) v[i] = vn[i];
;             cur = nxt; Nc = Nn;
;             if (base + stride < total) { lookup(it + stride, nxt, Nn); transpose_load(nxt, Nn, vn); }
;             transpose_store(cur, v, scr);
;             it += stride;
;         }
.Ltr_ld2:
	global_load_dwordx4 v[48:51], v96, s[6:7]
	global_load_dwordx4 v[52:55], v97, s[6:7]
	global_load_dwordx4 v[56:59], v98, s[6:7]
	global_load_dwordx4 v[60:63], v99, s[6:7]
	global_load_dwordx4 v[64:67], v100, s[6:7]
	global_load_dwordx4 v[68:71], v101, s[6:7]
	global_load_dwordx4 v[72:75], v102, s[6:7]
	global_load_dwordx4 v[76:79], v103, s[6:7]
.Ltr_le2:
.Ltr_wa0:
	s_waitcnt vmcnt(8)
	ds_write2_b32 v5, v16, v17 offset1:1
	ds_write2_b32 v5, v18, v19 offset0:2 offset1:3
	ds_write2_b32 v6, v20, v21 offset1:1
	ds_write2_b32 v6, v22, v23 offset0:2 offset1:3
	ds_write2_b32 v7, v24, v25 offset1:1
	ds_write2_b32 v7, v26, v27 offset0:2 offset1:3
	ds_write2_b32 v8, v28, v29 offset1:1
	ds_write2_b32 v8, v30, v31 offset0:2 offset1:3
	ds_write2_b32 v9, v32, v33 offset1:1
	ds_write2_b32 v9, v34, v35 offset0:2 offset1:3
	ds_write2_b32 v10, v36, v37 offset1:1
	ds_write2_b32 v10, v38, v39 offset0:2 offset1:3
	ds_write2_b32 v11, v40, v41 offset1:1
	ds_write2_b32 v11, v42, v43 offset0:2 offset1:3
	ds_write2_b32 v12, v44, v45 offset1:1
	ds_write2_b32 v12, v46, v47 offset0:2 offset1:3
	v_cndmask_b32_e64 v14, v2, v4, s[76:77]
	v_mad_u32_u24 v104, v14, s74, v3
	s_add_u32 s20, s72, s75
	s_addc_u32 s21, s73, 0
	s_add_u32 s22, s20, s75
	s_addc_u32 s23, s21, 0
	s_add_u32 s24, s22, s75
	s_addc_u32 s25, s23, 0
	s_waitcnt lgkmcnt(0)
	ds_read2_b32 v[16:17], v13 offset0:0 offset1:33
	ds_read2_b32 v[18:19], v13 offset0:66 offset1:99
	ds_read2_b32 v[20:21], v13 offset0:132 offset1:165
	ds_read2_b32 v[22:23], v13 offset0:198 offset1:231
	ds_read2_b32 v[24:25], v13 offset0:8 offset1:41
	ds_read2_b32 v[26:27], v13 offset0:74 offset1:107
	ds_read2_b32 v[28:29], v13 offset0:140 offset1:173
	ds_read2_b32 v[30:31], v13 offset0:206 offset1:239
	ds_read2_b32 v[32:33], v13 offset0:16 offset1:49
	ds_read2_b32 v[34:35], v13 offset0:82 offset1:115
	ds_read2_b32 v[36:37], v13 offset0:148 offset1:181
	ds_read2_b32 v[38:39], v13 offset0:214 offset1:247
	ds_read2_b32 v[40:41], v13 offset0:24 offset1:57
	ds_read2_b32 v[42:43], v13 offset0:90 offset1:123
	ds_read2_b32 v[44:45], v13 offset0:156 offset1:189
	ds_read2_b32 v[46:47], v13 offset0:222 offset1:255
	s_waitcnt lgkmcnt(12)
	v_cvt_pk_bf16_f32 v80, v16, v17
	v_cvt_pk_bf16_f32 v81, v18, v19
	v_cvt_pk_bf16_f32 v82, v20, v21
	v_cvt_pk_bf16_f32 v83, v22, v23
.Ltr_ps1:
	global_store_dwordx4 v104, v[80:83], s[72:73]
	s_waitcnt lgkmcnt(8)
	v_cvt_pk_bf16_f32 v84, v24, v25
	v_cvt_pk_bf16_f32 v85, v26, v27
	v_cvt_pk_bf16_f32 v86, v28, v29
	v_cvt_pk_bf16_f32 v87, v30, v31
	global_store_dwordx4 v104, v[84:87], s[20:21]
	s_waitcnt lgkmcnt(4)
	v_cvt_pk_bf16_f32 v88, v32, v33
	v_cvt_pk_bf16_f32 v89, v34, v35
	v_cvt_pk_bf16_f32 v90, v36, v37
	v_cvt_pk_bf16_f32 v91, v38, v39
	global_store_dwordx4 v104, v[88:91], s[22:23]
	s_waitcnt lgkmcnt(0)
	v_cvt_pk_bf16_f32 v92, v40, v41
	v_cvt_pk_bf16_f32 v93, v42, v43
	v_cvt_pk_bf16_f32 v94, v44, v45
	v_cvt_pk_bf16_f32 v95, v46, v47
	global_store_dwordx4 v104, v[92:95], s[24:25]
.Ltr_pe1:
.Ltr_loop:
	s_add_u32 s2, s2, 1
	s_cmp_lt_u32 s2, 4
	s_cbranch_scc1 .Ltr4_common
	s_cmp_lg_u32 s17, 0
	s_cbranch_scc1 .Ltr_last1
	s_cmp_eq_u32 s2, 4
	s_cbranch_scc0 .Ltr4_stride
	s_add_u32 s1, s18, 0x2000
	s_branch .Ltr4_chk

; __device__ __forceinline__ unsigned pk2(float a, float b) { const f32x2_t v = {a, b}; const bf16x2_t r = __builtin_convertvector(v, bf16x2_t); return __builtin_bit_cast(unsigned, r); }
; __device__ __forceinline__ void transpose_store(const TItem& t, const float (&v)[8], float* scr) {
;     const int tid = threadIdx.x & 255;
; #pragma unroll
;     for (int i = 0; i < 8; ++i) scr[((tid >> 5) + 8 * i) * 33 + (tid & 31)] = v[i];
;     __syncthreads();
;     const int n = tid >> 3, kc = (tid & 7) * 8;
;     const float* s = scr + kc * 33 + n;
;     uint4 o; o.x = pk2(s[0], s[33]); o.y = pk2(s[66], s[99]); o.z = pk2(s[132], s[165]); o.w = pk2(s[198], s[231]);
;     const int nd = map_row(t.mode, t.n0 + n);
;     *(uint4*)(t.dst + (size_t)nd * t.K) = o;
;     __syncthreads();
; }
.Ltr_le3:
.Ltr_wa1:
	s_waitcnt vmcnt(12)
	ds_write2_b32 v5, v48, v49 offset1:1
	ds_write2_b32 v5, v50, v51 offset0:2 offset1:3
	ds_write2_b32 v6, v52, v53 offset1:1
	ds_write2_b32 v6, v54, v55 offset0:2 offset1:3
	ds_write2_b32 v7, v56, v57 offset1:1
	ds_write2_b32 v7, v58, v59 offset0:2 offset1:3
	ds_write2_b32 v8, v60, v61 offset1:1
	ds_write2_b32 v8, v62, v63 offset0:2 offset1:3
	ds_write2_b32 v9, v64, v65 offset1:1
	ds_write2_b32 v9, v66, v67 offset0:2 offset1:3
	ds_write2_b32 v10, v68, v69 offset1:1
	ds_write2_b32 v10, v70, v71 offset0:2 offset1:3
	ds_write2_b32 v11, v72, v73 offset1:1
	ds_write2_b32 v11, v74, v75 offset0:2 offset1:3
	ds_write2_b32 v12, v76, v77 offset1:1
	ds_write2_b32 v12, v78, v79 offset0:2 offset1:3
	v_cndmask_b32_e64 v14, v2, v4, s[82:83]
	v_mad_u32_u24 v104, v14, s80, v3
	s_add_u32 s20, s78, s81
	s_addc_u32 s21, s79, 0
	s_add_u32 s22, s20, s81
	s_addc_u32 s23, s21, 0
	s_add_u32 s24, s22, s81
	s_addc_u32 s25, s23, 0
	s_waitcnt lgkmcnt(0)
	ds_read2_b32 v[48:49], v13 offset0:0 offset1:33
	ds_read2_b32 v[50:51], v13 offset0:66 offset1:99
	ds_read2_b32 v[52:53], v13 offset0:132 offset1:165
	ds_read2_b32 v[54:55], v13 offset0:198 offset1:231
	ds_read2_b32 v[56:57], v13 offset0:8 offset1:41
	ds_read2_b32 v[58:59], v13 offset0:74 offset1:107
	ds_read2_b32 v[60:61], v13 offset0:140 offset1:173
	ds_read2_b32 v[62:63], v13 offset0:206 offset1:239
	ds_read2_b32 v[64:65], v13 offset0:16 offset1:49
	ds_read2_b32 v[66:67], v13 offset0:82 offset1:115
	ds_read2_b32 v[68:69], v13 offset0:148 offset1:181
	ds_read2_b32 v[70:71], v13 offset0:214 offset1:247
	ds_read2_b32 v[72:73], v13 offset0:24 offset1:57
	ds_read2_b32 v[74:75], v13 offset0:90 offset1:123
	ds_read2_b32 v[76:77], v13 offset0:156 offset1:189
	ds_read2_b32 v[78:79], v13 offset0:222 offset1:255
	s_waitcnt lgkmcnt(12)
	v_cvt_pk_bf16_f32 v80, v48, v49
	v_cvt_pk_bf16_f32 v81, v50, v51
	v_cvt_pk_bf16_f32 v82, v52, v53
	v_cvt_pk_bf16_f32 v83, v54, v55
.Ltr_ps2:
	global_store_dwordx4 v104, v[80:83], s[78:79]
	s_waitcnt lgkmcnt(8)
	v_cvt_pk_bf16_f32 v84, v56, v57
	v_cvt_pk_bf16_f32 v85, v58, v59
	v_cvt_pk_bf16_f32 v86, v60, v61
	v_cvt_pk_bf16_f32 v87, v62, v63
	global_store_dwordx4 v104, v[84:87], s[20:21]
	s_waitcnt lgkmcnt(4)
	v_cvt_pk_bf16_f32 v88, v64, v65
	v_cvt_pk_bf16_f32 v89, v66, v67
	v_cvt_pk_bf16_f32 v90, v68, v69
	v_cvt_pk_bf16_f32 v91, v70, v71
	global_store_dwordx4 v104, v[88:91], s[22:23]
	s_waitcnt lgkmcnt(0)
	v_cvt_pk_bf16_f32 v92, v72, v73
	v_cvt_pk_bf16_f32 v93, v74, v75
	v_cvt_pk_bf16_f32 v94, v76, v77
	v_cvt_pk_bf16_f32 v95, v78, v79
	global_store_dwordx4 v104, v[92:95], s[24:25]

; __device__ __forceinline__ unsigned pk2(float a, float b) { const f32x2_t v = {a, b}; const bf16x2_t r = __builtin_convertvector(v, bf16x2_t); return __builtin_bit_cast(unsigned, r); }
; __device__ __forceinline__ void transpose_store(const TItem& t, const float (&v)[8], float* scr) {
;     const int tid = threadIdx.x & 255;
; #pragma unroll
;     for (int i = 0; i < 8; ++i) scr[((tid >> 5) + 8 * i) * 33 + (tid & 31)] = v[i];
;     __syncthreads();
;     const int n = tid >> 3, kc = (tid & 7) * 8;
;     const float* s = scr + kc * 33 + n;
;     uint4 o; o.x = pk2(s[0], s[33]); o.y = pk2(s[66], s[99]); o.z = pk2(s[132], s[165]); o.w = pk2(s[198], s[231]);
;     const int nd = map_row(t.mode, t.n0 + n);
;     *(uint4*)(t.dst + (size_t)nd * t.K) = o;
;     __syncthreads();
; }
.Ltr_le4:
.Ltr_wa2:
	s_waitcnt vmcnt(12)
	ds_write2_b32 v5, v16, v17 offset1:1
	ds_write2_b32 v5, v18, v19 offset0:2 offset1:3
	ds_write2_b32 v6, v20, v21 offset1:1
	ds_write2_b32 v6, v22, v23 offset0:2 offset1:3
	ds_write2_b32 v7, v24, v25 offset1:1
	ds_write2_b32 v7, v26, v27 offset0:2 offset1:3
	ds_write2_b32 v8, v28, v29 offset1:1
	ds_write2_b32 v8, v30, v31 offset0:2 offset1:3
	ds_write2_b32 v9, v32, v33 offset1:1
	ds_write2_b32 v9, v34, v35 offset0:2 offset1:3
	ds_write2_b32 v10, v36, v37 offset1:1
	ds_write2_b32 v10, v38, v39 offset0:2 offset1:3
	ds_write2_b32 v11, v40, v41 offset1:1
	ds_write2_b32 v11, v42, v43 offset0:2 offset1:3
	ds_write2_b32 v12, v44, v45 offset1:1
	ds_write2_b32 v12, v46, v47 offset0:2 offset1:3
	v_cndmask_b32_e64 v14, v2, v4, s[76:77]
	v_mad_u32_u24 v104, v14, s74, v3
	s_add_u32 s20, s72, s75
	s_addc_u32 s21, s73, 0
	s_add_u32 s22, s20, s75
	s_addc_u32 s23, s21, 0
	s_add_u32 s24, s22, s75
	s_addc_u32 s25, s23, 0
	s_waitcnt lgkmcnt(0)
	ds_read2_b32 v[16:17], v13 offset0:0 offset1:33
	ds_read2_b32 v[18:19], v13 offset0:66 offset1:99
	ds_read2_b32 v[20:21], v13 offset0:132 offset1:165
	ds_read2_b32 v[22:23], v13 offset0:198 offset1:231
	ds_read2_b32 v[24:25], v13 offset0:8 offset1:41
	ds_read2_b32 v[26:27], v13 offset0:74 offset1:107
	ds_read2_b32 v[28:29], v13 offset0:140 offset1:173
	ds_read2_b32 v[30:31], v13 offset0:206 offset1:239
	ds_read2_b32 v[32:33], v13 offset0:16 offset1:49
	ds_read2_b32 v[34:35], v13 offset0:82 offset1:115
	ds_read2_b32 v[36:37], v13 offset0:148 offset1:181
	ds_read2_b32 v[38:39], v13 offset0:214 offset1:247
	ds_read2_b32 v[40:41], v13 offset0:24 offset1:57
	ds_read2_b32 v[42:43], v13 offset0:90 offset1:123
	ds_read2_b32 v[44:45], v13 offset0:156 offset1:189
	ds_read2_b32 v[46:47], v13 offset0:222 offset1:255
	s_waitcnt lgkmcnt(12)
	v_cvt_pk_bf16_f32 v80, v16, v17
	v_cvt_pk_bf16_f32 v81, v18, v19
	v_cvt_pk_bf16_f32 v82, v20, v21
	v_cvt_pk_bf16_f32 v83, v22, v23

; __device__ __forceinline__ unsigned pk2(float a, float b) { const f32x2_t v = {a, b}; const bf16x2_t r = __builtin_convertvector(v, bf16x2_t); return __builtin_bit_cast(unsigned, r); }
; __device__ __forceinline__ void transpose_store(const TItem& t, const float (&v)[8], float* scr) {
;     const int tid = threadIdx.x & 255;
; #pragma unroll
;     for (int i = 0; i < 8; ++i) scr[((tid >> 5) + 8 * i) * 33 + (tid & 31)] = v[i];
;     __syncthreads();
;     const int n = tid >> 3, kc = (tid & 7) * 8;
;     const float* s = scr + kc * 33 + n;
;     uint4 o; o.x = pk2(s[0], s[33]); o.y = pk2(s[66], s[99]); o.z = pk2(s[132], s[165]); o.w = pk2(s[198], s[231]);
;     const int nd = map_row(t.mode, t.n0 + n);
;     *(uint4*)(t.dst + (size_t)nd * t.K) = o;
;     __syncthreads();
; }
.Ltr_last1:
.Ltr_wa3:
	s_waitcnt vmcnt(4)
	ds_write2_b32 v5, v48, v49 offset1:1
	ds_write2_b32 v5, v50, v51 offset0:2 offset1:3
	ds_write2_b32 v6, v52, v53 offset1:1
	ds_write2_b32 v6, v54, v55 offset0:2 offset1:3
	ds_write2_b32 v7, v56, v57 offset1:1
	ds_write2_b32 v7, v58, v59 offset0:2 offset1:3
	ds_write2_b32 v8, v60, v61 offset1:1
	ds_write2_b32 v8, v62, v63 offset0:2 offset1:3
	ds_write2_b32 v9, v64, v65 offset1:1
	ds_write2_b32 v9, v66, v67 offset0:2 offset1:3
	ds_write2_b32 v10, v68, v69 offset1:1
	ds_write2_b32 v10, v70, v71 offset0:2 offset1:3
	ds_write2_b32 v11, v72, v73 offset1:1
	ds_write2_b32 v11, v74, v75 offset0:2 offset1:3
	ds_write2_b32 v12, v76, v77 offset1:1
	ds_write2_b32 v12, v78, v79 offset0:2 offset1:3
	v_cndmask_b32_e64 v14, v2, v4, s[82:83]
	v_mad_u32_u24 v104, v14, s80, v3
	s_add_u32 s20, s78, s81
	s_addc_u32 s21, s79, 0
	s_add_u32 s22, s20, s81
	s_addc_u32 s23, s21, 0
	s_add_u32 s24, s22, s81
	s_addc_u32 s25, s23, 0
	s_waitcnt lgkmcnt(0)
	ds_read2_b32 v[48:49], v13 offset0:0 offset1:33
	ds_read2_b32 v[50:51], v13 offset0:66 offset1:99
	ds_read2_b32 v[52:53], v13 offset0:132 offset1:165
	ds_read2_b32 v[54:55], v13 offset0:198 offset1:231
	ds_read2_b32 v[56:57], v13 offset0:8 offset1:41
	ds_read2_b32 v[58:59], v13 offset0:74 offset1:107
	ds_read2_b32 v[60:61], v13 offset0:140 offset1:173
	ds_read2_b32 v[62:63], v13 offset0:206 offset1:239
	ds_read2_b32 v[64:65], v13 offset0:16 offset1:49
	ds_read2_b32 v[66:67], v13 offset0:82 offset1:115
	ds_read2_b32 v[68:69], v13 offset0:148 offset1:181
	ds_read2_b32 v[70:71], v13 offset0:214 offset1:247
	ds_read2_b32 v[72:73], v13 offset0:24 offset1:57
	ds_read2_b32 v[74:75], v13 offset0:90 offset1:123
	ds_read2_b32 v[76:77], v13 offset0:156 offset1:189
	ds_read2_b32 v[78:79], v13 offset0:222 offset1:255
	s_waitcnt lgkmcnt(12)
	v_cvt_pk_bf16_f32 v80, v48, v49
	v_cvt_pk_bf16_f32 v81, v50, v51
	v_cvt_pk_bf16_f32 v82, v52, v53
	v_cvt_pk_bf16_f32 v83, v54, v55

; __device__ __forceinline__ unsigned pk2(float a, float b) { const f32x2_t v = {a, b}; const bf16x2_t r = __builtin_convertvector(v, bf16x2_t); return __builtin_bit_cast(unsigned, r); }
; __device__ __forceinline__ void transpose_store(const TItem& t, const float (&v)[8], float* scr) {
;     const int tid = threadIdx.x & 255;
; #pragma unroll
;     for (int i = 0; i < 8; ++i) scr[((tid >> 5) + 8 * i) * 33 + (tid & 31)] = v[i];
;     __syncthreads();
;     const int n = tid >> 3, kc = (tid & 7) * 8;
;     const float* s = scr + kc * 33 + n;
;     uint4 o; o.x = pk2(s[0], s[33]); o.y = pk2(s[66], s[99]); o.z = pk2(s[132], s[165]); o.w = pk2(s[198], s[231]);
;     const int nd = map_row(t.mode, t.n0 + n);
;     *(uint4*)(t.dst + (size_t)nd * t.K) = o;
;     __syncthreads();
; }
.Ltr_last0f:
.Ltr_last0:
.Ltr_wa4:
	s_waitcnt vmcnt(0)
	ds_write2_b32 v5, v16, v17 offset1:1
	ds_write2_b32 v5, v18, v19 offset0:2 offset1:3
	ds_write2_b32 v6, v20, v21 offset1:1
	ds_write2_b32 v6, v22, v23 offset0:2 offset1:3
	ds_write2_b32 v7, v24, v25 offset1:1
	ds_write2_b32 v7, v26, v27 offset0:2 offset1:3
	ds_write2_b32 v8, v28, v29 offset1:1
	ds_write2_b32 v8, v30, v31 offset0:2 offset1:3
	ds_write2_b32 v9, v32, v33 offset1:1
	ds_write2_b32 v9, v34, v35 offset0:2 offset1:3
	ds_write2_b32 v10, v36, v37 offset1:1
	ds_write2_b32 v10, v38, v39 offset0:2 offset1:3
	ds_write2_b32 v11, v40, v41 offset1:1
	ds_write2_b32 v11, v42, v43 offset0:2 offset1:3
	ds_write2_b32 v12, v44, v45 offset1:1
	ds_write2_b32 v12, v46, v47 offset0:2 offset1:3
	v_cndmask_b32_e64 v14, v2, v4, s[76:77]
	v_mad_u32_u24 v104, v14, s74, v3
	s_add_u32 s20, s72, s75
	s_addc_u32 s21, s73, 0
	s_add_u32 s22, s20, s75
	s_addc_u32 s23, s21, 0
	s_add_u32 s24, s22, s75
	s_addc_u32 s25, s23, 0
	s_waitcnt lgkmcnt(0)
	ds_read2_b32 v[16:17], v13 offset0:0 offset1:33
	ds_read2_b32 v[18:19], v13 offset0:66 offset1:99
	ds_read2_b32 v[20:21], v13 offset0:132 offset1:165
	ds_read2_b32 v[22:23], v13 offset0:198 offset1:231
	ds_read2_b32 v[24:25], v13 offset0:8 offset1:41
	ds_read2_b32 v[26:27], v13 offset0:74 offset1:107
	ds_read2_b32 v[28:29], v13 offset0:140 offset1:173
	ds_read2_b32 v[30:31], v13 offset0:206 offset1:239
	ds_read2_b32 v[32:33], v13 offset0:16 offset1:49
	ds_read2_b32 v[34:35], v13 offset0:82 offset1:115
	ds_read2_b32 v[36:37], v13 offset0:148 offset1:181
	ds_read2_b32 v[38:39], v13 offset0:214 offset1:247
	ds_read2_b32 v[40:41], v13 offset0:24 offset1:57
	ds_read2_b32 v[42:43], v13 offset0:90 offset1:123
	ds_read2_b32 v[44:45], v13 offset0:156 offset1:189
	ds_read2_b32 v[46:47], v13 offset0:222 offset1:255
	s_waitcnt lgkmcnt(12)
	v_cvt_pk_bf16_f32 v80, v16, v17
	v_cvt_pk_bf16_f32 v81, v18, v19
	v_cvt_pk_bf16_f32 v82, v20, v21
	v_cvt_pk_bf16_f32 v83, v22, v23

; __device__ __forceinline__ void phase0(const Params& P, unsigned char* smem) {
;     ...
;     const int gtid = blockIdx.x * NTHR + threadIdx.x, gsz = gridDim.x * NTHR;
;     for (int e = gtid; e < NT + 2 * NL; e += gsz) ((float*)(P.ws + OFF_SS))[e] = 0.f;
.Ltr_pe5:
.Ltr_done:
	v_readlane_b32 s0, v251, 1
	v_readlane_b32 s1, v251, 2
	s_nop 3
	s_load_dword s2, s[0:1], 0x10
	s_waitcnt lgkmcnt(0)
	s_lshr_b32 s0, s2, 16
	s_and_b32 s0, 0xffff, s0
	s_cmp_lg_u32 s0, 0
	s_cselect_b64 s[0:1], -1, 0
	s_cmp_lg_u64 s[0:1], 0
	s_addc_u32 s30, s90, 0
	s_branch .Ltr_pad
	s_nop 0
	s_nop 0
	s_nop 0
	s_nop 0
	s_nop 0
